# hand-written HGRN forget-gate (log f) epilogue of the mixer in-projection: branch-free, log argument selected before the log (2 logs per element instead of 3 divergent ones)
# speedup vs baseline: 1.0122x; 1.0122x over previous
; __device__ __forceinline__ unsigned cvt_pk_bf16(float lo, float hi) { const f32x2c v = {lo, hi}; const bf16x2c b = __builtin_convertvector(v, bf16x2c); return __builtin_bit_cast(unsigned, b); }
; #define PG8_GAS __attribute__((address_space(1)))
;     __device__ __forceinline__ void operator()(const f32x4 (&acc)[2][2][4][2], const Unit& u, int wr, int wc, int fr, int fq) const {
;         const int seg = u.pn >> 1; const int rbase = u.pm * BM + wr * 64 + fr; const int b = u.pm >> 5;
;         bf16_t* segp = proj + (size_t)seg * ((size_t)65536 * 512);
; #pragma unroll
;         for (int bj = 0; bj < 2; ++bj) {
;             const int wcol = (u.pn & 1) * 256 + bj * HALF + wc * 32 + 8 * fq;
;             if (seg < 3) {
;                 const int head = wcol >> 6, ch = wcol & 63;
;                 const bool rotw = (seg < 2) && ((wc & 1) == 0);
; #pragma unroll
;                 for (int ai = 0; ai < 2; ++ai)
; #pragma unroll
;                     for (int m = 0; m < 4; ++m) {
;                         const int r = rbase + ai * HALF + m * 16; const int s = r & 8191;
;                         f32x4 v0 = acc[ai][bj][m][0], v1 = acc[ai][bj][m][1];
;                         if (rotw) {
;                             f32x4 p0, p1;
; #pragma unroll
;                             for (int j = 0; j < 4; ++j) { p0[j] = __shfl_xor(v0[j], 16); p1[j] = __shfl_xor(v1[j], 16); }
;                             if (fq < 2) {
;                                 const f32x4 c0 = *(const PG8_GAS f32x4*)(rope + (size_t)r * 16), c1 = *(const PG8_GAS f32x4*)(rope + (size_t)r * 16 + 4);
;                                 const f32x4 s0 = *(const PG8_GAS f32x4*)(rope + (size_t)r * 16 + 8), s1 = *(const PG8_GAS f32x4*)(rope + (size_t)r * 16 + 12);
;                                 if (fq == 0) { v0 = v0 * c0 - p0 * s0; v1 = v1 * c1 - p1 * s1; }
;                                 else { v0 = v0 * c0 + p0 * s0; v1 = v1 * c1 + p1 * s1; }
;                             }
;                         }
;                         if (seg == 0) { v0 = v0 * 0.18033688011112042f; v1 = v1 * 0.18033688011112042f; }
;                         u32x4 w; w.x = cvt_pk_bf16(v0[0], v0[1]); w.y = cvt_pk_bf16(v0[2], v0[3]); w.z = cvt_pk_bf16(v1[0], v1[1]); w.w = cvt_pk_bf16(v1[2], v1[3]);
;                         *(PG8_GAS u32x4*)(segp + ((size_t)((b * 8 + head) * 8192 + s)) * 64 + ch) = w;
.LBB0_153:
	s_cmp_lt_u32 s0, 4
	s_cbranch_scc1 .Lrope_go
	s_lshr_b32 s30, s0, 1
	s_cmp_eq_u32 s30, 4
	s_cbranch_scc1 .Llogf_new
	s_branch .Lrope_old
.Lrope_go:
	s_cmp_lt_u32 s0, 2
	s_cselect_b32 s28, s78, 1.0
	s_mov_b32 s29, 0
	s_lshr_b32 s30, s0, 1
	s_lshl_b32 s31, s30, 26
	s_add_u32 s26, s92, s31
	s_addc_u32 s27, s93, 0
	v_readlane_b32 s30, v255, 12
	s_and_b32 s31, s0, 1
	s_lshl_b32 s31, s31, 2
	s_lshr_b32 s32, s30, 6
	s_add_i32 s31, s31, s32
	s_lshr_b32 s32, s54, 5
	s_lshl_b32 s32, s32, 3
	s_add_i32 s31, s31, s32
	s_lshl_b32 s31, s31, 20
	s_and_b32 s32, s54, 31
	s_lshl_b32 s32, s32, 15
	s_add_u32 s31, s31, s32
	s_add_u32 s26, s26, s31
	s_addc_u32 s27, s27, 0
	s_add_u32 s98, s26, 0x200000
	s_addc_u32 s99, s27, 0
	s_and_b32 s32, s30, 32
	s_lshl_b32 s32, s32, 1
	v_lshlrev_b32_e32 v169, 7, v160
	v_lshl_add_u32 v169, v161, 1, v169
	v_add_u32_e32 v169, s32, v169
	v_readlane_b32 s30, v255, 15
	s_nop 3
	s_cmp_lg_u32 s30, 0
	s_cbranch_scc0 .Lrope_plain
	s_lshl_b32 s30, s54, 14
	s_add_u32 s24, s48, s30
	s_addc_u32 s25, s49, 0
	v_lshlrev_b32_e32 v168, 6, v160
	v_lshlrev_b32_e32 v202, 2, v207
	v_cmp_eq_u32_e32 vcc, 0, v161
	v_bfrev_b32_e32 v244, 1
	s_nop 0
	v_cndmask_b32_e32 v252, 0, v244, vcc
	global_load_dwordx4 v[128:131], v168, s[24:25] offset:0
	global_load_dwordx4 v[132:135], v168, s[24:25] offset:16
	global_load_dwordx4 v[136:139], v168, s[24:25] offset:32
	global_load_dwordx4 v[140:143], v168, s[24:25] offset:48
	global_load_dwordx4 v[180:183], v168, s[24:25] offset:1024
	global_load_dwordx4 v[184:187], v168, s[24:25] offset:1040
	global_load_dwordx4 v[188:191], v168, s[24:25] offset:1056
	global_load_dwordx4 v[192:195], v168, s[24:25] offset:1072
	global_load_dwordx4 v[214:217], v168, s[24:25] offset:2048
	global_load_dwordx4 v[218:221], v168, s[24:25] offset:2064
	global_load_dwordx4 v[222:225], v168, s[24:25] offset:2080
	global_load_dwordx4 v[226:229], v168, s[24:25] offset:2096
	ds_bpermute_b32 v230, v202, v120
	ds_bpermute_b32 v231, v202, v121
	ds_bpermute_b32 v232, v202, v122
	ds_bpermute_b32 v233, v202, v123
	ds_bpermute_b32 v234, v202, v124
	ds_bpermute_b32 v235, v202, v125
	ds_bpermute_b32 v236, v202, v126
	ds_bpermute_b32 v237, v202, v127
	ds_bpermute_b32 v196, v202, v56
	ds_bpermute_b32 v197, v202, v57
	ds_bpermute_b32 v198, v202, v58
	ds_bpermute_b32 v199, v202, v59
	ds_bpermute_b32 v156, v202, v60
	ds_bpermute_b32 v157, v202, v61
	ds_bpermute_b32 v158, v202, v62
	ds_bpermute_b32 v159, v202, v63
	s_waitcnt vmcnt(8)
	s_waitcnt lgkmcnt(8)
	v_pk_mul_f32 v[230:231], v[136:137], v[230:231]
	v_pk_mul_f32 v[232:233], v[138:139], v[232:233]
	v_pk_mul_f32 v[244:245], v[120:121], v[128:129]
	v_pk_mul_f32 v[246:247], v[122:123], v[130:131]
	v_xor_b32_e32 v230, v252, v230
	v_xor_b32_e32 v231, v252, v231
	v_xor_b32_e32 v232, v252, v232
	v_xor_b32_e32 v233, v252, v233
	v_pk_add_f32 v[244:245], v[244:245], v[230:231]
	v_pk_add_f32 v[246:247], v[246:247], v[232:233]
	v_cndmask_b32_e64 v120, v120, v244, s[4:5]
	v_cndmask_b32_e64 v121, v121, v245, s[4:5]
	v_cndmask_b32_e64 v122, v122, v246, s[4:5]
	v_cndmask_b32_e64 v123, v123, v247, s[4:5]
	v_pk_mul_f32 v[234:235], v[140:141], v[234:235]
	v_pk_mul_f32 v[236:237], v[142:143], v[236:237]
	v_pk_mul_f32 v[244:245], v[124:125], v[132:133]
	v_pk_mul_f32 v[246:247], v[126:127], v[134:135]
	v_xor_b32_e32 v234, v252, v234
	v_xor_b32_e32 v235, v252, v235
	v_xor_b32_e32 v236, v252, v236
	v_xor_b32_e32 v237, v252, v237
	v_pk_add_f32 v[244:245], v[244:245], v[234:235]
	v_pk_add_f32 v[246:247], v[246:247], v[236:237]
	v_cndmask_b32_e64 v124, v124, v244, s[4:5]
	v_cndmask_b32_e64 v125, v125, v245, s[4:5]
	v_cndmask_b32_e64 v126, v126, v246, s[4:5]
	v_cndmask_b32_e64 v127, v127, v247, s[4:5]
	v_pk_mul_f32 v[120:121], v[120:121], s[28:29] op_sel_hi:[1,0]
	v_pk_mul_f32 v[122:123], v[122:123], s[28:29] op_sel_hi:[1,0]
	v_pk_mul_f32 v[124:125], v[124:125], s[28:29] op_sel_hi:[1,0]
	v_pk_mul_f32 v[126:127], v[126:127], s[28:29] op_sel_hi:[1,0]
	v_cvt_pk_bf16_f32 v248, v120, v121
	v_cvt_pk_bf16_f32 v249, v122, v123
	v_cvt_pk_bf16_f32 v250, v124, v125
	v_cvt_pk_bf16_f32 v251, v126, v127
	global_store_dwordx4 v169, v[248:251], s[26:27]
	s_nop 1
	ds_bpermute_b32 v230, v202, v112
	ds_bpermute_b32 v231, v202, v113
	ds_bpermute_b32 v232, v202, v114
	ds_bpermute_b32 v233, v202, v115
	ds_bpermute_b32 v234, v202, v116
	ds_bpermute_b32 v235, v202, v117
	ds_bpermute_b32 v236, v202, v118
	ds_bpermute_b32 v237, v202, v119
	s_waitcnt lgkmcnt(8)
	v_pk_mul_f32 v[196:197], v[136:137], v[196:197]
	v_pk_mul_f32 v[198:199], v[138:139], v[198:199]
	v_pk_mul_f32 v[244:245], v[56:57], v[128:129]
	v_pk_mul_f32 v[246:247], v[58:59], v[130:131]
	v_xor_b32_e32 v196, v252, v196
	v_xor_b32_e32 v197, v252, v197
	v_xor_b32_e32 v198, v252, v198
	v_xor_b32_e32 v199, v252, v199
	v_pk_add_f32 v[244:245], v[244:245], v[196:197]
	v_pk_add_f32 v[246:247], v[246:247], v[198:199]
	v_cndmask_b32_e64 v56, v56, v244, s[4:5]
	v_cndmask_b32_e64 v57, v57, v245, s[4:5]
	v_cndmask_b32_e64 v58, v58, v246, s[4:5]
	v_cndmask_b32_e64 v59, v59, v247, s[4:5]
	v_pk_mul_f32 v[156:157], v[140:141], v[156:157]
	v_pk_mul_f32 v[158:159], v[142:143], v[158:159]
	v_pk_mul_f32 v[244:245], v[60:61], v[132:133]
	v_pk_mul_f32 v[246:247], v[62:63], v[134:135]
	v_xor_b32_e32 v156, v252, v156
	v_xor_b32_e32 v157, v252, v157
	v_xor_b32_e32 v158, v252, v158
	v_xor_b32_e32 v159, v252, v159
	v_pk_add_f32 v[244:245], v[244:245], v[156:157]
	v_pk_add_f32 v[246:247], v[246:247], v[158:159]
	v_cndmask_b32_e64 v60, v60, v244, s[4:5]
	v_cndmask_b32_e64 v61, v61, v245, s[4:5]
	v_cndmask_b32_e64 v62, v62, v246, s[4:5]
	v_cndmask_b32_e64 v63, v63, v247, s[4:5]
	v_pk_mul_f32 v[56:57], v[56:57], s[28:29] op_sel_hi:[1,0]
	v_pk_mul_f32 v[58:59], v[58:59], s[28:29] op_sel_hi:[1,0]
	v_pk_mul_f32 v[60:61], v[60:61], s[28:29] op_sel_hi:[1,0]
	v_pk_mul_f32 v[62:63], v[62:63], s[28:29] op_sel_hi:[1,0]
	v_cvt_pk_bf16_f32 v248, v56, v57
	v_cvt_pk_bf16_f32 v249, v58, v59
	v_cvt_pk_bf16_f32 v250, v60, v61
	v_cvt_pk_bf16_f32 v251, v62, v63
	global_store_dwordx4 v169, v[248:251], s[98:99]
	s_nop 1
	s_add_u32 s26, s26, 0x800
	s_addc_u32 s27, s27, 0
	s_add_u32 s98, s98, 0x800
	s_addc_u32 s99, s99, 0
	global_load_dwordx4 v[128:131], v168, s[24:25] offset:3072
	global_load_dwordx4 v[132:135], v168, s[24:25] offset:3088
	global_load_dwordx4 v[136:139], v168, s[24:25] offset:3104
	global_load_dwordx4 v[140:143], v168, s[24:25] offset:3120
	s_add_u32 s24, s24, 0x2000
	s_addc_u32 s25, s25, 0
	ds_bpermute_b32 v196, v202, v48
	ds_bpermute_b32 v197, v202, v49
	ds_bpermute_b32 v198, v202, v50
	ds_bpermute_b32 v199, v202, v51
	ds_bpermute_b32 v156, v202, v52
	ds_bpermute_b32 v157, v202, v53
	ds_bpermute_b32 v158, v202, v54
	ds_bpermute_b32 v159, v202, v55
	s_waitcnt vmcnt(10)
; __device__ __forceinline__ unsigned cvt_pk_bf16(float lo, float hi) { const f32x2c v = {lo, hi}; const bf16x2c b = __builtin_convertvector(v, bf16x2c); return __builtin_bit_cast(unsigned, b); }
; #define PG8_GAS __attribute__((address_space(1)))
;     __device__ __forceinline__ void operator()(const f32x4 (&acc)[2][2][4][2], const Unit& u, int wr, int wc, int fr, int fq) const {
;     ...
;                         const int r = rbase + ai * HALF + m * 16; const int s = r & 8191;
;                         f32x4 v0 = acc[ai][bj][m][0], v1 = acc[ai][bj][m][1];
;                         if (rotw) {
;                             f32x4 p0, p1;
; #pragma unroll
;                             for (int j = 0; j < 4; ++j) { p0[j] = __shfl_xor(v0[j], 16); p1[j] = __shfl_xor(v1[j], 16); }
;                             if (fq < 2) {
;                                 const f32x4 c0 = *(const PG8_GAS f32x4*)(rope + (size_t)r * 16), c1 = *(const PG8_GAS f32x4*)(rope + (size_t)r * 16 + 4);
;                                 const f32x4 s0 = *(const PG8_GAS f32x4*)(rope + (size_t)r * 16 + 8), s1 = *(const PG8_GAS f32x4*)(rope + (size_t)r * 16 + 12);
;                                 if (fq == 0) { v0 = v0 * c0 - p0 * s0; v1 = v1 * c1 - p1 * s1; }
;                                 else { v0 = v0 * c0 + p0 * s0; v1 = v1 * c1 + p1 * s1; }
;                             }
;                         }
;                         if (seg == 0) { v0 = v0 * 0.18033688011112042f; v1 = v1 * 0.18033688011112042f; }
;                         u32x4 w; w.x = cvt_pk_bf16(v0[0], v0[1]); w.y = cvt_pk_bf16(v0[2], v0[3]); w.z = cvt_pk_bf16(v1[0], v1[1]); w.w = cvt_pk_bf16(v1[2], v1[3]);
;                         *(PG8_GAS u32x4*)(segp + ((size_t)((b * 8 + head) * 8192 + s)) * 64 + ch) = w;
	s_waitcnt lgkmcnt(8)
	v_pk_mul_f32 v[230:231], v[188:189], v[230:231]
	v_pk_mul_f32 v[232:233], v[190:191], v[232:233]
	v_pk_mul_f32 v[244:245], v[112:113], v[180:181]
	v_pk_mul_f32 v[246:247], v[114:115], v[182:183]
	v_xor_b32_e32 v230, v252, v230
	v_xor_b32_e32 v231, v252, v231
	v_xor_b32_e32 v232, v252, v232
	v_xor_b32_e32 v233, v252, v233
	v_pk_add_f32 v[244:245], v[244:245], v[230:231]
	v_pk_add_f32 v[246:247], v[246:247], v[232:233]
	v_cndmask_b32_e64 v112, v112, v244, s[4:5]
	v_cndmask_b32_e64 v113, v113, v245, s[4:5]
	v_cndmask_b32_e64 v114, v114, v246, s[4:5]
	v_cndmask_b32_e64 v115, v115, v247, s[4:5]
	v_pk_mul_f32 v[234:235], v[192:193], v[234:235]
	v_pk_mul_f32 v[236:237], v[194:195], v[236:237]
	v_pk_mul_f32 v[244:245], v[116:117], v[184:185]
	v_pk_mul_f32 v[246:247], v[118:119], v[186:187]
	v_xor_b32_e32 v234, v252, v234
	v_xor_b32_e32 v235, v252, v235
	v_xor_b32_e32 v236, v252, v236
	v_xor_b32_e32 v237, v252, v237
	v_pk_add_f32 v[244:245], v[244:245], v[234:235]
	v_pk_add_f32 v[246:247], v[246:247], v[236:237]
	v_cndmask_b32_e64 v116, v116, v244, s[4:5]
	v_cndmask_b32_e64 v117, v117, v245, s[4:5]
	v_cndmask_b32_e64 v118, v118, v246, s[4:5]
	v_cndmask_b32_e64 v119, v119, v247, s[4:5]
	v_pk_mul_f32 v[112:113], v[112:113], s[28:29] op_sel_hi:[1,0]
	v_pk_mul_f32 v[114:115], v[114:115], s[28:29] op_sel_hi:[1,0]
	v_pk_mul_f32 v[116:117], v[116:117], s[28:29] op_sel_hi:[1,0]
	v_pk_mul_f32 v[118:119], v[118:119], s[28:29] op_sel_hi:[1,0]
	v_cvt_pk_bf16_f32 v248, v112, v113
	v_cvt_pk_bf16_f32 v249, v114, v115
	v_cvt_pk_bf16_f32 v250, v116, v117
	v_cvt_pk_bf16_f32 v251, v118, v119
	global_store_dwordx4 v169, v[248:251], s[26:27]
	s_nop 1
	ds_bpermute_b32 v230, v202, v104
	ds_bpermute_b32 v231, v202, v105
	ds_bpermute_b32 v232, v202, v106
	ds_bpermute_b32 v233, v202, v107
	ds_bpermute_b32 v234, v202, v108
	ds_bpermute_b32 v235, v202, v109
	ds_bpermute_b32 v236, v202, v110
	ds_bpermute_b32 v237, v202, v111
	s_waitcnt lgkmcnt(8)
	v_pk_mul_f32 v[196:197], v[188:189], v[196:197]
	v_pk_mul_f32 v[198:199], v[190:191], v[198:199]
	v_pk_mul_f32 v[244:245], v[48:49], v[180:181]
	v_pk_mul_f32 v[246:247], v[50:51], v[182:183]
	v_xor_b32_e32 v196, v252, v196
	v_xor_b32_e32 v197, v252, v197
	v_xor_b32_e32 v198, v252, v198
	v_xor_b32_e32 v199, v252, v199
	v_pk_add_f32 v[244:245], v[244:245], v[196:197]
	v_pk_add_f32 v[246:247], v[246:247], v[198:199]
	v_cndmask_b32_e64 v48, v48, v244, s[4:5]
	v_cndmask_b32_e64 v49, v49, v245, s[4:5]
	v_cndmask_b32_e64 v50, v50, v246, s[4:5]
	v_cndmask_b32_e64 v51, v51, v247, s[4:5]
	v_pk_mul_f32 v[156:157], v[192:193], v[156:157]
	v_pk_mul_f32 v[158:159], v[194:195], v[158:159]
	v_pk_mul_f32 v[244:245], v[52:53], v[184:185]
	v_pk_mul_f32 v[246:247], v[54:55], v[186:187]
	v_xor_b32_e32 v156, v252, v156
	v_xor_b32_e32 v157, v252, v157
	v_xor_b32_e32 v158, v252, v158
	v_xor_b32_e32 v159, v252, v159
	v_pk_add_f32 v[244:245], v[244:245], v[156:157]
	v_pk_add_f32 v[246:247], v[246:247], v[158:159]
	v_cndmask_b32_e64 v52, v52, v244, s[4:5]
	v_cndmask_b32_e64 v53, v53, v245, s[4:5]
	v_cndmask_b32_e64 v54, v54, v246, s[4:5]
	v_cndmask_b32_e64 v55, v55, v247, s[4:5]
	v_pk_mul_f32 v[48:49], v[48:49], s[28:29] op_sel_hi:[1,0]
	v_pk_mul_f32 v[50:51], v[50:51], s[28:29] op_sel_hi:[1,0]
	v_pk_mul_f32 v[52:53], v[52:53], s[28:29] op_sel_hi:[1,0]
	v_pk_mul_f32 v[54:55], v[54:55], s[28:29] op_sel_hi:[1,0]
	v_cvt_pk_bf16_f32 v248, v48, v49
	v_cvt_pk_bf16_f32 v249, v50, v51
	v_cvt_pk_bf16_f32 v250, v52, v53
	v_cvt_pk_bf16_f32 v251, v54, v55
	global_store_dwordx4 v169, v[248:251], s[98:99]
	s_nop 1
	s_add_u32 s26, s26, 0x800
	s_addc_u32 s27, s27, 0
	s_add_u32 s98, s98, 0x800
	s_addc_u32 s99, s99, 0
	global_load_dwordx4 v[180:183], v168, s[24:25] offset:0
	global_load_dwordx4 v[184:187], v168, s[24:25] offset:16
	global_load_dwordx4 v[188:191], v168, s[24:25] offset:32
	global_load_dwordx4 v[192:195], v168, s[24:25] offset:48
	ds_bpermute_b32 v196, v202, v40
	ds_bpermute_b32 v197, v202, v41
	ds_bpermute_b32 v198, v202, v42
	ds_bpermute_b32 v199, v202, v43
	ds_bpermute_b32 v156, v202, v44
	ds_bpermute_b32 v157, v202, v45
	ds_bpermute_b32 v158, v202, v46
	ds_bpermute_b32 v159, v202, v47
	s_waitcnt vmcnt(12)
	s_waitcnt lgkmcnt(8)
	v_pk_mul_f32 v[230:231], v[222:223], v[230:231]
	v_pk_mul_f32 v[232:233], v[224:225], v[232:233]
	v_pk_mul_f32 v[244:245], v[104:105], v[214:215]
	v_pk_mul_f32 v[246:247], v[106:107], v[216:217]
	v_xor_b32_e32 v230, v252, v230
	v_xor_b32_e32 v231, v252, v231
	v_xor_b32_e32 v232, v252, v232
	v_xor_b32_e32 v233, v252, v233
	v_pk_add_f32 v[244:245], v[244:245], v[230:231]
	v_pk_add_f32 v[246:247], v[246:247], v[232:233]
	v_cndmask_b32_e64 v104, v104, v244, s[4:5]
	v_cndmask_b32_e64 v105, v105, v245, s[4:5]
	v_cndmask_b32_e64 v106, v106, v246, s[4:5]
	v_cndmask_b32_e64 v107, v107, v247, s[4:5]
	v_pk_mul_f32 v[234:235], v[226:227], v[234:235]
	v_pk_mul_f32 v[236:237], v[228:229], v[236:237]
	v_pk_mul_f32 v[244:245], v[108:109], v[218:219]
	v_pk_mul_f32 v[246:247], v[110:111], v[220:221]
	v_xor_b32_e32 v234, v252, v234
	v_xor_b32_e32 v235, v252, v235
	v_xor_b32_e32 v236, v252, v236
	v_xor_b32_e32 v237, v252, v237
	v_pk_add_f32 v[244:245], v[244:245], v[234:235]
	v_pk_add_f32 v[246:247], v[246:247], v[236:237]
	v_cndmask_b32_e64 v108, v108, v244, s[4:5]
	v_cndmask_b32_e64 v109, v109, v245, s[4:5]
	v_cndmask_b32_e64 v110, v110, v246, s[4:5]
	v_cndmask_b32_e64 v111, v111, v247, s[4:5]
	v_pk_mul_f32 v[104:105], v[104:105], s[28:29] op_sel_hi:[1,0]
	v_pk_mul_f32 v[106:107], v[106:107], s[28:29] op_sel_hi:[1,0]
	v_pk_mul_f32 v[108:109], v[108:109], s[28:29] op_sel_hi:[1,0]
	v_pk_mul_f32 v[110:111], v[110:111], s[28:29] op_sel_hi:[1,0]
	v_cvt_pk_bf16_f32 v248, v104, v105
	v_cvt_pk_bf16_f32 v249, v106, v107
	v_cvt_pk_bf16_f32 v250, v108, v109
	v_cvt_pk_bf16_f32 v251, v110, v111
	global_store_dwordx4 v169, v[248:251], s[26:27]
	s_nop 1
	ds_bpermute_b32 v230, v202, v96
	ds_bpermute_b32 v231, v202, v97
	ds_bpermute_b32 v232, v202, v98
	ds_bpermute_b32 v233, v202, v99
	ds_bpermute_b32 v234, v202, v100
	ds_bpermute_b32 v235, v202, v101
	ds_bpermute_b32 v236, v202, v102
	ds_bpermute_b32 v237, v202, v103
	s_waitcnt lgkmcnt(8)
; __device__ __forceinline__ unsigned cvt_pk_bf16(float lo, float hi) { const f32x2c v = {lo, hi}; const bf16x2c b = __builtin_convertvector(v, bf16x2c); return __builtin_bit_cast(unsigned, b); }
; #define PG8_GAS __attribute__((address_space(1)))
;     __device__ __forceinline__ void operator()(const f32x4 (&acc)[2][2][4][2], const Unit& u, int wr, int wc, int fr, int fq) const {
;     ...
;                         const int r = rbase + ai * HALF + m * 16; const int s = r & 8191;
;                         f32x4 v0 = acc[ai][bj][m][0], v1 = acc[ai][bj][m][1];
;                         if (rotw) {
;                             f32x4 p0, p1;
; #pragma unroll
;                             for (int j = 0; j < 4; ++j) { p0[j] = __shfl_xor(v0[j], 16); p1[j] = __shfl_xor(v1[j], 16); }
;                             if (fq < 2) {
;                                 const f32x4 c0 = *(const PG8_GAS f32x4*)(rope + (size_t)r * 16), c1 = *(const PG8_GAS f32x4*)(rope + (size_t)r * 16 + 4);
;                                 const f32x4 s0 = *(const PG8_GAS f32x4*)(rope + (size_t)r * 16 + 8), s1 = *(const PG8_GAS f32x4*)(rope + (size_t)r * 16 + 12);
;                                 if (fq == 0) { v0 = v0 * c0 - p0 * s0; v1 = v1 * c1 - p1 * s1; }
;                                 else { v0 = v0 * c0 + p0 * s0; v1 = v1 * c1 + p1 * s1; }
;                             }
;                         }
;                         if (seg == 0) { v0 = v0 * 0.18033688011112042f; v1 = v1 * 0.18033688011112042f; }
;                         u32x4 w; w.x = cvt_pk_bf16(v0[0], v0[1]); w.y = cvt_pk_bf16(v0[2], v0[3]); w.z = cvt_pk_bf16(v1[0], v1[1]); w.w = cvt_pk_bf16(v1[2], v1[3]);
;                         *(PG8_GAS u32x4*)(segp + ((size_t)((b * 8 + head) * 8192 + s)) * 64 + ch) = w;
	v_pk_mul_f32 v[196:197], v[222:223], v[196:197]
	v_pk_mul_f32 v[198:199], v[224:225], v[198:199]
	v_pk_mul_f32 v[244:245], v[40:41], v[214:215]
	v_pk_mul_f32 v[246:247], v[42:43], v[216:217]
	v_xor_b32_e32 v196, v252, v196
	v_xor_b32_e32 v197, v252, v197
	v_xor_b32_e32 v198, v252, v198
	v_xor_b32_e32 v199, v252, v199
	v_pk_add_f32 v[244:245], v[244:245], v[196:197]
	v_pk_add_f32 v[246:247], v[246:247], v[198:199]
	v_cndmask_b32_e64 v40, v40, v244, s[4:5]
	v_cndmask_b32_e64 v41, v41, v245, s[4:5]
	v_cndmask_b32_e64 v42, v42, v246, s[4:5]
	v_cndmask_b32_e64 v43, v43, v247, s[4:5]
	v_pk_mul_f32 v[156:157], v[226:227], v[156:157]
	v_pk_mul_f32 v[158:159], v[228:229], v[158:159]
	v_pk_mul_f32 v[244:245], v[44:45], v[218:219]
	v_pk_mul_f32 v[246:247], v[46:47], v[220:221]
	v_xor_b32_e32 v156, v252, v156
	v_xor_b32_e32 v157, v252, v157
	v_xor_b32_e32 v158, v252, v158
	v_xor_b32_e32 v159, v252, v159
	v_pk_add_f32 v[244:245], v[244:245], v[156:157]
	v_pk_add_f32 v[246:247], v[246:247], v[158:159]
	v_cndmask_b32_e64 v44, v44, v244, s[4:5]
	v_cndmask_b32_e64 v45, v45, v245, s[4:5]
	v_cndmask_b32_e64 v46, v46, v246, s[4:5]
	v_cndmask_b32_e64 v47, v47, v247, s[4:5]
	v_pk_mul_f32 v[40:41], v[40:41], s[28:29] op_sel_hi:[1,0]
	v_pk_mul_f32 v[42:43], v[42:43], s[28:29] op_sel_hi:[1,0]
	v_pk_mul_f32 v[44:45], v[44:45], s[28:29] op_sel_hi:[1,0]
	v_pk_mul_f32 v[46:47], v[46:47], s[28:29] op_sel_hi:[1,0]
	v_cvt_pk_bf16_f32 v248, v40, v41
	v_cvt_pk_bf16_f32 v249, v42, v43
	v_cvt_pk_bf16_f32 v250, v44, v45
	v_cvt_pk_bf16_f32 v251, v46, v47
	global_store_dwordx4 v169, v[248:251], s[98:99]
	s_nop 1
	s_add_u32 s26, s26, 0x800
	s_addc_u32 s27, s27, 0
	s_add_u32 s98, s98, 0x800
	s_addc_u32 s99, s99, 0
	global_load_dwordx4 v[214:217], v168, s[24:25] offset:1024
	global_load_dwordx4 v[218:221], v168, s[24:25] offset:1040
	global_load_dwordx4 v[222:225], v168, s[24:25] offset:1056
	global_load_dwordx4 v[226:229], v168, s[24:25] offset:1072
	ds_bpermute_b32 v196, v202, v32
	ds_bpermute_b32 v197, v202, v33
	ds_bpermute_b32 v198, v202, v34
	ds_bpermute_b32 v199, v202, v35
	ds_bpermute_b32 v156, v202, v36
	ds_bpermute_b32 v157, v202, v37
	ds_bpermute_b32 v158, v202, v38
	ds_bpermute_b32 v159, v202, v39
	s_waitcnt vmcnt(12)
	s_waitcnt lgkmcnt(8)
	v_pk_mul_f32 v[230:231], v[136:137], v[230:231]
	v_pk_mul_f32 v[232:233], v[138:139], v[232:233]
	v_pk_mul_f32 v[244:245], v[96:97], v[128:129]
	v_pk_mul_f32 v[246:247], v[98:99], v[130:131]
	v_xor_b32_e32 v230, v252, v230
	v_xor_b32_e32 v231, v252, v231
	v_xor_b32_e32 v232, v252, v232
	v_xor_b32_e32 v233, v252, v233
	v_pk_add_f32 v[244:245], v[244:245], v[230:231]
	v_pk_add_f32 v[246:247], v[246:247], v[232:233]
	v_cndmask_b32_e64 v96, v96, v244, s[4:5]
	v_cndmask_b32_e64 v97, v97, v245, s[4:5]
	v_cndmask_b32_e64 v98, v98, v246, s[4:5]
	v_cndmask_b32_e64 v99, v99, v247, s[4:5]
	v_pk_mul_f32 v[234:235], v[140:141], v[234:235]
	v_pk_mul_f32 v[236:237], v[142:143], v[236:237]
	v_pk_mul_f32 v[244:245], v[100:101], v[132:133]
	v_pk_mul_f32 v[246:247], v[102:103], v[134:135]
	v_xor_b32_e32 v234, v252, v234
	v_xor_b32_e32 v235, v252, v235
	v_xor_b32_e32 v236, v252, v236
	v_xor_b32_e32 v237, v252, v237
	v_pk_add_f32 v[244:245], v[244:245], v[234:235]
	v_pk_add_f32 v[246:247], v[246:247], v[236:237]
	v_cndmask_b32_e64 v100, v100, v244, s[4:5]
	v_cndmask_b32_e64 v101, v101, v245, s[4:5]
	v_cndmask_b32_e64 v102, v102, v246, s[4:5]
	v_cndmask_b32_e64 v103, v103, v247, s[4:5]
	v_pk_mul_f32 v[96:97], v[96:97], s[28:29] op_sel_hi:[1,0]
	v_pk_mul_f32 v[98:99], v[98:99], s[28:29] op_sel_hi:[1,0]
	v_pk_mul_f32 v[100:101], v[100:101], s[28:29] op_sel_hi:[1,0]
	v_pk_mul_f32 v[102:103], v[102:103], s[28:29] op_sel_hi:[1,0]
	v_cvt_pk_bf16_f32 v248, v96, v97
	v_cvt_pk_bf16_f32 v249, v98, v99
	v_cvt_pk_bf16_f32 v250, v100, v101
	v_cvt_pk_bf16_f32 v251, v102, v103
	global_store_dwordx4 v169, v[248:251], s[26:27]
	s_nop 1
	ds_bpermute_b32 v230, v202, v88
	ds_bpermute_b32 v231, v202, v89
	ds_bpermute_b32 v232, v202, v90
	ds_bpermute_b32 v233, v202, v91
	ds_bpermute_b32 v234, v202, v92
	ds_bpermute_b32 v235, v202, v93
	ds_bpermute_b32 v236, v202, v94
	ds_bpermute_b32 v237, v202, v95
	s_waitcnt lgkmcnt(8)
	v_pk_mul_f32 v[196:197], v[136:137], v[196:197]
	v_pk_mul_f32 v[198:199], v[138:139], v[198:199]
	v_pk_mul_f32 v[244:245], v[32:33], v[128:129]
	v_pk_mul_f32 v[246:247], v[34:35], v[130:131]
	v_xor_b32_e32 v196, v252, v196
	v_xor_b32_e32 v197, v252, v197
	v_xor_b32_e32 v198, v252, v198
	v_xor_b32_e32 v199, v252, v199
	v_pk_add_f32 v[244:245], v[244:245], v[196:197]
	v_pk_add_f32 v[246:247], v[246:247], v[198:199]
	v_cndmask_b32_e64 v32, v32, v244, s[4:5]
	v_cndmask_b32_e64 v33, v33, v245, s[4:5]
	v_cndmask_b32_e64 v34, v34, v246, s[4:5]
	v_cndmask_b32_e64 v35, v35, v247, s[4:5]
	v_pk_mul_f32 v[156:157], v[140:141], v[156:157]
	v_pk_mul_f32 v[158:159], v[142:143], v[158:159]
	v_pk_mul_f32 v[244:245], v[36:37], v[132:133]
	v_pk_mul_f32 v[246:247], v[38:39], v[134:135]
	v_xor_b32_e32 v156, v252, v156
	v_xor_b32_e32 v157, v252, v157
	v_xor_b32_e32 v158, v252, v158
	v_xor_b32_e32 v159, v252, v159
	v_pk_add_f32 v[244:245], v[244:245], v[156:157]
	v_pk_add_f32 v[246:247], v[246:247], v[158:159]
	v_cndmask_b32_e64 v36, v36, v244, s[4:5]
	v_cndmask_b32_e64 v37, v37, v245, s[4:5]
	v_cndmask_b32_e64 v38, v38, v246, s[4:5]
	v_cndmask_b32_e64 v39, v39, v247, s[4:5]
	v_pk_mul_f32 v[32:33], v[32:33], s[28:29] op_sel_hi:[1,0]
	v_pk_mul_f32 v[34:35], v[34:35], s[28:29] op_sel_hi:[1,0]
	v_pk_mul_f32 v[36:37], v[36:37], s[28:29] op_sel_hi:[1,0]
	v_pk_mul_f32 v[38:39], v[38:39], s[28:29] op_sel_hi:[1,0]
	v_cvt_pk_bf16_f32 v248, v32, v33
	v_cvt_pk_bf16_f32 v249, v34, v35
	v_cvt_pk_bf16_f32 v250, v36, v37
	v_cvt_pk_bf16_f32 v251, v38, v39
	global_store_dwordx4 v169, v[248:251], s[98:99]
	s_nop 1
	s_add_u32 s26, s26, 0x2800
	s_addc_u32 s27, s27, 0
	s_add_u32 s98, s98, 0x2800
	s_addc_u32 s99, s99, 0
	global_load_dwordx4 v[128:131], v168, s[24:25] offset:2048
	global_load_dwordx4 v[132:135], v168, s[24:25] offset:2064
	global_load_dwordx4 v[136:139], v168, s[24:25] offset:2080
	global_load_dwordx4 v[140:143], v168, s[24:25] offset:2096
	ds_bpermute_b32 v196, v202, v24
	ds_bpermute_b32 v197, v202, v25
	ds_bpermute_b32 v198, v202, v26
	ds_bpermute_b32 v199, v202, v27
	ds_bpermute_b32 v156, v202, v28
	ds_bpermute_b32 v157, v202, v29
	ds_bpermute_b32 v158, v202, v30
	ds_bpermute_b32 v159, v202, v31
	s_waitcnt vmcnt(12)
; __device__ __forceinline__ unsigned cvt_pk_bf16(float lo, float hi) { const f32x2c v = {lo, hi}; const bf16x2c b = __builtin_convertvector(v, bf16x2c); return __builtin_bit_cast(unsigned, b); }
; #define PG8_GAS __attribute__((address_space(1)))
;     __device__ __forceinline__ void operator()(const f32x4 (&acc)[2][2][4][2], const Unit& u, int wr, int wc, int fr, int fq) const {
;     ...
;                         const int r = rbase + ai * HALF + m * 16; const int s = r & 8191;
;                         f32x4 v0 = acc[ai][bj][m][0], v1 = acc[ai][bj][m][1];
;                         if (rotw) {
;                             f32x4 p0, p1;
; #pragma unroll
;                             for (int j = 0; j < 4; ++j) { p0[j] = __shfl_xor(v0[j], 16); p1[j] = __shfl_xor(v1[j], 16); }
;                             if (fq < 2) {
;                                 const f32x4 c0 = *(const PG8_GAS f32x4*)(rope + (size_t)r * 16), c1 = *(const PG8_GAS f32x4*)(rope + (size_t)r * 16 + 4);
;                                 const f32x4 s0 = *(const PG8_GAS f32x4*)(rope + (size_t)r * 16 + 8), s1 = *(const PG8_GAS f32x4*)(rope + (size_t)r * 16 + 12);
;                                 if (fq == 0) { v0 = v0 * c0 - p0 * s0; v1 = v1 * c1 - p1 * s1; }
;                                 else { v0 = v0 * c0 + p0 * s0; v1 = v1 * c1 + p1 * s1; }
;                             }
;                         }
;                         if (seg == 0) { v0 = v0 * 0.18033688011112042f; v1 = v1 * 0.18033688011112042f; }
;                         u32x4 w; w.x = cvt_pk_bf16(v0[0], v0[1]); w.y = cvt_pk_bf16(v0[2], v0[3]); w.z = cvt_pk_bf16(v1[0], v1[1]); w.w = cvt_pk_bf16(v1[2], v1[3]);
;                         *(PG8_GAS u32x4*)(segp + ((size_t)((b * 8 + head) * 8192 + s)) * 64 + ch) = w;
	s_waitcnt lgkmcnt(8)
	v_pk_mul_f32 v[230:231], v[188:189], v[230:231]
	v_pk_mul_f32 v[232:233], v[190:191], v[232:233]
	v_pk_mul_f32 v[244:245], v[88:89], v[180:181]
	v_pk_mul_f32 v[246:247], v[90:91], v[182:183]
	v_xor_b32_e32 v230, v252, v230
	v_xor_b32_e32 v231, v252, v231
	v_xor_b32_e32 v232, v252, v232
	v_xor_b32_e32 v233, v252, v233
	v_pk_add_f32 v[244:245], v[244:245], v[230:231]
	v_pk_add_f32 v[246:247], v[246:247], v[232:233]
	v_cndmask_b32_e64 v88, v88, v244, s[4:5]
	v_cndmask_b32_e64 v89, v89, v245, s[4:5]
	v_cndmask_b32_e64 v90, v90, v246, s[4:5]
	v_cndmask_b32_e64 v91, v91, v247, s[4:5]
	v_pk_mul_f32 v[234:235], v[192:193], v[234:235]
	v_pk_mul_f32 v[236:237], v[194:195], v[236:237]
	v_pk_mul_f32 v[244:245], v[92:93], v[184:185]
	v_pk_mul_f32 v[246:247], v[94:95], v[186:187]
	v_xor_b32_e32 v234, v252, v234
	v_xor_b32_e32 v235, v252, v235
	v_xor_b32_e32 v236, v252, v236
	v_xor_b32_e32 v237, v252, v237
	v_pk_add_f32 v[244:245], v[244:245], v[234:235]
	v_pk_add_f32 v[246:247], v[246:247], v[236:237]
	v_cndmask_b32_e64 v92, v92, v244, s[4:5]
	v_cndmask_b32_e64 v93, v93, v245, s[4:5]
	v_cndmask_b32_e64 v94, v94, v246, s[4:5]
	v_cndmask_b32_e64 v95, v95, v247, s[4:5]
	v_pk_mul_f32 v[88:89], v[88:89], s[28:29] op_sel_hi:[1,0]
	v_pk_mul_f32 v[90:91], v[90:91], s[28:29] op_sel_hi:[1,0]
	v_pk_mul_f32 v[92:93], v[92:93], s[28:29] op_sel_hi:[1,0]
	v_pk_mul_f32 v[94:95], v[94:95], s[28:29] op_sel_hi:[1,0]
	v_cvt_pk_bf16_f32 v248, v88, v89
	v_cvt_pk_bf16_f32 v249, v90, v91
	v_cvt_pk_bf16_f32 v250, v92, v93
	v_cvt_pk_bf16_f32 v251, v94, v95
	global_store_dwordx4 v169, v[248:251], s[26:27]
	s_nop 1
	ds_bpermute_b32 v230, v202, v80
	ds_bpermute_b32 v231, v202, v81
	ds_bpermute_b32 v232, v202, v82
	ds_bpermute_b32 v233, v202, v83
	ds_bpermute_b32 v234, v202, v84
	ds_bpermute_b32 v235, v202, v85
	ds_bpermute_b32 v236, v202, v86
	ds_bpermute_b32 v237, v202, v87
	s_waitcnt lgkmcnt(8)
	v_pk_mul_f32 v[196:197], v[188:189], v[196:197]
	v_pk_mul_f32 v[198:199], v[190:191], v[198:199]
	v_pk_mul_f32 v[244:245], v[24:25], v[180:181]
	v_pk_mul_f32 v[246:247], v[26:27], v[182:183]
	v_xor_b32_e32 v196, v252, v196
	v_xor_b32_e32 v197, v252, v197
	v_xor_b32_e32 v198, v252, v198
	v_xor_b32_e32 v199, v252, v199
	v_pk_add_f32 v[244:245], v[244:245], v[196:197]
	v_pk_add_f32 v[246:247], v[246:247], v[198:199]
	v_cndmask_b32_e64 v24, v24, v244, s[4:5]
	v_cndmask_b32_e64 v25, v25, v245, s[4:5]
	v_cndmask_b32_e64 v26, v26, v246, s[4:5]
	v_cndmask_b32_e64 v27, v27, v247, s[4:5]
	v_pk_mul_f32 v[156:157], v[192:193], v[156:157]
	v_pk_mul_f32 v[158:159], v[194:195], v[158:159]
	v_pk_mul_f32 v[244:245], v[28:29], v[184:185]
	v_pk_mul_f32 v[246:247], v[30:31], v[186:187]
	v_xor_b32_e32 v156, v252, v156
	v_xor_b32_e32 v157, v252, v157
	v_xor_b32_e32 v158, v252, v158
	v_xor_b32_e32 v159, v252, v159
	v_pk_add_f32 v[244:245], v[244:245], v[156:157]
	v_pk_add_f32 v[246:247], v[246:247], v[158:159]
	v_cndmask_b32_e64 v28, v28, v244, s[4:5]
	v_cndmask_b32_e64 v29, v29, v245, s[4:5]
	v_cndmask_b32_e64 v30, v30, v246, s[4:5]
	v_cndmask_b32_e64 v31, v31, v247, s[4:5]
	v_pk_mul_f32 v[24:25], v[24:25], s[28:29] op_sel_hi:[1,0]
	v_pk_mul_f32 v[26:27], v[26:27], s[28:29] op_sel_hi:[1,0]
	v_pk_mul_f32 v[28:29], v[28:29], s[28:29] op_sel_hi:[1,0]
	v_pk_mul_f32 v[30:31], v[30:31], s[28:29] op_sel_hi:[1,0]
	v_cvt_pk_bf16_f32 v248, v24, v25
	v_cvt_pk_bf16_f32 v249, v26, v27
	v_cvt_pk_bf16_f32 v250, v28, v29
	v_cvt_pk_bf16_f32 v251, v30, v31
	global_store_dwordx4 v169, v[248:251], s[98:99]
	s_nop 1
	s_add_u32 s26, s26, 0x800
	s_addc_u32 s27, s27, 0
	s_add_u32 s98, s98, 0x800
	s_addc_u32 s99, s99, 0
	global_load_dwordx4 v[180:183], v168, s[24:25] offset:3072
	global_load_dwordx4 v[184:187], v168, s[24:25] offset:3088
	global_load_dwordx4 v[188:191], v168, s[24:25] offset:3104
	global_load_dwordx4 v[192:195], v168, s[24:25] offset:3120
	ds_bpermute_b32 v196, v202, v16
	ds_bpermute_b32 v197, v202, v17
	ds_bpermute_b32 v198, v202, v18
	ds_bpermute_b32 v199, v202, v19
	ds_bpermute_b32 v156, v202, v20
	ds_bpermute_b32 v157, v202, v21
	ds_bpermute_b32 v158, v202, v22
	ds_bpermute_b32 v159, v202, v23
	s_waitcnt vmcnt(12)
	s_waitcnt lgkmcnt(8)
	v_pk_mul_f32 v[230:231], v[222:223], v[230:231]
	v_pk_mul_f32 v[232:233], v[224:225], v[232:233]
	v_pk_mul_f32 v[244:245], v[80:81], v[214:215]
	v_pk_mul_f32 v[246:247], v[82:83], v[216:217]
	v_xor_b32_e32 v230, v252, v230
	v_xor_b32_e32 v231, v252, v231
	v_xor_b32_e32 v232, v252, v232
	v_xor_b32_e32 v233, v252, v233
	v_pk_add_f32 v[244:245], v[244:245], v[230:231]
	v_pk_add_f32 v[246:247], v[246:247], v[232:233]
	v_cndmask_b32_e64 v80, v80, v244, s[4:5]
	v_cndmask_b32_e64 v81, v81, v245, s[4:5]
	v_cndmask_b32_e64 v82, v82, v246, s[4:5]
	v_cndmask_b32_e64 v83, v83, v247, s[4:5]
	v_pk_mul_f32 v[234:235], v[226:227], v[234:235]
	v_pk_mul_f32 v[236:237], v[228:229], v[236:237]
	v_pk_mul_f32 v[244:245], v[84:85], v[218:219]
	v_pk_mul_f32 v[246:247], v[86:87], v[220:221]
	v_xor_b32_e32 v234, v252, v234
	v_xor_b32_e32 v235, v252, v235
	v_xor_b32_e32 v236, v252, v236
	v_xor_b32_e32 v237, v252, v237
	v_pk_add_f32 v[244:245], v[244:245], v[234:235]
	v_pk_add_f32 v[246:247], v[246:247], v[236:237]
	v_cndmask_b32_e64 v84, v84, v244, s[4:5]
	v_cndmask_b32_e64 v85, v85, v245, s[4:5]
	v_cndmask_b32_e64 v86, v86, v246, s[4:5]
	v_cndmask_b32_e64 v87, v87, v247, s[4:5]
	v_pk_mul_f32 v[80:81], v[80:81], s[28:29] op_sel_hi:[1,0]
	v_pk_mul_f32 v[82:83], v[82:83], s[28:29] op_sel_hi:[1,0]
	v_pk_mul_f32 v[84:85], v[84:85], s[28:29] op_sel_hi:[1,0]
	v_pk_mul_f32 v[86:87], v[86:87], s[28:29] op_sel_hi:[1,0]
	v_cvt_pk_bf16_f32 v248, v80, v81
	v_cvt_pk_bf16_f32 v249, v82, v83
	v_cvt_pk_bf16_f32 v250, v84, v85
	v_cvt_pk_bf16_f32 v251, v86, v87
	global_store_dwordx4 v169, v[248:251], s[26:27]
	s_nop 1
	ds_bpermute_b32 v230, v202, v72
	ds_bpermute_b32 v231, v202, v73
	ds_bpermute_b32 v232, v202, v74
	ds_bpermute_b32 v233, v202, v75
	ds_bpermute_b32 v234, v202, v76
	ds_bpermute_b32 v235, v202, v77
	ds_bpermute_b32 v236, v202, v78
	ds_bpermute_b32 v237, v202, v79
	s_waitcnt lgkmcnt(8)
; __device__ __forceinline__ unsigned cvt_pk_bf16(float lo, float hi) { const f32x2c v = {lo, hi}; const bf16x2c b = __builtin_convertvector(v, bf16x2c); return __builtin_bit_cast(unsigned, b); }
; #define PG8_GAS __attribute__((address_space(1)))
;     __device__ __forceinline__ void operator()(const f32x4 (&acc)[2][2][4][2], const Unit& u, int wr, int wc, int fr, int fq) const {
;     ...
;                         const int r = rbase + ai * HALF + m * 16; const int s = r & 8191;
;                         f32x4 v0 = acc[ai][bj][m][0], v1 = acc[ai][bj][m][1];
;                         if (rotw) {
;                             f32x4 p0, p1;
; #pragma unroll
;                             for (int j = 0; j < 4; ++j) { p0[j] = __shfl_xor(v0[j], 16); p1[j] = __shfl_xor(v1[j], 16); }
;                             if (fq < 2) {
;                                 const f32x4 c0 = *(const PG8_GAS f32x4*)(rope + (size_t)r * 16), c1 = *(const PG8_GAS f32x4*)(rope + (size_t)r * 16 + 4);
;                                 const f32x4 s0 = *(const PG8_GAS f32x4*)(rope + (size_t)r * 16 + 8), s1 = *(const PG8_GAS f32x4*)(rope + (size_t)r * 16 + 12);
;                                 if (fq == 0) { v0 = v0 * c0 - p0 * s0; v1 = v1 * c1 - p1 * s1; }
;                                 else { v0 = v0 * c0 + p0 * s0; v1 = v1 * c1 + p1 * s1; }
;                             }
;                         }
;                         if (seg == 0) { v0 = v0 * 0.18033688011112042f; v1 = v1 * 0.18033688011112042f; }
;                         u32x4 w; w.x = cvt_pk_bf16(v0[0], v0[1]); w.y = cvt_pk_bf16(v0[2], v0[3]); w.z = cvt_pk_bf16(v1[0], v1[1]); w.w = cvt_pk_bf16(v1[2], v1[3]);
;                         *(PG8_GAS u32x4*)(segp + ((size_t)((b * 8 + head) * 8192 + s)) * 64 + ch) = w;
	v_pk_mul_f32 v[196:197], v[222:223], v[196:197]
	v_pk_mul_f32 v[198:199], v[224:225], v[198:199]
	v_pk_mul_f32 v[244:245], v[16:17], v[214:215]
	v_pk_mul_f32 v[246:247], v[18:19], v[216:217]
	v_xor_b32_e32 v196, v252, v196
	v_xor_b32_e32 v197, v252, v197
	v_xor_b32_e32 v198, v252, v198
	v_xor_b32_e32 v199, v252, v199
	v_pk_add_f32 v[244:245], v[244:245], v[196:197]
	v_pk_add_f32 v[246:247], v[246:247], v[198:199]
	v_cndmask_b32_e64 v16, v16, v244, s[4:5]
	v_cndmask_b32_e64 v17, v17, v245, s[4:5]
	v_cndmask_b32_e64 v18, v18, v246, s[4:5]
	v_cndmask_b32_e64 v19, v19, v247, s[4:5]
	v_pk_mul_f32 v[156:157], v[226:227], v[156:157]
	v_pk_mul_f32 v[158:159], v[228:229], v[158:159]
	v_pk_mul_f32 v[244:245], v[20:21], v[218:219]
	v_pk_mul_f32 v[246:247], v[22:23], v[220:221]
	v_xor_b32_e32 v156, v252, v156
	v_xor_b32_e32 v157, v252, v157
	v_xor_b32_e32 v158, v252, v158
	v_xor_b32_e32 v159, v252, v159
	v_pk_add_f32 v[244:245], v[244:245], v[156:157]
	v_pk_add_f32 v[246:247], v[246:247], v[158:159]
	v_cndmask_b32_e64 v20, v20, v244, s[4:5]
	v_cndmask_b32_e64 v21, v21, v245, s[4:5]
	v_cndmask_b32_e64 v22, v22, v246, s[4:5]
	v_cndmask_b32_e64 v23, v23, v247, s[4:5]
	v_pk_mul_f32 v[16:17], v[16:17], s[28:29] op_sel_hi:[1,0]
	v_pk_mul_f32 v[18:19], v[18:19], s[28:29] op_sel_hi:[1,0]
	v_pk_mul_f32 v[20:21], v[20:21], s[28:29] op_sel_hi:[1,0]
	v_pk_mul_f32 v[22:23], v[22:23], s[28:29] op_sel_hi:[1,0]
	v_cvt_pk_bf16_f32 v248, v16, v17
	v_cvt_pk_bf16_f32 v249, v18, v19
	v_cvt_pk_bf16_f32 v250, v20, v21
	v_cvt_pk_bf16_f32 v251, v22, v23
	global_store_dwordx4 v169, v[248:251], s[98:99]
	s_nop 1
	s_add_u32 s26, s26, 0x800
	s_addc_u32 s27, s27, 0
	s_add_u32 s98, s98, 0x800
	s_addc_u32 s99, s99, 0
	ds_bpermute_b32 v196, v202, v8
	ds_bpermute_b32 v197, v202, v9
	ds_bpermute_b32 v198, v202, v10
	ds_bpermute_b32 v199, v202, v11
	ds_bpermute_b32 v156, v202, v12
	ds_bpermute_b32 v157, v202, v13
	ds_bpermute_b32 v158, v202, v14
	ds_bpermute_b32 v159, v202, v15
	s_waitcnt vmcnt(8)
	s_waitcnt lgkmcnt(8)
	v_pk_mul_f32 v[230:231], v[136:137], v[230:231]
	v_pk_mul_f32 v[232:233], v[138:139], v[232:233]
	v_pk_mul_f32 v[244:245], v[72:73], v[128:129]
	v_pk_mul_f32 v[246:247], v[74:75], v[130:131]
	v_xor_b32_e32 v230, v252, v230
	v_xor_b32_e32 v231, v252, v231
	v_xor_b32_e32 v232, v252, v232
	v_xor_b32_e32 v233, v252, v233
	v_pk_add_f32 v[244:245], v[244:245], v[230:231]
	v_pk_add_f32 v[246:247], v[246:247], v[232:233]
	v_cndmask_b32_e64 v72, v72, v244, s[4:5]
	v_cndmask_b32_e64 v73, v73, v245, s[4:5]
	v_cndmask_b32_e64 v74, v74, v246, s[4:5]
	v_cndmask_b32_e64 v75, v75, v247, s[4:5]
	v_pk_mul_f32 v[234:235], v[140:141], v[234:235]
	v_pk_mul_f32 v[236:237], v[142:143], v[236:237]
	v_pk_mul_f32 v[244:245], v[76:77], v[132:133]
	v_pk_mul_f32 v[246:247], v[78:79], v[134:135]
	v_xor_b32_e32 v234, v252, v234
	v_xor_b32_e32 v235, v252, v235
	v_xor_b32_e32 v236, v252, v236
	v_xor_b32_e32 v237, v252, v237
	v_pk_add_f32 v[244:245], v[244:245], v[234:235]
	v_pk_add_f32 v[246:247], v[246:247], v[236:237]
	v_cndmask_b32_e64 v76, v76, v244, s[4:5]
	v_cndmask_b32_e64 v77, v77, v245, s[4:5]
	v_cndmask_b32_e64 v78, v78, v246, s[4:5]
	v_cndmask_b32_e64 v79, v79, v247, s[4:5]
	v_pk_mul_f32 v[72:73], v[72:73], s[28:29] op_sel_hi:[1,0]
	v_pk_mul_f32 v[74:75], v[74:75], s[28:29] op_sel_hi:[1,0]
	v_pk_mul_f32 v[76:77], v[76:77], s[28:29] op_sel_hi:[1,0]
	v_pk_mul_f32 v[78:79], v[78:79], s[28:29] op_sel_hi:[1,0]
	v_cvt_pk_bf16_f32 v248, v72, v73
	v_cvt_pk_bf16_f32 v249, v74, v75
	v_cvt_pk_bf16_f32 v250, v76, v77
	v_cvt_pk_bf16_f32 v251, v78, v79
	global_store_dwordx4 v169, v[248:251], s[26:27]
	s_nop 1
	ds_bpermute_b32 v230, v202, v64
	ds_bpermute_b32 v231, v202, v65
	ds_bpermute_b32 v232, v202, v66
	ds_bpermute_b32 v233, v202, v67
	ds_bpermute_b32 v234, v202, v68
	ds_bpermute_b32 v235, v202, v69
	ds_bpermute_b32 v236, v202, v70
	ds_bpermute_b32 v237, v202, v71
	s_waitcnt lgkmcnt(8)
; __device__ __forceinline__ unsigned cvt_pk_bf16(float lo, float hi) { const f32x2c v = {lo, hi}; const bf16x2c b = __builtin_convertvector(v, bf16x2c); return __builtin_bit_cast(unsigned, b); }
; #define PG8_GAS __attribute__((address_space(1)))
;     __device__ __forceinline__ void operator()(const f32x4 (&acc)[2][2][4][2], const Unit& u, int wr, int wc, int fr, int fq) const {
;     ...
;                         const int r = rbase + ai * HALF + m * 16; const int s = r & 8191;
;                         f32x4 v0 = acc[ai][bj][m][0], v1 = acc[ai][bj][m][1];
;                         if (rotw) {
;                             f32x4 p0, p1;
; #pragma unroll
;                             for (int j = 0; j < 4; ++j) { p0[j] = __shfl_xor(v0[j], 16); p1[j] = __shfl_xor(v1[j], 16); }
;                             if (fq < 2) {
;                                 const f32x4 c0 = *(const PG8_GAS f32x4*)(rope + (size_t)r * 16), c1 = *(const PG8_GAS f32x4*)(rope + (size_t)r * 16 + 4);
;                                 const f32x4 s0 = *(const PG8_GAS f32x4*)(rope + (size_t)r * 16 + 8), s1 = *(const PG8_GAS f32x4*)(rope + (size_t)r * 16 + 12);
;                                 if (fq == 0) { v0 = v0 * c0 - p0 * s0; v1 = v1 * c1 - p1 * s1; }
;                                 else { v0 = v0 * c0 + p0 * s0; v1 = v1 * c1 + p1 * s1; }
;                             }
;                         }
;                         if (seg == 0) { v0 = v0 * 0.18033688011112042f; v1 = v1 * 0.18033688011112042f; }
;                         u32x4 w; w.x = cvt_pk_bf16(v0[0], v0[1]); w.y = cvt_pk_bf16(v0[2], v0[3]); w.z = cvt_pk_bf16(v1[0], v1[1]); w.w = cvt_pk_bf16(v1[2], v1[3]);
;                         *(PG8_GAS u32x4*)(segp + ((size_t)((b * 8 + head) * 8192 + s)) * 64 + ch) = w;
	v_pk_mul_f32 v[196:197], v[136:137], v[196:197]
	v_pk_mul_f32 v[198:199], v[138:139], v[198:199]
	v_pk_mul_f32 v[244:245], v[8:9], v[128:129]
	v_pk_mul_f32 v[246:247], v[10:11], v[130:131]
	v_xor_b32_e32 v196, v252, v196
	v_xor_b32_e32 v197, v252, v197
	v_xor_b32_e32 v198, v252, v198
	v_xor_b32_e32 v199, v252, v199
	v_pk_add_f32 v[244:245], v[244:245], v[196:197]
	v_pk_add_f32 v[246:247], v[246:247], v[198:199]
	v_cndmask_b32_e64 v8, v8, v244, s[4:5]
	v_cndmask_b32_e64 v9, v9, v245, s[4:5]
	v_cndmask_b32_e64 v10, v10, v246, s[4:5]
	v_cndmask_b32_e64 v11, v11, v247, s[4:5]
	v_pk_mul_f32 v[156:157], v[140:141], v[156:157]
	v_pk_mul_f32 v[158:159], v[142:143], v[158:159]
	v_pk_mul_f32 v[244:245], v[12:13], v[132:133]
	v_pk_mul_f32 v[246:247], v[14:15], v[134:135]
	v_xor_b32_e32 v156, v252, v156
	v_xor_b32_e32 v157, v252, v157
	v_xor_b32_e32 v158, v252, v158
	v_xor_b32_e32 v159, v252, v159
	v_pk_add_f32 v[244:245], v[244:245], v[156:157]
	v_pk_add_f32 v[246:247], v[246:247], v[158:159]
	v_cndmask_b32_e64 v12, v12, v244, s[4:5]
	v_cndmask_b32_e64 v13, v13, v245, s[4:5]
	v_cndmask_b32_e64 v14, v14, v246, s[4:5]
	v_cndmask_b32_e64 v15, v15, v247, s[4:5]
	v_pk_mul_f32 v[8:9], v[8:9], s[28:29] op_sel_hi:[1,0]
	v_pk_mul_f32 v[10:11], v[10:11], s[28:29] op_sel_hi:[1,0]
	v_pk_mul_f32 v[12:13], v[12:13], s[28:29] op_sel_hi:[1,0]
	v_pk_mul_f32 v[14:15], v[14:15], s[28:29] op_sel_hi:[1,0]
	v_cvt_pk_bf16_f32 v248, v8, v9
	v_cvt_pk_bf16_f32 v249, v10, v11
	v_cvt_pk_bf16_f32 v250, v12, v13
	v_cvt_pk_bf16_f32 v251, v14, v15
	global_store_dwordx4 v169, v[248:251], s[98:99]
	s_nop 1
	s_add_u32 s26, s26, 0x800
	s_addc_u32 s27, s27, 0
	s_add_u32 s98, s98, 0x800
	s_addc_u32 s99, s99, 0
	ds_bpermute_b32 v196, v202, v4
	ds_bpermute_b32 v197, v202, v5
	ds_bpermute_b32 v198, v202, v6
	ds_bpermute_b32 v199, v202, v7
	ds_bpermute_b32 v156, v202, v0
	ds_bpermute_b32 v157, v202, v1
	ds_bpermute_b32 v158, v202, v2
	ds_bpermute_b32 v159, v202, v3
	s_waitcnt vmcnt(4)
	s_waitcnt lgkmcnt(8)
	v_pk_mul_f32 v[230:231], v[188:189], v[230:231]
	v_pk_mul_f32 v[232:233], v[190:191], v[232:233]
	v_pk_mul_f32 v[244:245], v[64:65], v[180:181]
	v_pk_mul_f32 v[246:247], v[66:67], v[182:183]
	v_xor_b32_e32 v230, v252, v230
	v_xor_b32_e32 v231, v252, v231
	v_xor_b32_e32 v232, v252, v232
	v_xor_b32_e32 v233, v252, v233
	v_pk_add_f32 v[244:245], v[244:245], v[230:231]
	v_pk_add_f32 v[246:247], v[246:247], v[232:233]
	v_cndmask_b32_e64 v64, v64, v244, s[4:5]
	v_cndmask_b32_e64 v65, v65, v245, s[4:5]
	v_cndmask_b32_e64 v66, v66, v246, s[4:5]
	v_cndmask_b32_e64 v67, v67, v247, s[4:5]
	v_pk_mul_f32 v[234:235], v[192:193], v[234:235]
	v_pk_mul_f32 v[236:237], v[194:195], v[236:237]
	v_pk_mul_f32 v[244:245], v[68:69], v[184:185]
	v_pk_mul_f32 v[246:247], v[70:71], v[186:187]
	v_xor_b32_e32 v234, v252, v234
	v_xor_b32_e32 v235, v252, v235
	v_xor_b32_e32 v236, v252, v236
	v_xor_b32_e32 v237, v252, v237
	v_pk_add_f32 v[244:245], v[244:245], v[234:235]
	v_pk_add_f32 v[246:247], v[246:247], v[236:237]
	v_cndmask_b32_e64 v68, v68, v244, s[4:5]
	v_cndmask_b32_e64 v69, v69, v245, s[4:5]
	v_cndmask_b32_e64 v70, v70, v246, s[4:5]
	v_cndmask_b32_e64 v71, v71, v247, s[4:5]
	v_pk_mul_f32 v[64:65], v[64:65], s[28:29] op_sel_hi:[1,0]
	v_pk_mul_f32 v[66:67], v[66:67], s[28:29] op_sel_hi:[1,0]
	v_pk_mul_f32 v[68:69], v[68:69], s[28:29] op_sel_hi:[1,0]
	v_pk_mul_f32 v[70:71], v[70:71], s[28:29] op_sel_hi:[1,0]
	v_cvt_pk_bf16_f32 v248, v64, v65
	v_cvt_pk_bf16_f32 v249, v66, v67
	v_cvt_pk_bf16_f32 v250, v68, v69
	v_cvt_pk_bf16_f32 v251, v70, v71
	global_store_dwordx4 v169, v[248:251], s[26:27]
	s_nop 1
	s_waitcnt lgkmcnt(0)
	v_pk_mul_f32 v[196:197], v[188:189], v[196:197]
	v_pk_mul_f32 v[198:199], v[190:191], v[198:199]
	v_pk_mul_f32 v[244:245], v[4:5], v[180:181]
	v_pk_mul_f32 v[246:247], v[6:7], v[182:183]
	v_xor_b32_e32 v196, v252, v196
	v_xor_b32_e32 v197, v252, v197
	v_xor_b32_e32 v198, v252, v198
	v_xor_b32_e32 v199, v252, v199
	v_pk_add_f32 v[244:245], v[244:245], v[196:197]
	v_pk_add_f32 v[246:247], v[246:247], v[198:199]
	v_cndmask_b32_e64 v4, v4, v244, s[4:5]
	v_cndmask_b32_e64 v5, v5, v245, s[4:5]
	v_cndmask_b32_e64 v6, v6, v246, s[4:5]
	v_cndmask_b32_e64 v7, v7, v247, s[4:5]
	v_pk_mul_f32 v[156:157], v[192:193], v[156:157]
	v_pk_mul_f32 v[158:159], v[194:195], v[158:159]
	v_pk_mul_f32 v[244:245], v[0:1], v[184:185]
	v_pk_mul_f32 v[246:247], v[2:3], v[186:187]
	v_xor_b32_e32 v156, v252, v156
	v_xor_b32_e32 v157, v252, v157
	v_xor_b32_e32 v158, v252, v158
	v_xor_b32_e32 v159, v252, v159
	v_pk_add_f32 v[244:245], v[244:245], v[156:157]
	v_pk_add_f32 v[246:247], v[246:247], v[158:159]
	v_cndmask_b32_e64 v0, v0, v244, s[4:5]
	v_cndmask_b32_e64 v1, v1, v245, s[4:5]
	v_cndmask_b32_e64 v2, v2, v246, s[4:5]
	v_cndmask_b32_e64 v3, v3, v247, s[4:5]
	v_pk_mul_f32 v[4:5], v[4:5], s[28:29] op_sel_hi:[1,0]
	v_pk_mul_f32 v[6:7], v[6:7], s[28:29] op_sel_hi:[1,0]
	v_pk_mul_f32 v[0:1], v[0:1], s[28:29] op_sel_hi:[1,0]
	v_pk_mul_f32 v[2:3], v[2:3], s[28:29] op_sel_hi:[1,0]
	v_cvt_pk_bf16_f32 v248, v4, v5
	v_cvt_pk_bf16_f32 v249, v6, v7
	v_cvt_pk_bf16_f32 v250, v0, v1
	v_cvt_pk_bf16_f32 v251, v2, v3
	global_store_dwordx4 v169, v[248:251], s[98:99]
	s_nop 1
	s_branch .Lrope_done

; __device__ __forceinline__ unsigned cvt_pk_bf16(float lo, float hi) { const f32x2c v = {lo, hi}; const bf16x2c b = __builtin_convertvector(v, bf16x2c); return __builtin_bit_cast(unsigned, b); }
; #define PG8_GAS __attribute__((address_space(1)))
; __device__ __forceinline__ float gate_logf(float fp, float lb) {
;     const float e = __expf(-fabsf(fp)), l1pe = __logf(1.f + e);
;     return (fp >= 0.f ? __logf(1.f + lb * e) : (lb > 0.f ? __logf(lb + e) : fp)) - l1pe;
; }
;     __device__ __forceinline__ void operator()(const f32x4 (&acc)[2][2][4][2], const Unit& u, int wr, int wc, int fr, int fq) const {
;     ...
;                         if (seg == 4) {
;                             const f32x4 l0 = *(const PG8_GAS f32x4*)(lbl + wcol), l1 = *(const PG8_GAS f32x4*)(lbl + wcol + 4);
; #pragma unroll
;                             for (int j = 0; j < 4; ++j) { v0[j] = gate_logf(v0[j], l0[j]); v1[j] = gate_logf(v1[j], l1[j]); }
;                         }
;                         u32x4 w;
;                         if (seg == 4) { w.x = cvt_pk_f16(v0[0], v0[1]); w.y = cvt_pk_f16(v0[2], v0[3]); w.z = cvt_pk_f16(v1[0], v1[1]); w.w = cvt_pk_f16(v1[2], v1[3]); }
;                         else { w.x = cvt_pk_bf16(v0[0], v0[1]); w.y = cvt_pk_bf16(v0[2], v0[3]); w.z = cvt_pk_bf16(v1[0], v1[1]); w.w = cvt_pk_bf16(v1[2], v1[3]); }
;                         *(PG8_GAS u32x4*)(segp + (size_t)r * 512 + wcol) = w;
.Llogf_new:
	v_readlane_b32 s30, v255, 12
	s_and_b32 s31, s0, 1
	s_lshl_b32 s31, s31, 10
	s_nop 0
	s_lshl_b32 s32, s30, 2
	s_add_u32 s31, s31, s32
	s_add_u32 s24, s72, s31
	s_addc_u32 s25, s73, 0
	v_lshlrev_b32_e32 v168, 2, v161
	global_load_dwordx4 v[128:131], v168, s[24:25] offset:0
	global_load_dwordx4 v[132:135], v168, s[24:25] offset:16
	global_load_dwordx4 v[136:139], v168, s[24:25] offset:512
	global_load_dwordx4 v[140:143], v168, s[24:25] offset:528
	s_and_b32 s31, s0, 1
	s_lshl_b32 s31, s31, 9
	s_lshl_b32 s32, s54, 18
	s_add_u32 s31, s31, s32
	s_add_u32 s31, s31, 0x10000000
	s_add_u32 s26, s92, s31
	s_addc_u32 s27, s93, 0
	s_lshl_b32 s32, s30, 1
	v_lshlrev_b32_e32 v169, 10, v160
	v_lshl_add_u32 v169, v161, 1, v169
	v_add_u32_e32 v169, s32, v169
	s_waitcnt vmcnt(0)
	v_cmp_lt_f32_e32 vcc, 0, v128
	s_nop 1
	v_cndmask_b32_e64 v180, 0, -1, vcc
	v_cmp_lt_f32_e32 vcc, 0, v129
	s_nop 1
	v_cndmask_b32_e64 v181, 0, -1, vcc
	v_cmp_lt_f32_e32 vcc, 0, v130
	s_nop 1
	v_cndmask_b32_e64 v182, 0, -1, vcc
	v_cmp_lt_f32_e32 vcc, 0, v131
	s_nop 1
	v_cndmask_b32_e64 v183, 0, -1, vcc
	v_cmp_lt_f32_e32 vcc, 0, v132
	s_nop 1
	v_cndmask_b32_e64 v184, 0, -1, vcc
	v_cmp_lt_f32_e32 vcc, 0, v133
	s_nop 1
	v_cndmask_b32_e64 v185, 0, -1, vcc
	v_cmp_lt_f32_e32 vcc, 0, v134
	s_nop 1
	v_cndmask_b32_e64 v186, 0, -1, vcc
	v_cmp_lt_f32_e32 vcc, 0, v135
	s_nop 1
	v_cndmask_b32_e64 v187, 0, -1, vcc
	v_cmp_lt_f32_e32 vcc, 0, v136
	s_nop 1
	v_cndmask_b32_e64 v188, 0, -1, vcc
	v_cmp_lt_f32_e32 vcc, 0, v137
	s_nop 1
	v_cndmask_b32_e64 v189, 0, -1, vcc
	v_cmp_lt_f32_e32 vcc, 0, v138
	s_nop 1
	v_cndmask_b32_e64 v190, 0, -1, vcc
	v_cmp_lt_f32_e32 vcc, 0, v139
	s_nop 1
	v_cndmask_b32_e64 v191, 0, -1, vcc
	v_cmp_lt_f32_e32 vcc, 0, v140
	s_nop 1
	v_cndmask_b32_e64 v192, 0, -1, vcc
	v_cmp_lt_f32_e32 vcc, 0, v141
	s_nop 1
	v_cndmask_b32_e64 v193, 0, -1, vcc
	v_cmp_lt_f32_e32 vcc, 0, v142
	s_nop 1
	v_cndmask_b32_e64 v194, 0, -1, vcc
	v_cmp_lt_f32_e32 vcc, 0, v143
	s_nop 1
	v_cndmask_b32_e64 v195, 0, -1, vcc
	v_mul_f32_e64 v226, |v120|, s83
	v_mul_f32_e64 v227, |v121|, s83
	v_mul_f32_e64 v228, |v122|, s83
	v_mul_f32_e64 v229, |v123|, s83
	v_exp_f32_e32 v214, v226
	v_exp_f32_e32 v215, v227
	v_exp_f32_e32 v216, v228
	v_exp_f32_e32 v217, v229
	v_cmp_le_f32_e64 s[24:25], 0, v120
	v_cmp_le_f32_e64 s[28:29], 0, v121
	v_cmp_le_f32_e64 s[30:31], 0, v122
	v_cmp_le_f32_e64 s[98:99], 0, v123
	v_fma_f32 v218, v214, v128, 1.0
	v_fma_f32 v219, v215, v129, 1.0
	v_fma_f32 v220, v216, v130, 1.0
	v_fma_f32 v221, v217, v131, 1.0
	v_add_f32_e32 v222, v214, v128
	v_add_f32_e32 v223, v215, v129
	v_add_f32_e32 v224, v216, v130
	v_add_f32_e32 v225, v217, v131
	v_cndmask_b32_e64 v218, v222, v218, s[24:25]
	v_cndmask_b32_e64 v219, v223, v219, s[28:29]
	v_cndmask_b32_e64 v220, v224, v220, s[30:31]
	v_cndmask_b32_e64 v221, v225, v221, s[98:99]
	v_cndmask_b32_e64 v230, v180, -1, s[24:25]
	v_cndmask_b32_e64 v231, v181, -1, s[28:29]
	v_cndmask_b32_e64 v232, v182, -1, s[30:31]
	v_cndmask_b32_e64 v233, v183, -1, s[98:99]
	v_cmp_gt_f32_e64 s[24:25], s35, v218
	v_cmp_gt_f32_e64 s[28:29], s35, v219
	v_cmp_gt_f32_e64 s[30:31], s35, v220
	v_cmp_gt_f32_e64 s[98:99], s35, v221
	v_add_f32_e32 v222, 1.0, v214
	v_add_f32_e32 v223, 1.0, v215
	v_add_f32_e32 v224, 1.0, v216
	v_add_f32_e32 v225, 1.0, v217
	v_cndmask_b32_e64 v226, 0, 32, s[24:25]
	v_cndmask_b32_e64 v227, 0, 32, s[28:29]
	v_cndmask_b32_e64 v228, 0, 32, s[30:31]
	v_cndmask_b32_e64 v229, 0, 32, s[98:99]
	v_cndmask_b32_e64 v238, 0, v213, s[24:25]
	v_cndmask_b32_e64 v239, 0, v213, s[28:29]
	v_cndmask_b32_e64 v240, 0, v213, s[30:31]
	v_cndmask_b32_e64 v241, 0, v213, s[98:99]
	v_ldexp_f32 v218, v218, v226
	v_ldexp_f32 v219, v219, v227
	v_ldexp_f32 v220, v220, v228
	v_ldexp_f32 v221, v221, v229
	v_log_f32_e32 v218, v218
	v_log_f32_e32 v219, v219
	v_log_f32_e32 v220, v220
	v_log_f32_e32 v221, v221
	v_log_f32_e32 v222, v222
	v_log_f32_e32 v223, v223
	v_log_f32_e32 v224, v224
	v_log_f32_e32 v225, v225
	v_mul_f32_e32 v226, 0x3f317217, v218
	v_mul_f32_e32 v227, 0x3f317217, v219
	v_mul_f32_e32 v228, 0x3f317217, v220
	v_mul_f32_e32 v229, 0x3f317217, v221
	v_fma_f32 v226, v218, s70, -v226
	v_fma_f32 v227, v219, s70, -v227
	v_fma_f32 v228, v220, s70, -v228
	v_fma_f32 v229, v221, s70, -v229
	v_fmac_f32_e32 v226, 0x3377d1cf, v218
	v_fmac_f32_e32 v227, 0x3377d1cf, v219
	v_fmac_f32_e32 v228, 0x3377d1cf, v220
	v_fmac_f32_e32 v229, 0x3377d1cf, v221
	v_fmac_f32_e32 v226, 0x3f317217, v218
	v_fmac_f32_e32 v227, 0x3f317217, v219
	v_fmac_f32_e32 v228, 0x3f317217, v220
	v_fmac_f32_e32 v229, 0x3f317217, v221
	v_cmp_lt_f32_e64 s[24:25], |v218|, s71
	v_cmp_lt_f32_e64 s[28:29], |v219|, s71
	v_cmp_lt_f32_e64 s[30:31], |v220|, s71
	v_cmp_lt_f32_e64 s[98:99], |v221|, s71
	v_cndmask_b32_e64 v218, v218, v226, s[24:25]
	v_cndmask_b32_e64 v219, v219, v227, s[28:29]
	v_cndmask_b32_e64 v220, v220, v228, s[30:31]
	v_cndmask_b32_e64 v221, v221, v229, s[98:99]
	v_sub_f32_e32 v218, v218, v238
	v_sub_f32_e32 v219, v219, v239
	v_sub_f32_e32 v220, v220, v240
	v_sub_f32_e32 v221, v221, v241
	v_mul_f32_e32 v226, 0x3f317217, v222
	v_mul_f32_e32 v227, 0x3f317217, v223
	v_mul_f32_e32 v228, 0x3f317217, v224
	v_mul_f32_e32 v229, 0x3f317217, v225
	v_fma_f32 v226, v222, s70, -v226
	v_fma_f32 v227, v223, s70, -v227
	v_fma_f32 v228, v224, s70, -v228
	v_fma_f32 v229, v225, s70, -v229
	v_fmac_f32_e32 v226, 0x3377d1cf, v222
	v_fmac_f32_e32 v227, 0x3377d1cf, v223
	v_fmac_f32_e32 v228, 0x3377d1cf, v224
	v_fmac_f32_e32 v229, 0x3377d1cf, v225
	v_fmac_f32_e32 v226, 0x3f317217, v222
	v_fmac_f32_e32 v227, 0x3f317217, v223
	v_fmac_f32_e32 v228, 0x3f317217, v224
	v_fmac_f32_e32 v229, 0x3f317217, v225
	v_bfi_b32 v218, v230, v218, v120
; __device__ __forceinline__ unsigned cvt_pk_bf16(float lo, float hi) { const f32x2c v = {lo, hi}; const bf16x2c b = __builtin_convertvector(v, bf16x2c); return __builtin_bit_cast(unsigned, b); }
; #define PG8_GAS __attribute__((address_space(1)))
; __device__ __forceinline__ float gate_logf(float fp, float lb) {
;     const float e = __expf(-fabsf(fp)), l1pe = __logf(1.f + e);
;     return (fp >= 0.f ? __logf(1.f + lb * e) : (lb > 0.f ? __logf(lb + e) : fp)) - l1pe;
; }
;     __device__ __forceinline__ void operator()(const f32x4 (&acc)[2][2][4][2], const Unit& u, int wr, int wc, int fr, int fq) const {
;     ...
;                         if (seg == 4) {
;                             const f32x4 l0 = *(const PG8_GAS f32x4*)(lbl + wcol), l1 = *(const PG8_GAS f32x4*)(lbl + wcol + 4);
; #pragma unroll
;                             for (int j = 0; j < 4; ++j) { v0[j] = gate_logf(v0[j], l0[j]); v1[j] = gate_logf(v1[j], l1[j]); }
;                         }
;                         u32x4 w;
;                         if (seg == 4) { w.x = cvt_pk_f16(v0[0], v0[1]); w.y = cvt_pk_f16(v0[2], v0[3]); w.z = cvt_pk_f16(v1[0], v1[1]); w.w = cvt_pk_f16(v1[2], v1[3]); }
;                         else { w.x = cvt_pk_bf16(v0[0], v0[1]); w.y = cvt_pk_bf16(v0[2], v0[3]); w.z = cvt_pk_bf16(v1[0], v1[1]); w.w = cvt_pk_bf16(v1[2], v1[3]); }
;                         *(PG8_GAS u32x4*)(segp + (size_t)r * 512 + wcol) = w;
	v_bfi_b32 v219, v231, v219, v121
	v_bfi_b32 v220, v232, v220, v122
	v_bfi_b32 v221, v233, v221, v123
	v_sub_f32_e32 v120, v218, v226
	v_sub_f32_e32 v121, v219, v227
	v_sub_f32_e32 v122, v220, v228
	v_sub_f32_e32 v123, v221, v229
	v_mul_f32_e64 v226, |v124|, s83
	v_mul_f32_e64 v227, |v125|, s83
	v_mul_f32_e64 v228, |v126|, s83
	v_mul_f32_e64 v229, |v127|, s83
	v_exp_f32_e32 v214, v226
	v_exp_f32_e32 v215, v227
	v_exp_f32_e32 v216, v228
	v_exp_f32_e32 v217, v229
	v_cmp_le_f32_e64 s[24:25], 0, v124
	v_cmp_le_f32_e64 s[28:29], 0, v125
	v_cmp_le_f32_e64 s[30:31], 0, v126
	v_cmp_le_f32_e64 s[98:99], 0, v127
	v_fma_f32 v218, v214, v132, 1.0
	v_fma_f32 v219, v215, v133, 1.0
	v_fma_f32 v220, v216, v134, 1.0
	v_fma_f32 v221, v217, v135, 1.0
	v_add_f32_e32 v222, v214, v132
	v_add_f32_e32 v223, v215, v133
	v_add_f32_e32 v224, v216, v134
	v_add_f32_e32 v225, v217, v135
	v_cndmask_b32_e64 v218, v222, v218, s[24:25]
	v_cndmask_b32_e64 v219, v223, v219, s[28:29]
	v_cndmask_b32_e64 v220, v224, v220, s[30:31]
	v_cndmask_b32_e64 v221, v225, v221, s[98:99]
	v_cndmask_b32_e64 v230, v184, -1, s[24:25]
	v_cndmask_b32_e64 v231, v185, -1, s[28:29]
	v_cndmask_b32_e64 v232, v186, -1, s[30:31]
	v_cndmask_b32_e64 v233, v187, -1, s[98:99]
	v_cmp_gt_f32_e64 s[24:25], s35, v218
	v_cmp_gt_f32_e64 s[28:29], s35, v219
	v_cmp_gt_f32_e64 s[30:31], s35, v220
	v_cmp_gt_f32_e64 s[98:99], s35, v221
	v_add_f32_e32 v222, 1.0, v214
	v_add_f32_e32 v223, 1.0, v215
	v_add_f32_e32 v224, 1.0, v216
	v_add_f32_e32 v225, 1.0, v217
	v_cndmask_b32_e64 v226, 0, 32, s[24:25]
	v_cndmask_b32_e64 v227, 0, 32, s[28:29]
	v_cndmask_b32_e64 v228, 0, 32, s[30:31]
	v_cndmask_b32_e64 v229, 0, 32, s[98:99]
	v_cndmask_b32_e64 v238, 0, v213, s[24:25]
	v_cndmask_b32_e64 v239, 0, v213, s[28:29]
	v_cndmask_b32_e64 v240, 0, v213, s[30:31]
	v_cndmask_b32_e64 v241, 0, v213, s[98:99]
	v_ldexp_f32 v218, v218, v226
	v_ldexp_f32 v219, v219, v227
	v_ldexp_f32 v220, v220, v228
	v_ldexp_f32 v221, v221, v229
	v_log_f32_e32 v218, v218
	v_log_f32_e32 v219, v219
	v_log_f32_e32 v220, v220
	v_log_f32_e32 v221, v221
	v_log_f32_e32 v222, v222
	v_log_f32_e32 v223, v223
	v_log_f32_e32 v224, v224
	v_log_f32_e32 v225, v225
	v_mul_f32_e32 v226, 0x3f317217, v218
	v_mul_f32_e32 v227, 0x3f317217, v219
	v_mul_f32_e32 v228, 0x3f317217, v220
	v_mul_f32_e32 v229, 0x3f317217, v221
	v_fma_f32 v226, v218, s70, -v226
	v_fma_f32 v227, v219, s70, -v227
	v_fma_f32 v228, v220, s70, -v228
	v_fma_f32 v229, v221, s70, -v229
	v_fmac_f32_e32 v226, 0x3377d1cf, v218
	v_fmac_f32_e32 v227, 0x3377d1cf, v219
	v_fmac_f32_e32 v228, 0x3377d1cf, v220
	v_fmac_f32_e32 v229, 0x3377d1cf, v221
	v_fmac_f32_e32 v226, 0x3f317217, v218
	v_fmac_f32_e32 v227, 0x3f317217, v219
	v_fmac_f32_e32 v228, 0x3f317217, v220
	v_fmac_f32_e32 v229, 0x3f317217, v221
	v_cmp_lt_f32_e64 s[24:25], |v218|, s71
	v_cmp_lt_f32_e64 s[28:29], |v219|, s71
	v_cmp_lt_f32_e64 s[30:31], |v220|, s71
	v_cmp_lt_f32_e64 s[98:99], |v221|, s71
	v_cndmask_b32_e64 v218, v218, v226, s[24:25]
	v_cndmask_b32_e64 v219, v219, v227, s[28:29]
	v_cndmask_b32_e64 v220, v220, v228, s[30:31]
	v_cndmask_b32_e64 v221, v221, v229, s[98:99]
	v_sub_f32_e32 v218, v218, v238
	v_sub_f32_e32 v219, v219, v239
	v_sub_f32_e32 v220, v220, v240
	v_sub_f32_e32 v221, v221, v241
	v_mul_f32_e32 v226, 0x3f317217, v222
	v_mul_f32_e32 v227, 0x3f317217, v223
	v_mul_f32_e32 v228, 0x3f317217, v224
	v_mul_f32_e32 v229, 0x3f317217, v225
	v_fma_f32 v226, v222, s70, -v226
	v_fma_f32 v227, v223, s70, -v227
	v_fma_f32 v228, v224, s70, -v228
	v_fma_f32 v229, v225, s70, -v229
	v_fmac_f32_e32 v226, 0x3377d1cf, v222
	v_fmac_f32_e32 v227, 0x3377d1cf, v223
	v_fmac_f32_e32 v228, 0x3377d1cf, v224
	v_fmac_f32_e32 v229, 0x3377d1cf, v225
	v_fmac_f32_e32 v226, 0x3f317217, v222
	v_fmac_f32_e32 v227, 0x3f317217, v223
	v_fmac_f32_e32 v228, 0x3f317217, v224
	v_fmac_f32_e32 v229, 0x3f317217, v225
	v_bfi_b32 v218, v230, v218, v124
	v_bfi_b32 v219, v231, v219, v125
	v_bfi_b32 v220, v232, v220, v126
	v_bfi_b32 v221, v233, v221, v127
	v_sub_f32_e32 v124, v218, v226
	v_sub_f32_e32 v125, v219, v227
	v_sub_f32_e32 v126, v220, v228
	v_sub_f32_e32 v127, v221, v229
	v_cvt_pk_f16_f32 v234, v120, v121
	v_cvt_pk_f16_f32 v235, v122, v123
	v_cvt_pk_f16_f32 v236, v124, v125
	v_cvt_pk_f16_f32 v237, v126, v127
	global_store_dwordx4 v169, v[234:237], s[26:27]
	v_mul_f32_e64 v226, |v56|, s83
	v_mul_f32_e64 v227, |v57|, s83
	v_mul_f32_e64 v228, |v58|, s83
	v_mul_f32_e64 v229, |v59|, s83
	v_exp_f32_e32 v214, v226
	v_exp_f32_e32 v215, v227
	v_exp_f32_e32 v216, v228
	v_exp_f32_e32 v217, v229
	v_cmp_le_f32_e64 s[24:25], 0, v56
	v_cmp_le_f32_e64 s[28:29], 0, v57
	v_cmp_le_f32_e64 s[30:31], 0, v58
	v_cmp_le_f32_e64 s[98:99], 0, v59
	v_fma_f32 v218, v214, v136, 1.0
	v_fma_f32 v219, v215, v137, 1.0
	v_fma_f32 v220, v216, v138, 1.0
	v_fma_f32 v221, v217, v139, 1.0
	v_add_f32_e32 v222, v214, v136
	v_add_f32_e32 v223, v215, v137
	v_add_f32_e32 v224, v216, v138
	v_add_f32_e32 v225, v217, v139
	v_cndmask_b32_e64 v218, v222, v218, s[24:25]
	v_cndmask_b32_e64 v219, v223, v219, s[28:29]
	v_cndmask_b32_e64 v220, v224, v220, s[30:31]
	v_cndmask_b32_e64 v221, v225, v221, s[98:99]
	v_cndmask_b32_e64 v230, v188, -1, s[24:25]
	v_cndmask_b32_e64 v231, v189, -1, s[28:29]
	v_cndmask_b32_e64 v232, v190, -1, s[30:31]
	v_cndmask_b32_e64 v233, v191, -1, s[98:99]
	v_cmp_gt_f32_e64 s[24:25], s35, v218
	v_cmp_gt_f32_e64 s[28:29], s35, v219
	v_cmp_gt_f32_e64 s[30:31], s35, v220
	v_cmp_gt_f32_e64 s[98:99], s35, v221
	v_add_f32_e32 v222, 1.0, v214
	v_add_f32_e32 v223, 1.0, v215
	v_add_f32_e32 v224, 1.0, v216
	v_add_f32_e32 v225, 1.0, v217
	v_cndmask_b32_e64 v226, 0, 32, s[24:25]
	v_cndmask_b32_e64 v227, 0, 32, s[28:29]
; #define PG8_GAS __attribute__((address_space(1)))
; __device__ __forceinline__ float gate_logf(float fp, float lb) {
;     const float e = __expf(-fabsf(fp)), l1pe = __logf(1.f + e);
;     return (fp >= 0.f ? __logf(1.f + lb * e) : (lb > 0.f ? __logf(lb + e) : fp)) - l1pe;
; }
;     __device__ __forceinline__ void operator()(const f32x4 (&acc)[2][2][4][2], const Unit& u, int wr, int wc, int fr, int fq) const {
;     ...
;                         if (seg == 4) {
;                             const f32x4 l0 = *(const PG8_GAS f32x4*)(lbl + wcol), l1 = *(const PG8_GAS f32x4*)(lbl + wcol + 4);
; #pragma unroll
;                             for (int j = 0; j < 4; ++j) { v0[j] = gate_logf(v0[j], l0[j]); v1[j] = gate_logf(v1[j], l1[j]); }
;                         }
;                         u32x4 w;
;                         if (seg == 4) { w.x = cvt_pk_f16(v0[0], v0[1]); w.y = cvt_pk_f16(v0[2], v0[3]); w.z = cvt_pk_f16(v1[0], v1[1]); w.w = cvt_pk_f16(v1[2], v1[3]); }
	v_cndmask_b32_e64 v228, 0, 32, s[30:31]
	v_cndmask_b32_e64 v229, 0, 32, s[98:99]
	v_cndmask_b32_e64 v238, 0, v213, s[24:25]
	v_cndmask_b32_e64 v239, 0, v213, s[28:29]
	v_cndmask_b32_e64 v240, 0, v213, s[30:31]
	v_cndmask_b32_e64 v241, 0, v213, s[98:99]
	v_ldexp_f32 v218, v218, v226
	v_ldexp_f32 v219, v219, v227
	v_ldexp_f32 v220, v220, v228
	v_ldexp_f32 v221, v221, v229
	v_log_f32_e32 v218, v218
	v_log_f32_e32 v219, v219
	v_log_f32_e32 v220, v220
	v_log_f32_e32 v221, v221
	v_log_f32_e32 v222, v222
	v_log_f32_e32 v223, v223
	v_log_f32_e32 v224, v224
	v_log_f32_e32 v225, v225
	v_mul_f32_e32 v226, 0x3f317217, v218
	v_mul_f32_e32 v227, 0x3f317217, v219
	v_mul_f32_e32 v228, 0x3f317217, v220
	v_mul_f32_e32 v229, 0x3f317217, v221
	v_fma_f32 v226, v218, s70, -v226
	v_fma_f32 v227, v219, s70, -v227
	v_fma_f32 v228, v220, s70, -v228
	v_fma_f32 v229, v221, s70, -v229
	v_fmac_f32_e32 v226, 0x3377d1cf, v218
	v_fmac_f32_e32 v227, 0x3377d1cf, v219
	v_fmac_f32_e32 v228, 0x3377d1cf, v220
	v_fmac_f32_e32 v229, 0x3377d1cf, v221
	v_fmac_f32_e32 v226, 0x3f317217, v218
	v_fmac_f32_e32 v227, 0x3f317217, v219
	v_fmac_f32_e32 v228, 0x3f317217, v220
	v_fmac_f32_e32 v229, 0x3f317217, v221
	v_cmp_lt_f32_e64 s[24:25], |v218|, s71
	v_cmp_lt_f32_e64 s[28:29], |v219|, s71
	v_cmp_lt_f32_e64 s[30:31], |v220|, s71
	v_cmp_lt_f32_e64 s[98:99], |v221|, s71
	v_cndmask_b32_e64 v218, v218, v226, s[24:25]
	v_cndmask_b32_e64 v219, v219, v227, s[28:29]
	v_cndmask_b32_e64 v220, v220, v228, s[30:31]
	v_cndmask_b32_e64 v221, v221, v229, s[98:99]
	v_sub_f32_e32 v218, v218, v238
	v_sub_f32_e32 v219, v219, v239
	v_sub_f32_e32 v220, v220, v240
	v_sub_f32_e32 v221, v221, v241
	v_mul_f32_e32 v226, 0x3f317217, v222
	v_mul_f32_e32 v227, 0x3f317217, v223
	v_mul_f32_e32 v228, 0x3f317217, v224
	v_mul_f32_e32 v229, 0x3f317217, v225
	v_fma_f32 v226, v222, s70, -v226
	v_fma_f32 v227, v223, s70, -v227
	v_fma_f32 v228, v224, s70, -v228
	v_fma_f32 v229, v225, s70, -v229
	v_fmac_f32_e32 v226, 0x3377d1cf, v222
	v_fmac_f32_e32 v227, 0x3377d1cf, v223
	v_fmac_f32_e32 v228, 0x3377d1cf, v224
	v_fmac_f32_e32 v229, 0x3377d1cf, v225
	v_fmac_f32_e32 v226, 0x3f317217, v222
	v_fmac_f32_e32 v227, 0x3f317217, v223
	v_fmac_f32_e32 v228, 0x3f317217, v224
	v_fmac_f32_e32 v229, 0x3f317217, v225
	v_bfi_b32 v218, v230, v218, v56
	v_bfi_b32 v219, v231, v219, v57
	v_bfi_b32 v220, v232, v220, v58
	v_bfi_b32 v221, v233, v221, v59
	v_sub_f32_e32 v56, v218, v226
	v_sub_f32_e32 v57, v219, v227
	v_sub_f32_e32 v58, v220, v228
	v_sub_f32_e32 v59, v221, v229
	v_mul_f32_e64 v226, |v60|, s83
	v_mul_f32_e64 v227, |v61|, s83
	v_mul_f32_e64 v228, |v62|, s83
	v_mul_f32_e64 v229, |v63|, s83
	v_exp_f32_e32 v214, v226
	v_exp_f32_e32 v215, v227
	v_exp_f32_e32 v216, v228
	v_exp_f32_e32 v217, v229
	v_cmp_le_f32_e64 s[24:25], 0, v60
	v_cmp_le_f32_e64 s[28:29], 0, v61
	v_cmp_le_f32_e64 s[30:31], 0, v62
	v_cmp_le_f32_e64 s[98:99], 0, v63
	v_fma_f32 v218, v214, v140, 1.0
	v_fma_f32 v219, v215, v141, 1.0
	v_fma_f32 v220, v216, v142, 1.0
	v_fma_f32 v221, v217, v143, 1.0
	v_add_f32_e32 v222, v214, v140
	v_add_f32_e32 v223, v215, v141
	v_add_f32_e32 v224, v216, v142
	v_add_f32_e32 v225, v217, v143
	v_cndmask_b32_e64 v218, v222, v218, s[24:25]
	v_cndmask_b32_e64 v219, v223, v219, s[28:29]
	v_cndmask_b32_e64 v220, v224, v220, s[30:31]
	v_cndmask_b32_e64 v221, v225, v221, s[98:99]
	v_cndmask_b32_e64 v230, v192, -1, s[24:25]
	v_cndmask_b32_e64 v231, v193, -1, s[28:29]
	v_cndmask_b32_e64 v232, v194, -1, s[30:31]
	v_cndmask_b32_e64 v233, v195, -1, s[98:99]
	v_cmp_gt_f32_e64 s[24:25], s35, v218
	v_cmp_gt_f32_e64 s[28:29], s35, v219
	v_cmp_gt_f32_e64 s[30:31], s35, v220
	v_cmp_gt_f32_e64 s[98:99], s35, v221
	v_add_f32_e32 v222, 1.0, v214
	v_add_f32_e32 v223, 1.0, v215
	v_add_f32_e32 v224, 1.0, v216
	v_add_f32_e32 v225, 1.0, v217
	v_cndmask_b32_e64 v226, 0, 32, s[24:25]
	v_cndmask_b32_e64 v227, 0, 32, s[28:29]
	v_cndmask_b32_e64 v228, 0, 32, s[30:31]
	v_cndmask_b32_e64 v229, 0, 32, s[98:99]
	v_cndmask_b32_e64 v238, 0, v213, s[24:25]
	v_cndmask_b32_e64 v239, 0, v213, s[28:29]
	v_cndmask_b32_e64 v240, 0, v213, s[30:31]
	v_cndmask_b32_e64 v241, 0, v213, s[98:99]
	v_ldexp_f32 v218, v218, v226
	v_ldexp_f32 v219, v219, v227
	v_ldexp_f32 v220, v220, v228
	v_ldexp_f32 v221, v221, v229
	v_log_f32_e32 v218, v218
	v_log_f32_e32 v219, v219
	v_log_f32_e32 v220, v220
	v_log_f32_e32 v221, v221
	v_log_f32_e32 v222, v222
	v_log_f32_e32 v223, v223
	v_log_f32_e32 v224, v224
	v_log_f32_e32 v225, v225
	v_mul_f32_e32 v226, 0x3f317217, v218
	v_mul_f32_e32 v227, 0x3f317217, v219
	v_mul_f32_e32 v228, 0x3f317217, v220
	v_mul_f32_e32 v229, 0x3f317217, v221
	v_fma_f32 v226, v218, s70, -v226
	v_fma_f32 v227, v219, s70, -v227
	v_fma_f32 v228, v220, s70, -v228
	v_fma_f32 v229, v221, s70, -v229
	v_fmac_f32_e32 v226, 0x3377d1cf, v218
	v_fmac_f32_e32 v227, 0x3377d1cf, v219
	v_fmac_f32_e32 v228, 0x3377d1cf, v220
	v_fmac_f32_e32 v229, 0x3377d1cf, v221
	v_fmac_f32_e32 v226, 0x3f317217, v218
	v_fmac_f32_e32 v227, 0x3f317217, v219
	v_fmac_f32_e32 v228, 0x3f317217, v220
	v_fmac_f32_e32 v229, 0x3f317217, v221
	v_cmp_lt_f32_e64 s[24:25], |v218|, s71
	v_cmp_lt_f32_e64 s[28:29], |v219|, s71
	v_cmp_lt_f32_e64 s[30:31], |v220|, s71
	v_cmp_lt_f32_e64 s[98:99], |v221|, s71
	v_cndmask_b32_e64 v218, v218, v226, s[24:25]
	v_cndmask_b32_e64 v219, v219, v227, s[28:29]
	v_cndmask_b32_e64 v220, v220, v228, s[30:31]
	v_cndmask_b32_e64 v221, v221, v229, s[98:99]
	v_sub_f32_e32 v218, v218, v238
	v_sub_f32_e32 v219, v219, v239
	v_sub_f32_e32 v220, v220, v240
	v_sub_f32_e32 v221, v221, v241
	v_mul_f32_e32 v226, 0x3f317217, v222
	v_mul_f32_e32 v227, 0x3f317217, v223
	v_mul_f32_e32 v228, 0x3f317217, v224
; __device__ __forceinline__ unsigned cvt_pk_bf16(float lo, float hi) { const f32x2c v = {lo, hi}; const bf16x2c b = __builtin_convertvector(v, bf16x2c); return __builtin_bit_cast(unsigned, b); }
; #define PG8_GAS __attribute__((address_space(1)))
; __device__ __forceinline__ float gate_logf(float fp, float lb) {
;     const float e = __expf(-fabsf(fp)), l1pe = __logf(1.f + e);
;     return (fp >= 0.f ? __logf(1.f + lb * e) : (lb > 0.f ? __logf(lb + e) : fp)) - l1pe;
;     __device__ __forceinline__ void operator()(const f32x4 (&acc)[2][2][4][2], const Unit& u, int wr, int wc, int fr, int fq) const {
;     ...
;                         if (seg == 4) {
;                             const f32x4 l0 = *(const PG8_GAS f32x4*)(lbl + wcol), l1 = *(const PG8_GAS f32x4*)(lbl + wcol + 4);
; #pragma unroll
;                             for (int j = 0; j < 4; ++j) { v0[j] = gate_logf(v0[j], l0[j]); v1[j] = gate_logf(v1[j], l1[j]); }
;                         }
;                         u32x4 w;
;                         if (seg == 4) { w.x = cvt_pk_f16(v0[0], v0[1]); w.y = cvt_pk_f16(v0[2], v0[3]); w.z = cvt_pk_f16(v1[0], v1[1]); w.w = cvt_pk_f16(v1[2], v1[3]); }
;                         else { w.x = cvt_pk_bf16(v0[0], v0[1]); w.y = cvt_pk_bf16(v0[2], v0[3]); w.z = cvt_pk_bf16(v1[0], v1[1]); w.w = cvt_pk_bf16(v1[2], v1[3]); }
;                         *(PG8_GAS u32x4*)(segp + (size_t)r * 512 + wcol) = w;
	v_mul_f32_e32 v229, 0x3f317217, v225
	v_fma_f32 v226, v222, s70, -v226
	v_fma_f32 v227, v223, s70, -v227
	v_fma_f32 v228, v224, s70, -v228
	v_fma_f32 v229, v225, s70, -v229
	v_fmac_f32_e32 v226, 0x3377d1cf, v222
	v_fmac_f32_e32 v227, 0x3377d1cf, v223
	v_fmac_f32_e32 v228, 0x3377d1cf, v224
	v_fmac_f32_e32 v229, 0x3377d1cf, v225
	v_fmac_f32_e32 v226, 0x3f317217, v222
	v_fmac_f32_e32 v227, 0x3f317217, v223
	v_fmac_f32_e32 v228, 0x3f317217, v224
	v_fmac_f32_e32 v229, 0x3f317217, v225
	v_bfi_b32 v218, v230, v218, v60
	v_bfi_b32 v219, v231, v219, v61
	v_bfi_b32 v220, v232, v220, v62
	v_bfi_b32 v221, v233, v221, v63
	v_sub_f32_e32 v60, v218, v226
	v_sub_f32_e32 v61, v219, v227
	v_sub_f32_e32 v62, v220, v228
	v_sub_f32_e32 v63, v221, v229
	v_cvt_pk_f16_f32 v234, v56, v57
	v_cvt_pk_f16_f32 v235, v58, v59
	v_cvt_pk_f16_f32 v236, v60, v61
	v_cvt_pk_f16_f32 v237, v62, v63
	global_store_dwordx4 v169, v[234:237], s[26:27] offset:256
	s_add_u32 s26, s26, 0x4000
	s_addc_u32 s27, s27, 0
	v_mul_f32_e64 v226, |v112|, s83
	v_mul_f32_e64 v227, |v113|, s83
	v_mul_f32_e64 v228, |v114|, s83
	v_mul_f32_e64 v229, |v115|, s83
	v_exp_f32_e32 v214, v226
	v_exp_f32_e32 v215, v227
	v_exp_f32_e32 v216, v228
	v_exp_f32_e32 v217, v229
	v_cmp_le_f32_e64 s[24:25], 0, v112
	v_cmp_le_f32_e64 s[28:29], 0, v113
	v_cmp_le_f32_e64 s[30:31], 0, v114
	v_cmp_le_f32_e64 s[98:99], 0, v115
	v_fma_f32 v218, v214, v128, 1.0
	v_fma_f32 v219, v215, v129, 1.0
	v_fma_f32 v220, v216, v130, 1.0
	v_fma_f32 v221, v217, v131, 1.0
	v_add_f32_e32 v222, v214, v128
	v_add_f32_e32 v223, v215, v129
	v_add_f32_e32 v224, v216, v130
	v_add_f32_e32 v225, v217, v131
	v_cndmask_b32_e64 v218, v222, v218, s[24:25]
	v_cndmask_b32_e64 v219, v223, v219, s[28:29]
	v_cndmask_b32_e64 v220, v224, v220, s[30:31]
	v_cndmask_b32_e64 v221, v225, v221, s[98:99]
	v_cndmask_b32_e64 v230, v180, -1, s[24:25]
	v_cndmask_b32_e64 v231, v181, -1, s[28:29]
	v_cndmask_b32_e64 v232, v182, -1, s[30:31]
	v_cndmask_b32_e64 v233, v183, -1, s[98:99]
	v_cmp_gt_f32_e64 s[24:25], s35, v218
	v_cmp_gt_f32_e64 s[28:29], s35, v219
	v_cmp_gt_f32_e64 s[30:31], s35, v220
	v_cmp_gt_f32_e64 s[98:99], s35, v221
	v_add_f32_e32 v222, 1.0, v214
	v_add_f32_e32 v223, 1.0, v215
	v_add_f32_e32 v224, 1.0, v216
	v_add_f32_e32 v225, 1.0, v217
	v_cndmask_b32_e64 v226, 0, 32, s[24:25]
	v_cndmask_b32_e64 v227, 0, 32, s[28:29]
	v_cndmask_b32_e64 v228, 0, 32, s[30:31]
	v_cndmask_b32_e64 v229, 0, 32, s[98:99]
	v_cndmask_b32_e64 v238, 0, v213, s[24:25]
	v_cndmask_b32_e64 v239, 0, v213, s[28:29]
	v_cndmask_b32_e64 v240, 0, v213, s[30:31]
	v_cndmask_b32_e64 v241, 0, v213, s[98:99]
	v_ldexp_f32 v218, v218, v226
	v_ldexp_f32 v219, v219, v227
	v_ldexp_f32 v220, v220, v228
	v_ldexp_f32 v221, v221, v229
	v_log_f32_e32 v218, v218
	v_log_f32_e32 v219, v219
	v_log_f32_e32 v220, v220
	v_log_f32_e32 v221, v221
	v_log_f32_e32 v222, v222
	v_log_f32_e32 v223, v223
	v_log_f32_e32 v224, v224
	v_log_f32_e32 v225, v225
	v_mul_f32_e32 v226, 0x3f317217, v218
	v_mul_f32_e32 v227, 0x3f317217, v219
	v_mul_f32_e32 v228, 0x3f317217, v220
	v_mul_f32_e32 v229, 0x3f317217, v221
	v_fma_f32 v226, v218, s70, -v226
	v_fma_f32 v227, v219, s70, -v227
	v_fma_f32 v228, v220, s70, -v228
	v_fma_f32 v229, v221, s70, -v229
	v_fmac_f32_e32 v226, 0x3377d1cf, v218
	v_fmac_f32_e32 v227, 0x3377d1cf, v219
	v_fmac_f32_e32 v228, 0x3377d1cf, v220
	v_fmac_f32_e32 v229, 0x3377d1cf, v221
	v_fmac_f32_e32 v226, 0x3f317217, v218
	v_fmac_f32_e32 v227, 0x3f317217, v219
	v_fmac_f32_e32 v228, 0x3f317217, v220
	v_fmac_f32_e32 v229, 0x3f317217, v221
	v_cmp_lt_f32_e64 s[24:25], |v218|, s71
	v_cmp_lt_f32_e64 s[28:29], |v219|, s71
	v_cmp_lt_f32_e64 s[30:31], |v220|, s71
	v_cmp_lt_f32_e64 s[98:99], |v221|, s71
	v_cndmask_b32_e64 v218, v218, v226, s[24:25]
	v_cndmask_b32_e64 v219, v219, v227, s[28:29]
	v_cndmask_b32_e64 v220, v220, v228, s[30:31]
	v_cndmask_b32_e64 v221, v221, v229, s[98:99]
	v_sub_f32_e32 v218, v218, v238
	v_sub_f32_e32 v219, v219, v239
	v_sub_f32_e32 v220, v220, v240
	v_sub_f32_e32 v221, v221, v241
	v_mul_f32_e32 v226, 0x3f317217, v222
	v_mul_f32_e32 v227, 0x3f317217, v223
	v_mul_f32_e32 v228, 0x3f317217, v224
	v_mul_f32_e32 v229, 0x3f317217, v225
	v_fma_f32 v226, v222, s70, -v226
	v_fma_f32 v227, v223, s70, -v227
	v_fma_f32 v228, v224, s70, -v228
	v_fma_f32 v229, v225, s70, -v229
	v_fmac_f32_e32 v226, 0x3377d1cf, v222
	v_fmac_f32_e32 v227, 0x3377d1cf, v223
	v_fmac_f32_e32 v228, 0x3377d1cf, v224
	v_fmac_f32_e32 v229, 0x3377d1cf, v225
	v_fmac_f32_e32 v226, 0x3f317217, v222
	v_fmac_f32_e32 v227, 0x3f317217, v223
	v_fmac_f32_e32 v228, 0x3f317217, v224
	v_fmac_f32_e32 v229, 0x3f317217, v225
	v_bfi_b32 v218, v230, v218, v112
	v_bfi_b32 v219, v231, v219, v113
	v_bfi_b32 v220, v232, v220, v114
	v_bfi_b32 v221, v233, v221, v115
	v_sub_f32_e32 v112, v218, v226
	v_sub_f32_e32 v113, v219, v227
	v_sub_f32_e32 v114, v220, v228
	v_sub_f32_e32 v115, v221, v229
	v_mul_f32_e64 v226, |v116|, s83
	v_mul_f32_e64 v227, |v117|, s83
	v_mul_f32_e64 v228, |v118|, s83
	v_mul_f32_e64 v229, |v119|, s83
	v_exp_f32_e32 v214, v226
	v_exp_f32_e32 v215, v227
	v_exp_f32_e32 v216, v228
	v_exp_f32_e32 v217, v229
	v_cmp_le_f32_e64 s[24:25], 0, v116
	v_cmp_le_f32_e64 s[28:29], 0, v117
	v_cmp_le_f32_e64 s[30:31], 0, v118
	v_cmp_le_f32_e64 s[98:99], 0, v119
	v_fma_f32 v218, v214, v132, 1.0
	v_fma_f32 v219, v215, v133, 1.0
	v_fma_f32 v220, v216, v134, 1.0
	v_fma_f32 v221, v217, v135, 1.0
	v_add_f32_e32 v222, v214, v132
	v_add_f32_e32 v223, v215, v133
	v_add_f32_e32 v224, v216, v134
	v_add_f32_e32 v225, v217, v135
	v_cndmask_b32_e64 v218, v222, v218, s[24:25]
	v_cndmask_b32_e64 v219, v223, v219, s[28:29]
	v_cndmask_b32_e64 v220, v224, v220, s[30:31]
; __device__ __forceinline__ unsigned cvt_pk_bf16(float lo, float hi) { const f32x2c v = {lo, hi}; const bf16x2c b = __builtin_convertvector(v, bf16x2c); return __builtin_bit_cast(unsigned, b); }
; #define PG8_GAS __attribute__((address_space(1)))
; __device__ __forceinline__ float gate_logf(float fp, float lb) {
;     const float e = __expf(-fabsf(fp)), l1pe = __logf(1.f + e);
;     return (fp >= 0.f ? __logf(1.f + lb * e) : (lb > 0.f ? __logf(lb + e) : fp)) - l1pe;
;     __device__ __forceinline__ void operator()(const f32x4 (&acc)[2][2][4][2], const Unit& u, int wr, int wc, int fr, int fq) const {
;     ...
;                         if (seg == 4) {
;                             const f32x4 l0 = *(const PG8_GAS f32x4*)(lbl + wcol), l1 = *(const PG8_GAS f32x4*)(lbl + wcol + 4);
; #pragma unroll
;                             for (int j = 0; j < 4; ++j) { v0[j] = gate_logf(v0[j], l0[j]); v1[j] = gate_logf(v1[j], l1[j]); }
;                         }
;                         u32x4 w;
;                         if (seg == 4) { w.x = cvt_pk_f16(v0[0], v0[1]); w.y = cvt_pk_f16(v0[2], v0[3]); w.z = cvt_pk_f16(v1[0], v1[1]); w.w = cvt_pk_f16(v1[2], v1[3]); }
;                         else { w.x = cvt_pk_bf16(v0[0], v0[1]); w.y = cvt_pk_bf16(v0[2], v0[3]); w.z = cvt_pk_bf16(v1[0], v1[1]); w.w = cvt_pk_bf16(v1[2], v1[3]); }
;                         *(PG8_GAS u32x4*)(segp + (size_t)r * 512 + wcol) = w;
	v_cndmask_b32_e64 v221, v225, v221, s[98:99]
	v_cndmask_b32_e64 v230, v184, -1, s[24:25]
	v_cndmask_b32_e64 v231, v185, -1, s[28:29]
	v_cndmask_b32_e64 v232, v186, -1, s[30:31]
	v_cndmask_b32_e64 v233, v187, -1, s[98:99]
	v_cmp_gt_f32_e64 s[24:25], s35, v218
	v_cmp_gt_f32_e64 s[28:29], s35, v219
	v_cmp_gt_f32_e64 s[30:31], s35, v220
	v_cmp_gt_f32_e64 s[98:99], s35, v221
	v_add_f32_e32 v222, 1.0, v214
	v_add_f32_e32 v223, 1.0, v215
	v_add_f32_e32 v224, 1.0, v216
	v_add_f32_e32 v225, 1.0, v217
	v_cndmask_b32_e64 v226, 0, 32, s[24:25]
	v_cndmask_b32_e64 v227, 0, 32, s[28:29]
	v_cndmask_b32_e64 v228, 0, 32, s[30:31]
	v_cndmask_b32_e64 v229, 0, 32, s[98:99]
	v_cndmask_b32_e64 v238, 0, v213, s[24:25]
	v_cndmask_b32_e64 v239, 0, v213, s[28:29]
	v_cndmask_b32_e64 v240, 0, v213, s[30:31]
	v_cndmask_b32_e64 v241, 0, v213, s[98:99]
	v_ldexp_f32 v218, v218, v226
	v_ldexp_f32 v219, v219, v227
	v_ldexp_f32 v220, v220, v228
	v_ldexp_f32 v221, v221, v229
	v_log_f32_e32 v218, v218
	v_log_f32_e32 v219, v219
	v_log_f32_e32 v220, v220
	v_log_f32_e32 v221, v221
	v_log_f32_e32 v222, v222
	v_log_f32_e32 v223, v223
	v_log_f32_e32 v224, v224
	v_log_f32_e32 v225, v225
	v_mul_f32_e32 v226, 0x3f317217, v218
	v_mul_f32_e32 v227, 0x3f317217, v219
	v_mul_f32_e32 v228, 0x3f317217, v220
	v_mul_f32_e32 v229, 0x3f317217, v221
	v_fma_f32 v226, v218, s70, -v226
	v_fma_f32 v227, v219, s70, -v227
	v_fma_f32 v228, v220, s70, -v228
	v_fma_f32 v229, v221, s70, -v229
	v_fmac_f32_e32 v226, 0x3377d1cf, v218
	v_fmac_f32_e32 v227, 0x3377d1cf, v219
	v_fmac_f32_e32 v228, 0x3377d1cf, v220
	v_fmac_f32_e32 v229, 0x3377d1cf, v221
	v_fmac_f32_e32 v226, 0x3f317217, v218
	v_fmac_f32_e32 v227, 0x3f317217, v219
	v_fmac_f32_e32 v228, 0x3f317217, v220
	v_fmac_f32_e32 v229, 0x3f317217, v221
	v_cmp_lt_f32_e64 s[24:25], |v218|, s71
	v_cmp_lt_f32_e64 s[28:29], |v219|, s71
	v_cmp_lt_f32_e64 s[30:31], |v220|, s71
	v_cmp_lt_f32_e64 s[98:99], |v221|, s71
	v_cndmask_b32_e64 v218, v218, v226, s[24:25]
	v_cndmask_b32_e64 v219, v219, v227, s[28:29]
	v_cndmask_b32_e64 v220, v220, v228, s[30:31]
	v_cndmask_b32_e64 v221, v221, v229, s[98:99]
	v_sub_f32_e32 v218, v218, v238
	v_sub_f32_e32 v219, v219, v239
	v_sub_f32_e32 v220, v220, v240
	v_sub_f32_e32 v221, v221, v241
	v_mul_f32_e32 v226, 0x3f317217, v222
	v_mul_f32_e32 v227, 0x3f317217, v223
	v_mul_f32_e32 v228, 0x3f317217, v224
	v_mul_f32_e32 v229, 0x3f317217, v225
	v_fma_f32 v226, v222, s70, -v226
	v_fma_f32 v227, v223, s70, -v227
	v_fma_f32 v228, v224, s70, -v228
	v_fma_f32 v229, v225, s70, -v229
	v_fmac_f32_e32 v226, 0x3377d1cf, v222
	v_fmac_f32_e32 v227, 0x3377d1cf, v223
	v_fmac_f32_e32 v228, 0x3377d1cf, v224
	v_fmac_f32_e32 v229, 0x3377d1cf, v225
	v_fmac_f32_e32 v226, 0x3f317217, v222
	v_fmac_f32_e32 v227, 0x3f317217, v223
	v_fmac_f32_e32 v228, 0x3f317217, v224
	v_fmac_f32_e32 v229, 0x3f317217, v225
	v_bfi_b32 v218, v230, v218, v116
	v_bfi_b32 v219, v231, v219, v117
	v_bfi_b32 v220, v232, v220, v118
	v_bfi_b32 v221, v233, v221, v119
	v_sub_f32_e32 v116, v218, v226
	v_sub_f32_e32 v117, v219, v227
	v_sub_f32_e32 v118, v220, v228
	v_sub_f32_e32 v119, v221, v229
	v_cvt_pk_f16_f32 v234, v112, v113
	v_cvt_pk_f16_f32 v235, v114, v115
	v_cvt_pk_f16_f32 v236, v116, v117
	v_cvt_pk_f16_f32 v237, v118, v119
	global_store_dwordx4 v169, v[234:237], s[26:27]
	v_mul_f32_e64 v226, |v48|, s83
	v_mul_f32_e64 v227, |v49|, s83
	v_mul_f32_e64 v228, |v50|, s83
	v_mul_f32_e64 v229, |v51|, s83
	v_exp_f32_e32 v214, v226
	v_exp_f32_e32 v215, v227
	v_exp_f32_e32 v216, v228
	v_exp_f32_e32 v217, v229
	v_cmp_le_f32_e64 s[24:25], 0, v48
	v_cmp_le_f32_e64 s[28:29], 0, v49
	v_cmp_le_f32_e64 s[30:31], 0, v50
	v_cmp_le_f32_e64 s[98:99], 0, v51
	v_fma_f32 v218, v214, v136, 1.0
	v_fma_f32 v219, v215, v137, 1.0
	v_fma_f32 v220, v216, v138, 1.0
	v_fma_f32 v221, v217, v139, 1.0
	v_add_f32_e32 v222, v214, v136
	v_add_f32_e32 v223, v215, v137
	v_add_f32_e32 v224, v216, v138
	v_add_f32_e32 v225, v217, v139
	v_cndmask_b32_e64 v218, v222, v218, s[24:25]
	v_cndmask_b32_e64 v219, v223, v219, s[28:29]
	v_cndmask_b32_e64 v220, v224, v220, s[30:31]
	v_cndmask_b32_e64 v221, v225, v221, s[98:99]
	v_cndmask_b32_e64 v230, v188, -1, s[24:25]
	v_cndmask_b32_e64 v231, v189, -1, s[28:29]
	v_cndmask_b32_e64 v232, v190, -1, s[30:31]
	v_cndmask_b32_e64 v233, v191, -1, s[98:99]
	v_cmp_gt_f32_e64 s[24:25], s35, v218
	v_cmp_gt_f32_e64 s[28:29], s35, v219
	v_cmp_gt_f32_e64 s[30:31], s35, v220
	v_cmp_gt_f32_e64 s[98:99], s35, v221
	v_add_f32_e32 v222, 1.0, v214
	v_add_f32_e32 v223, 1.0, v215
	v_add_f32_e32 v224, 1.0, v216
	v_add_f32_e32 v225, 1.0, v217
	v_cndmask_b32_e64 v226, 0, 32, s[24:25]
	v_cndmask_b32_e64 v227, 0, 32, s[28:29]
	v_cndmask_b32_e64 v228, 0, 32, s[30:31]
	v_cndmask_b32_e64 v229, 0, 32, s[98:99]
	v_cndmask_b32_e64 v238, 0, v213, s[24:25]
	v_cndmask_b32_e64 v239, 0, v213, s[28:29]
	v_cndmask_b32_e64 v240, 0, v213, s[30:31]
	v_cndmask_b32_e64 v241, 0, v213, s[98:99]
	v_ldexp_f32 v218, v218, v226
	v_ldexp_f32 v219, v219, v227
	v_ldexp_f32 v220, v220, v228
	v_ldexp_f32 v221, v221, v229
	v_log_f32_e32 v218, v218
	v_log_f32_e32 v219, v219
	v_log_f32_e32 v220, v220
	v_log_f32_e32 v221, v221
	v_log_f32_e32 v222, v222
	v_log_f32_e32 v223, v223
	v_log_f32_e32 v224, v224
	v_log_f32_e32 v225, v225
	v_mul_f32_e32 v226, 0x3f317217, v218
	v_mul_f32_e32 v227, 0x3f317217, v219
	v_mul_f32_e32 v228, 0x3f317217, v220
	v_mul_f32_e32 v229, 0x3f317217, v221
	v_fma_f32 v226, v218, s70, -v226
	v_fma_f32 v227, v219, s70, -v227
	v_fma_f32 v228, v220, s70, -v228
	v_fma_f32 v229, v221, s70, -v229
	v_fmac_f32_e32 v226, 0x3377d1cf, v218
	v_fmac_f32_e32 v227, 0x3377d1cf, v219
	v_fmac_f32_e32 v228, 0x3377d1cf, v220
; __device__ __forceinline__ unsigned cvt_pk_bf16(float lo, float hi) { const f32x2c v = {lo, hi}; const bf16x2c b = __builtin_convertvector(v, bf16x2c); return __builtin_bit_cast(unsigned, b); }
; #define PG8_GAS __attribute__((address_space(1)))
; __device__ __forceinline__ float gate_logf(float fp, float lb) {
;     const float e = __expf(-fabsf(fp)), l1pe = __logf(1.f + e);
;     return (fp >= 0.f ? __logf(1.f + lb * e) : (lb > 0.f ? __logf(lb + e) : fp)) - l1pe;
;     __device__ __forceinline__ void operator()(const f32x4 (&acc)[2][2][4][2], const Unit& u, int wr, int wc, int fr, int fq) const {
;     ...
;                         if (seg == 4) {
;                             const f32x4 l0 = *(const PG8_GAS f32x4*)(lbl + wcol), l1 = *(const PG8_GAS f32x4*)(lbl + wcol + 4);
; #pragma unroll
;                             for (int j = 0; j < 4; ++j) { v0[j] = gate_logf(v0[j], l0[j]); v1[j] = gate_logf(v1[j], l1[j]); }
;                         }
;                         u32x4 w;
;                         if (seg == 4) { w.x = cvt_pk_f16(v0[0], v0[1]); w.y = cvt_pk_f16(v0[2], v0[3]); w.z = cvt_pk_f16(v1[0], v1[1]); w.w = cvt_pk_f16(v1[2], v1[3]); }
;                         else { w.x = cvt_pk_bf16(v0[0], v0[1]); w.y = cvt_pk_bf16(v0[2], v0[3]); w.z = cvt_pk_bf16(v1[0], v1[1]); w.w = cvt_pk_bf16(v1[2], v1[3]); }
;                         *(PG8_GAS u32x4*)(segp + (size_t)r * 512 + wcol) = w;
	v_fmac_f32_e32 v229, 0x3377d1cf, v221
	v_fmac_f32_e32 v226, 0x3f317217, v218
	v_fmac_f32_e32 v227, 0x3f317217, v219
	v_fmac_f32_e32 v228, 0x3f317217, v220
	v_fmac_f32_e32 v229, 0x3f317217, v221
	v_cmp_lt_f32_e64 s[24:25], |v218|, s71
	v_cmp_lt_f32_e64 s[28:29], |v219|, s71
	v_cmp_lt_f32_e64 s[30:31], |v220|, s71
	v_cmp_lt_f32_e64 s[98:99], |v221|, s71
	v_cndmask_b32_e64 v218, v218, v226, s[24:25]
	v_cndmask_b32_e64 v219, v219, v227, s[28:29]
	v_cndmask_b32_e64 v220, v220, v228, s[30:31]
	v_cndmask_b32_e64 v221, v221, v229, s[98:99]
	v_sub_f32_e32 v218, v218, v238
	v_sub_f32_e32 v219, v219, v239
	v_sub_f32_e32 v220, v220, v240
	v_sub_f32_e32 v221, v221, v241
	v_mul_f32_e32 v226, 0x3f317217, v222
	v_mul_f32_e32 v227, 0x3f317217, v223
	v_mul_f32_e32 v228, 0x3f317217, v224
	v_mul_f32_e32 v229, 0x3f317217, v225
	v_fma_f32 v226, v222, s70, -v226
	v_fma_f32 v227, v223, s70, -v227
	v_fma_f32 v228, v224, s70, -v228
	v_fma_f32 v229, v225, s70, -v229
	v_fmac_f32_e32 v226, 0x3377d1cf, v222
	v_fmac_f32_e32 v227, 0x3377d1cf, v223
	v_fmac_f32_e32 v228, 0x3377d1cf, v224
	v_fmac_f32_e32 v229, 0x3377d1cf, v225
	v_fmac_f32_e32 v226, 0x3f317217, v222
	v_fmac_f32_e32 v227, 0x3f317217, v223
	v_fmac_f32_e32 v228, 0x3f317217, v224
	v_fmac_f32_e32 v229, 0x3f317217, v225
	v_bfi_b32 v218, v230, v218, v48
	v_bfi_b32 v219, v231, v219, v49
	v_bfi_b32 v220, v232, v220, v50
	v_bfi_b32 v221, v233, v221, v51
	v_sub_f32_e32 v48, v218, v226
	v_sub_f32_e32 v49, v219, v227
	v_sub_f32_e32 v50, v220, v228
	v_sub_f32_e32 v51, v221, v229
	v_mul_f32_e64 v226, |v52|, s83
	v_mul_f32_e64 v227, |v53|, s83
	v_mul_f32_e64 v228, |v54|, s83
	v_mul_f32_e64 v229, |v55|, s83
	v_exp_f32_e32 v214, v226
	v_exp_f32_e32 v215, v227
	v_exp_f32_e32 v216, v228
	v_exp_f32_e32 v217, v229
	v_cmp_le_f32_e64 s[24:25], 0, v52
	v_cmp_le_f32_e64 s[28:29], 0, v53
	v_cmp_le_f32_e64 s[30:31], 0, v54
	v_cmp_le_f32_e64 s[98:99], 0, v55
	v_fma_f32 v218, v214, v140, 1.0
	v_fma_f32 v219, v215, v141, 1.0
	v_fma_f32 v220, v216, v142, 1.0
	v_fma_f32 v221, v217, v143, 1.0
	v_add_f32_e32 v222, v214, v140
	v_add_f32_e32 v223, v215, v141
	v_add_f32_e32 v224, v216, v142
	v_add_f32_e32 v225, v217, v143
	v_cndmask_b32_e64 v218, v222, v218, s[24:25]
	v_cndmask_b32_e64 v219, v223, v219, s[28:29]
	v_cndmask_b32_e64 v220, v224, v220, s[30:31]
	v_cndmask_b32_e64 v221, v225, v221, s[98:99]
	v_cndmask_b32_e64 v230, v192, -1, s[24:25]
	v_cndmask_b32_e64 v231, v193, -1, s[28:29]
	v_cndmask_b32_e64 v232, v194, -1, s[30:31]
	v_cndmask_b32_e64 v233, v195, -1, s[98:99]
	v_cmp_gt_f32_e64 s[24:25], s35, v218
	v_cmp_gt_f32_e64 s[28:29], s35, v219
	v_cmp_gt_f32_e64 s[30:31], s35, v220
	v_cmp_gt_f32_e64 s[98:99], s35, v221
	v_add_f32_e32 v222, 1.0, v214
	v_add_f32_e32 v223, 1.0, v215
	v_add_f32_e32 v224, 1.0, v216
	v_add_f32_e32 v225, 1.0, v217
	v_cndmask_b32_e64 v226, 0, 32, s[24:25]
	v_cndmask_b32_e64 v227, 0, 32, s[28:29]
	v_cndmask_b32_e64 v228, 0, 32, s[30:31]
	v_cndmask_b32_e64 v229, 0, 32, s[98:99]
	v_cndmask_b32_e64 v238, 0, v213, s[24:25]
	v_cndmask_b32_e64 v239, 0, v213, s[28:29]
	v_cndmask_b32_e64 v240, 0, v213, s[30:31]
	v_cndmask_b32_e64 v241, 0, v213, s[98:99]
	v_ldexp_f32 v218, v218, v226
	v_ldexp_f32 v219, v219, v227
	v_ldexp_f32 v220, v220, v228
	v_ldexp_f32 v221, v221, v229
	v_log_f32_e32 v218, v218
	v_log_f32_e32 v219, v219
	v_log_f32_e32 v220, v220
	v_log_f32_e32 v221, v221
	v_log_f32_e32 v222, v222
	v_log_f32_e32 v223, v223
	v_log_f32_e32 v224, v224
	v_log_f32_e32 v225, v225
	v_mul_f32_e32 v226, 0x3f317217, v218
	v_mul_f32_e32 v227, 0x3f317217, v219
	v_mul_f32_e32 v228, 0x3f317217, v220
	v_mul_f32_e32 v229, 0x3f317217, v221
	v_fma_f32 v226, v218, s70, -v226
	v_fma_f32 v227, v219, s70, -v227
	v_fma_f32 v228, v220, s70, -v228
	v_fma_f32 v229, v221, s70, -v229
	v_fmac_f32_e32 v226, 0x3377d1cf, v218
	v_fmac_f32_e32 v227, 0x3377d1cf, v219
	v_fmac_f32_e32 v228, 0x3377d1cf, v220
	v_fmac_f32_e32 v229, 0x3377d1cf, v221
	v_fmac_f32_e32 v226, 0x3f317217, v218
	v_fmac_f32_e32 v227, 0x3f317217, v219
	v_fmac_f32_e32 v228, 0x3f317217, v220
	v_fmac_f32_e32 v229, 0x3f317217, v221
	v_cmp_lt_f32_e64 s[24:25], |v218|, s71
	v_cmp_lt_f32_e64 s[28:29], |v219|, s71
	v_cmp_lt_f32_e64 s[30:31], |v220|, s71
	v_cmp_lt_f32_e64 s[98:99], |v221|, s71
	v_cndmask_b32_e64 v218, v218, v226, s[24:25]
	v_cndmask_b32_e64 v219, v219, v227, s[28:29]
	v_cndmask_b32_e64 v220, v220, v228, s[30:31]
	v_cndmask_b32_e64 v221, v221, v229, s[98:99]
	v_sub_f32_e32 v218, v218, v238
	v_sub_f32_e32 v219, v219, v239
	v_sub_f32_e32 v220, v220, v240
	v_sub_f32_e32 v221, v221, v241
	v_mul_f32_e32 v226, 0x3f317217, v222
	v_mul_f32_e32 v227, 0x3f317217, v223
	v_mul_f32_e32 v228, 0x3f317217, v224
	v_mul_f32_e32 v229, 0x3f317217, v225
	v_fma_f32 v226, v222, s70, -v226
	v_fma_f32 v227, v223, s70, -v227
	v_fma_f32 v228, v224, s70, -v228
	v_fma_f32 v229, v225, s70, -v229
	v_fmac_f32_e32 v226, 0x3377d1cf, v222
	v_fmac_f32_e32 v227, 0x3377d1cf, v223
	v_fmac_f32_e32 v228, 0x3377d1cf, v224
	v_fmac_f32_e32 v229, 0x3377d1cf, v225
	v_fmac_f32_e32 v226, 0x3f317217, v222
	v_fmac_f32_e32 v227, 0x3f317217, v223
	v_fmac_f32_e32 v228, 0x3f317217, v224
	v_fmac_f32_e32 v229, 0x3f317217, v225
	v_bfi_b32 v218, v230, v218, v52
	v_bfi_b32 v219, v231, v219, v53
	v_bfi_b32 v220, v232, v220, v54
	v_bfi_b32 v221, v233, v221, v55
	v_sub_f32_e32 v52, v218, v226
	v_sub_f32_e32 v53, v219, v227
	v_sub_f32_e32 v54, v220, v228
	v_sub_f32_e32 v55, v221, v229
	v_cvt_pk_f16_f32 v234, v48, v49
	v_cvt_pk_f16_f32 v235, v50, v51
	v_cvt_pk_f16_f32 v236, v52, v53
	v_cvt_pk_f16_f32 v237, v54, v55
	global_store_dwordx4 v169, v[234:237], s[26:27] offset:256
	s_add_u32 s26, s26, 0x4000
	s_addc_u32 s27, s27, 0
; __device__ __forceinline__ unsigned cvt_pk_bf16(float lo, float hi) { const f32x2c v = {lo, hi}; const bf16x2c b = __builtin_convertvector(v, bf16x2c); return __builtin_bit_cast(unsigned, b); }
; #define PG8_GAS __attribute__((address_space(1)))
; __device__ __forceinline__ float gate_logf(float fp, float lb) {
;     const float e = __expf(-fabsf(fp)), l1pe = __logf(1.f + e);
;     return (fp >= 0.f ? __logf(1.f + lb * e) : (lb > 0.f ? __logf(lb + e) : fp)) - l1pe;
;     __device__ __forceinline__ void operator()(const f32x4 (&acc)[2][2][4][2], const Unit& u, int wr, int wc, int fr, int fq) const {
;     ...
;                         if (seg == 4) {
;                             const f32x4 l0 = *(const PG8_GAS f32x4*)(lbl + wcol), l1 = *(const PG8_GAS f32x4*)(lbl + wcol + 4);
; #pragma unroll
;                             for (int j = 0; j < 4; ++j) { v0[j] = gate_logf(v0[j], l0[j]); v1[j] = gate_logf(v1[j], l1[j]); }
;                         }
;                         u32x4 w;
;                         if (seg == 4) { w.x = cvt_pk_f16(v0[0], v0[1]); w.y = cvt_pk_f16(v0[2], v0[3]); w.z = cvt_pk_f16(v1[0], v1[1]); w.w = cvt_pk_f16(v1[2], v1[3]); }
;                         else { w.x = cvt_pk_bf16(v0[0], v0[1]); w.y = cvt_pk_bf16(v0[2], v0[3]); w.z = cvt_pk_bf16(v1[0], v1[1]); w.w = cvt_pk_bf16(v1[2], v1[3]); }
;                         *(PG8_GAS u32x4*)(segp + (size_t)r * 512 + wcol) = w;
	v_mul_f32_e64 v226, |v104|, s83
	v_mul_f32_e64 v227, |v105|, s83
	v_mul_f32_e64 v228, |v106|, s83
	v_mul_f32_e64 v229, |v107|, s83
	v_exp_f32_e32 v214, v226
	v_exp_f32_e32 v215, v227
	v_exp_f32_e32 v216, v228
	v_exp_f32_e32 v217, v229
	v_cmp_le_f32_e64 s[24:25], 0, v104
	v_cmp_le_f32_e64 s[28:29], 0, v105
	v_cmp_le_f32_e64 s[30:31], 0, v106
	v_cmp_le_f32_e64 s[98:99], 0, v107
	v_fma_f32 v218, v214, v128, 1.0
	v_fma_f32 v219, v215, v129, 1.0
	v_fma_f32 v220, v216, v130, 1.0
	v_fma_f32 v221, v217, v131, 1.0
	v_add_f32_e32 v222, v214, v128
	v_add_f32_e32 v223, v215, v129
	v_add_f32_e32 v224, v216, v130
	v_add_f32_e32 v225, v217, v131
	v_cndmask_b32_e64 v218, v222, v218, s[24:25]
	v_cndmask_b32_e64 v219, v223, v219, s[28:29]
	v_cndmask_b32_e64 v220, v224, v220, s[30:31]
	v_cndmask_b32_e64 v221, v225, v221, s[98:99]
	v_cndmask_b32_e64 v230, v180, -1, s[24:25]
	v_cndmask_b32_e64 v231, v181, -1, s[28:29]
	v_cndmask_b32_e64 v232, v182, -1, s[30:31]
	v_cndmask_b32_e64 v233, v183, -1, s[98:99]
	v_cmp_gt_f32_e64 s[24:25], s35, v218
	v_cmp_gt_f32_e64 s[28:29], s35, v219
	v_cmp_gt_f32_e64 s[30:31], s35, v220
	v_cmp_gt_f32_e64 s[98:99], s35, v221
	v_add_f32_e32 v222, 1.0, v214
	v_add_f32_e32 v223, 1.0, v215
	v_add_f32_e32 v224, 1.0, v216
	v_add_f32_e32 v225, 1.0, v217
	v_cndmask_b32_e64 v226, 0, 32, s[24:25]
	v_cndmask_b32_e64 v227, 0, 32, s[28:29]
	v_cndmask_b32_e64 v228, 0, 32, s[30:31]
	v_cndmask_b32_e64 v229, 0, 32, s[98:99]
	v_cndmask_b32_e64 v238, 0, v213, s[24:25]
	v_cndmask_b32_e64 v239, 0, v213, s[28:29]
	v_cndmask_b32_e64 v240, 0, v213, s[30:31]
	v_cndmask_b32_e64 v241, 0, v213, s[98:99]
	v_ldexp_f32 v218, v218, v226
	v_ldexp_f32 v219, v219, v227
	v_ldexp_f32 v220, v220, v228
	v_ldexp_f32 v221, v221, v229
	v_log_f32_e32 v218, v218
	v_log_f32_e32 v219, v219
	v_log_f32_e32 v220, v220
	v_log_f32_e32 v221, v221
	v_log_f32_e32 v222, v222
	v_log_f32_e32 v223, v223
	v_log_f32_e32 v224, v224
	v_log_f32_e32 v225, v225
	v_mul_f32_e32 v226, 0x3f317217, v218
	v_mul_f32_e32 v227, 0x3f317217, v219
	v_mul_f32_e32 v228, 0x3f317217, v220
	v_mul_f32_e32 v229, 0x3f317217, v221
	v_fma_f32 v226, v218, s70, -v226
	v_fma_f32 v227, v219, s70, -v227
	v_fma_f32 v228, v220, s70, -v228
	v_fma_f32 v229, v221, s70, -v229
	v_fmac_f32_e32 v226, 0x3377d1cf, v218
	v_fmac_f32_e32 v227, 0x3377d1cf, v219
	v_fmac_f32_e32 v228, 0x3377d1cf, v220
	v_fmac_f32_e32 v229, 0x3377d1cf, v221
	v_fmac_f32_e32 v226, 0x3f317217, v218
	v_fmac_f32_e32 v227, 0x3f317217, v219
	v_fmac_f32_e32 v228, 0x3f317217, v220
	v_fmac_f32_e32 v229, 0x3f317217, v221
	v_cmp_lt_f32_e64 s[24:25], |v218|, s71
	v_cmp_lt_f32_e64 s[28:29], |v219|, s71
	v_cmp_lt_f32_e64 s[30:31], |v220|, s71
	v_cmp_lt_f32_e64 s[98:99], |v221|, s71
	v_cndmask_b32_e64 v218, v218, v226, s[24:25]
	v_cndmask_b32_e64 v219, v219, v227, s[28:29]
	v_cndmask_b32_e64 v220, v220, v228, s[30:31]
	v_cndmask_b32_e64 v221, v221, v229, s[98:99]
	v_sub_f32_e32 v218, v218, v238
	v_sub_f32_e32 v219, v219, v239
	v_sub_f32_e32 v220, v220, v240
	v_sub_f32_e32 v221, v221, v241
	v_mul_f32_e32 v226, 0x3f317217, v222
	v_mul_f32_e32 v227, 0x3f317217, v223
	v_mul_f32_e32 v228, 0x3f317217, v224
	v_mul_f32_e32 v229, 0x3f317217, v225
	v_fma_f32 v226, v222, s70, -v226
	v_fma_f32 v227, v223, s70, -v227
	v_fma_f32 v228, v224, s70, -v228
	v_fma_f32 v229, v225, s70, -v229
	v_fmac_f32_e32 v226, 0x3377d1cf, v222
	v_fmac_f32_e32 v227, 0x3377d1cf, v223
	v_fmac_f32_e32 v228, 0x3377d1cf, v224
	v_fmac_f32_e32 v229, 0x3377d1cf, v225
	v_fmac_f32_e32 v226, 0x3f317217, v222
	v_fmac_f32_e32 v227, 0x3f317217, v223
	v_fmac_f32_e32 v228, 0x3f317217, v224
	v_fmac_f32_e32 v229, 0x3f317217, v225
	v_bfi_b32 v218, v230, v218, v104
	v_bfi_b32 v219, v231, v219, v105
	v_bfi_b32 v220, v232, v220, v106
	v_bfi_b32 v221, v233, v221, v107
	v_sub_f32_e32 v104, v218, v226
	v_sub_f32_e32 v105, v219, v227
	v_sub_f32_e32 v106, v220, v228
	v_sub_f32_e32 v107, v221, v229
	v_mul_f32_e64 v226, |v108|, s83
	v_mul_f32_e64 v227, |v109|, s83
	v_mul_f32_e64 v228, |v110|, s83
	v_mul_f32_e64 v229, |v111|, s83
	v_exp_f32_e32 v214, v226
	v_exp_f32_e32 v215, v227
	v_exp_f32_e32 v216, v228
	v_exp_f32_e32 v217, v229
	v_cmp_le_f32_e64 s[24:25], 0, v108
	v_cmp_le_f32_e64 s[28:29], 0, v109
	v_cmp_le_f32_e64 s[30:31], 0, v110
	v_cmp_le_f32_e64 s[98:99], 0, v111
	v_fma_f32 v218, v214, v132, 1.0
	v_fma_f32 v219, v215, v133, 1.0
	v_fma_f32 v220, v216, v134, 1.0
	v_fma_f32 v221, v217, v135, 1.0
	v_add_f32_e32 v222, v214, v132
	v_add_f32_e32 v223, v215, v133
	v_add_f32_e32 v224, v216, v134
	v_add_f32_e32 v225, v217, v135
	v_cndmask_b32_e64 v218, v222, v218, s[24:25]
	v_cndmask_b32_e64 v219, v223, v219, s[28:29]
	v_cndmask_b32_e64 v220, v224, v220, s[30:31]
	v_cndmask_b32_e64 v221, v225, v221, s[98:99]
	v_cndmask_b32_e64 v230, v184, -1, s[24:25]
	v_cndmask_b32_e64 v231, v185, -1, s[28:29]
	v_cndmask_b32_e64 v232, v186, -1, s[30:31]
	v_cndmask_b32_e64 v233, v187, -1, s[98:99]
	v_cmp_gt_f32_e64 s[24:25], s35, v218
	v_cmp_gt_f32_e64 s[28:29], s35, v219
	v_cmp_gt_f32_e64 s[30:31], s35, v220
	v_cmp_gt_f32_e64 s[98:99], s35, v221
	v_add_f32_e32 v222, 1.0, v214
	v_add_f32_e32 v223, 1.0, v215
	v_add_f32_e32 v224, 1.0, v216
	v_add_f32_e32 v225, 1.0, v217
	v_cndmask_b32_e64 v226, 0, 32, s[24:25]
	v_cndmask_b32_e64 v227, 0, 32, s[28:29]
	v_cndmask_b32_e64 v228, 0, 32, s[30:31]
	v_cndmask_b32_e64 v229, 0, 32, s[98:99]
	v_cndmask_b32_e64 v238, 0, v213, s[24:25]
	v_cndmask_b32_e64 v239, 0, v213, s[28:29]
	v_cndmask_b32_e64 v240, 0, v213, s[30:31]
	v_cndmask_b32_e64 v241, 0, v213, s[98:99]
	v_ldexp_f32 v218, v218, v226
	v_ldexp_f32 v219, v219, v227
	v_ldexp_f32 v220, v220, v228
	v_ldexp_f32 v221, v221, v229
	v_log_f32_e32 v218, v218
; __device__ __forceinline__ unsigned cvt_pk_bf16(float lo, float hi) { const f32x2c v = {lo, hi}; const bf16x2c b = __builtin_convertvector(v, bf16x2c); return __builtin_bit_cast(unsigned, b); }
; #define PG8_GAS __attribute__((address_space(1)))
; __device__ __forceinline__ float gate_logf(float fp, float lb) {
;     const float e = __expf(-fabsf(fp)), l1pe = __logf(1.f + e);
;     return (fp >= 0.f ? __logf(1.f + lb * e) : (lb > 0.f ? __logf(lb + e) : fp)) - l1pe;
;     __device__ __forceinline__ void operator()(const f32x4 (&acc)[2][2][4][2], const Unit& u, int wr, int wc, int fr, int fq) const {
;     ...
;                         if (seg == 4) {
;                             const f32x4 l0 = *(const PG8_GAS f32x4*)(lbl + wcol), l1 = *(const PG8_GAS f32x4*)(lbl + wcol + 4);
; #pragma unroll
;                             for (int j = 0; j < 4; ++j) { v0[j] = gate_logf(v0[j], l0[j]); v1[j] = gate_logf(v1[j], l1[j]); }
;                         }
;                         u32x4 w;
;                         if (seg == 4) { w.x = cvt_pk_f16(v0[0], v0[1]); w.y = cvt_pk_f16(v0[2], v0[3]); w.z = cvt_pk_f16(v1[0], v1[1]); w.w = cvt_pk_f16(v1[2], v1[3]); }
;                         else { w.x = cvt_pk_bf16(v0[0], v0[1]); w.y = cvt_pk_bf16(v0[2], v0[3]); w.z = cvt_pk_bf16(v1[0], v1[1]); w.w = cvt_pk_bf16(v1[2], v1[3]); }
;                         *(PG8_GAS u32x4*)(segp + (size_t)r * 512 + wcol) = w;
	v_log_f32_e32 v219, v219
	v_log_f32_e32 v220, v220
	v_log_f32_e32 v221, v221
	v_log_f32_e32 v222, v222
	v_log_f32_e32 v223, v223
	v_log_f32_e32 v224, v224
	v_log_f32_e32 v225, v225
	v_mul_f32_e32 v226, 0x3f317217, v218
	v_mul_f32_e32 v227, 0x3f317217, v219
	v_mul_f32_e32 v228, 0x3f317217, v220
	v_mul_f32_e32 v229, 0x3f317217, v221
	v_fma_f32 v226, v218, s70, -v226
	v_fma_f32 v227, v219, s70, -v227
	v_fma_f32 v228, v220, s70, -v228
	v_fma_f32 v229, v221, s70, -v229
	v_fmac_f32_e32 v226, 0x3377d1cf, v218
	v_fmac_f32_e32 v227, 0x3377d1cf, v219
	v_fmac_f32_e32 v228, 0x3377d1cf, v220
	v_fmac_f32_e32 v229, 0x3377d1cf, v221
	v_fmac_f32_e32 v226, 0x3f317217, v218
	v_fmac_f32_e32 v227, 0x3f317217, v219
	v_fmac_f32_e32 v228, 0x3f317217, v220
	v_fmac_f32_e32 v229, 0x3f317217, v221
	v_cmp_lt_f32_e64 s[24:25], |v218|, s71
	v_cmp_lt_f32_e64 s[28:29], |v219|, s71
	v_cmp_lt_f32_e64 s[30:31], |v220|, s71
	v_cmp_lt_f32_e64 s[98:99], |v221|, s71
	v_cndmask_b32_e64 v218, v218, v226, s[24:25]
	v_cndmask_b32_e64 v219, v219, v227, s[28:29]
	v_cndmask_b32_e64 v220, v220, v228, s[30:31]
	v_cndmask_b32_e64 v221, v221, v229, s[98:99]
	v_sub_f32_e32 v218, v218, v238
	v_sub_f32_e32 v219, v219, v239
	v_sub_f32_e32 v220, v220, v240
	v_sub_f32_e32 v221, v221, v241
	v_mul_f32_e32 v226, 0x3f317217, v222
	v_mul_f32_e32 v227, 0x3f317217, v223
	v_mul_f32_e32 v228, 0x3f317217, v224
	v_mul_f32_e32 v229, 0x3f317217, v225
	v_fma_f32 v226, v222, s70, -v226
	v_fma_f32 v227, v223, s70, -v227
	v_fma_f32 v228, v224, s70, -v228
	v_fma_f32 v229, v225, s70, -v229
	v_fmac_f32_e32 v226, 0x3377d1cf, v222
	v_fmac_f32_e32 v227, 0x3377d1cf, v223
	v_fmac_f32_e32 v228, 0x3377d1cf, v224
	v_fmac_f32_e32 v229, 0x3377d1cf, v225
	v_fmac_f32_e32 v226, 0x3f317217, v222
	v_fmac_f32_e32 v227, 0x3f317217, v223
	v_fmac_f32_e32 v228, 0x3f317217, v224
	v_fmac_f32_e32 v229, 0x3f317217, v225
	v_bfi_b32 v218, v230, v218, v108
	v_bfi_b32 v219, v231, v219, v109
	v_bfi_b32 v220, v232, v220, v110
	v_bfi_b32 v221, v233, v221, v111
	v_sub_f32_e32 v108, v218, v226
	v_sub_f32_e32 v109, v219, v227
	v_sub_f32_e32 v110, v220, v228
	v_sub_f32_e32 v111, v221, v229
	v_cvt_pk_f16_f32 v234, v104, v105
	v_cvt_pk_f16_f32 v235, v106, v107
	v_cvt_pk_f16_f32 v236, v108, v109
	v_cvt_pk_f16_f32 v237, v110, v111
	global_store_dwordx4 v169, v[234:237], s[26:27]
	v_mul_f32_e64 v226, |v40|, s83
	v_mul_f32_e64 v227, |v41|, s83
	v_mul_f32_e64 v228, |v42|, s83
	v_mul_f32_e64 v229, |v43|, s83
	v_exp_f32_e32 v214, v226
	v_exp_f32_e32 v215, v227
	v_exp_f32_e32 v216, v228
	v_exp_f32_e32 v217, v229
	v_cmp_le_f32_e64 s[24:25], 0, v40
	v_cmp_le_f32_e64 s[28:29], 0, v41
	v_cmp_le_f32_e64 s[30:31], 0, v42
	v_cmp_le_f32_e64 s[98:99], 0, v43
	v_fma_f32 v218, v214, v136, 1.0
	v_fma_f32 v219, v215, v137, 1.0
	v_fma_f32 v220, v216, v138, 1.0
	v_fma_f32 v221, v217, v139, 1.0
	v_add_f32_e32 v222, v214, v136
	v_add_f32_e32 v223, v215, v137
	v_add_f32_e32 v224, v216, v138
	v_add_f32_e32 v225, v217, v139
	v_cndmask_b32_e64 v218, v222, v218, s[24:25]
	v_cndmask_b32_e64 v219, v223, v219, s[28:29]
	v_cndmask_b32_e64 v220, v224, v220, s[30:31]
	v_cndmask_b32_e64 v221, v225, v221, s[98:99]
	v_cndmask_b32_e64 v230, v188, -1, s[24:25]
	v_cndmask_b32_e64 v231, v189, -1, s[28:29]
	v_cndmask_b32_e64 v232, v190, -1, s[30:31]
	v_cndmask_b32_e64 v233, v191, -1, s[98:99]
	v_cmp_gt_f32_e64 s[24:25], s35, v218
	v_cmp_gt_f32_e64 s[28:29], s35, v219
	v_cmp_gt_f32_e64 s[30:31], s35, v220
	v_cmp_gt_f32_e64 s[98:99], s35, v221
	v_add_f32_e32 v222, 1.0, v214
	v_add_f32_e32 v223, 1.0, v215
	v_add_f32_e32 v224, 1.0, v216
	v_add_f32_e32 v225, 1.0, v217
	v_cndmask_b32_e64 v226, 0, 32, s[24:25]
	v_cndmask_b32_e64 v227, 0, 32, s[28:29]
	v_cndmask_b32_e64 v228, 0, 32, s[30:31]
	v_cndmask_b32_e64 v229, 0, 32, s[98:99]
	v_cndmask_b32_e64 v238, 0, v213, s[24:25]
	v_cndmask_b32_e64 v239, 0, v213, s[28:29]
	v_cndmask_b32_e64 v240, 0, v213, s[30:31]
	v_cndmask_b32_e64 v241, 0, v213, s[98:99]
	v_ldexp_f32 v218, v218, v226
	v_ldexp_f32 v219, v219, v227
	v_ldexp_f32 v220, v220, v228
	v_ldexp_f32 v221, v221, v229
	v_log_f32_e32 v218, v218
	v_log_f32_e32 v219, v219
	v_log_f32_e32 v220, v220
	v_log_f32_e32 v221, v221
	v_log_f32_e32 v222, v222
	v_log_f32_e32 v223, v223
	v_log_f32_e32 v224, v224
	v_log_f32_e32 v225, v225
	v_mul_f32_e32 v226, 0x3f317217, v218
	v_mul_f32_e32 v227, 0x3f317217, v219
	v_mul_f32_e32 v228, 0x3f317217, v220
	v_mul_f32_e32 v229, 0x3f317217, v221
	v_fma_f32 v226, v218, s70, -v226
	v_fma_f32 v227, v219, s70, -v227
	v_fma_f32 v228, v220, s70, -v228
	v_fma_f32 v229, v221, s70, -v229
	v_fmac_f32_e32 v226, 0x3377d1cf, v218
	v_fmac_f32_e32 v227, 0x3377d1cf, v219
	v_fmac_f32_e32 v228, 0x3377d1cf, v220
	v_fmac_f32_e32 v229, 0x3377d1cf, v221
	v_fmac_f32_e32 v226, 0x3f317217, v218
	v_fmac_f32_e32 v227, 0x3f317217, v219
	v_fmac_f32_e32 v228, 0x3f317217, v220
	v_fmac_f32_e32 v229, 0x3f317217, v221
	v_cmp_lt_f32_e64 s[24:25], |v218|, s71
	v_cmp_lt_f32_e64 s[28:29], |v219|, s71
	v_cmp_lt_f32_e64 s[30:31], |v220|, s71
	v_cmp_lt_f32_e64 s[98:99], |v221|, s71
	v_cndmask_b32_e64 v218, v218, v226, s[24:25]
	v_cndmask_b32_e64 v219, v219, v227, s[28:29]
	v_cndmask_b32_e64 v220, v220, v228, s[30:31]
	v_cndmask_b32_e64 v221, v221, v229, s[98:99]
	v_sub_f32_e32 v218, v218, v238
	v_sub_f32_e32 v219, v219, v239
	v_sub_f32_e32 v220, v220, v240
	v_sub_f32_e32 v221, v221, v241
	v_mul_f32_e32 v226, 0x3f317217, v222
	v_mul_f32_e32 v227, 0x3f317217, v223
	v_mul_f32_e32 v228, 0x3f317217, v224
	v_mul_f32_e32 v229, 0x3f317217, v225
	v_fma_f32 v226, v222, s70, -v226
	v_fma_f32 v227, v223, s70, -v227
	v_fma_f32 v228, v224, s70, -v228
	v_fma_f32 v229, v225, s70, -v229
	v_fmac_f32_e32 v226, 0x3377d1cf, v222
; __device__ __forceinline__ unsigned cvt_pk_bf16(float lo, float hi) { const f32x2c v = {lo, hi}; const bf16x2c b = __builtin_convertvector(v, bf16x2c); return __builtin_bit_cast(unsigned, b); }
; #define PG8_GAS __attribute__((address_space(1)))
; __device__ __forceinline__ float gate_logf(float fp, float lb) {
;     const float e = __expf(-fabsf(fp)), l1pe = __logf(1.f + e);
;     return (fp >= 0.f ? __logf(1.f + lb * e) : (lb > 0.f ? __logf(lb + e) : fp)) - l1pe;
;     __device__ __forceinline__ void operator()(const f32x4 (&acc)[2][2][4][2], const Unit& u, int wr, int wc, int fr, int fq) const {
;     ...
;                         if (seg == 4) {
;                             const f32x4 l0 = *(const PG8_GAS f32x4*)(lbl + wcol), l1 = *(const PG8_GAS f32x4*)(lbl + wcol + 4);
; #pragma unroll
;                             for (int j = 0; j < 4; ++j) { v0[j] = gate_logf(v0[j], l0[j]); v1[j] = gate_logf(v1[j], l1[j]); }
;                         }
;                         u32x4 w;
;                         if (seg == 4) { w.x = cvt_pk_f16(v0[0], v0[1]); w.y = cvt_pk_f16(v0[2], v0[3]); w.z = cvt_pk_f16(v1[0], v1[1]); w.w = cvt_pk_f16(v1[2], v1[3]); }
;                         else { w.x = cvt_pk_bf16(v0[0], v0[1]); w.y = cvt_pk_bf16(v0[2], v0[3]); w.z = cvt_pk_bf16(v1[0], v1[1]); w.w = cvt_pk_bf16(v1[2], v1[3]); }
;                         *(PG8_GAS u32x4*)(segp + (size_t)r * 512 + wcol) = w;
	v_fmac_f32_e32 v227, 0x3377d1cf, v223
	v_fmac_f32_e32 v228, 0x3377d1cf, v224
	v_fmac_f32_e32 v229, 0x3377d1cf, v225
	v_fmac_f32_e32 v226, 0x3f317217, v222
	v_fmac_f32_e32 v227, 0x3f317217, v223
	v_fmac_f32_e32 v228, 0x3f317217, v224
	v_fmac_f32_e32 v229, 0x3f317217, v225
	v_bfi_b32 v218, v230, v218, v40
	v_bfi_b32 v219, v231, v219, v41
	v_bfi_b32 v220, v232, v220, v42
	v_bfi_b32 v221, v233, v221, v43
	v_sub_f32_e32 v40, v218, v226
	v_sub_f32_e32 v41, v219, v227
	v_sub_f32_e32 v42, v220, v228
	v_sub_f32_e32 v43, v221, v229
	v_mul_f32_e64 v226, |v44|, s83
	v_mul_f32_e64 v227, |v45|, s83
	v_mul_f32_e64 v228, |v46|, s83
	v_mul_f32_e64 v229, |v47|, s83
	v_exp_f32_e32 v214, v226
	v_exp_f32_e32 v215, v227
	v_exp_f32_e32 v216, v228
	v_exp_f32_e32 v217, v229
	v_cmp_le_f32_e64 s[24:25], 0, v44
	v_cmp_le_f32_e64 s[28:29], 0, v45
	v_cmp_le_f32_e64 s[30:31], 0, v46
	v_cmp_le_f32_e64 s[98:99], 0, v47
	v_fma_f32 v218, v214, v140, 1.0
	v_fma_f32 v219, v215, v141, 1.0
	v_fma_f32 v220, v216, v142, 1.0
	v_fma_f32 v221, v217, v143, 1.0
	v_add_f32_e32 v222, v214, v140
	v_add_f32_e32 v223, v215, v141
	v_add_f32_e32 v224, v216, v142
	v_add_f32_e32 v225, v217, v143
	v_cndmask_b32_e64 v218, v222, v218, s[24:25]
	v_cndmask_b32_e64 v219, v223, v219, s[28:29]
	v_cndmask_b32_e64 v220, v224, v220, s[30:31]
	v_cndmask_b32_e64 v221, v225, v221, s[98:99]
	v_cndmask_b32_e64 v230, v192, -1, s[24:25]
	v_cndmask_b32_e64 v231, v193, -1, s[28:29]
	v_cndmask_b32_e64 v232, v194, -1, s[30:31]
	v_cndmask_b32_e64 v233, v195, -1, s[98:99]
	v_cmp_gt_f32_e64 s[24:25], s35, v218
	v_cmp_gt_f32_e64 s[28:29], s35, v219
	v_cmp_gt_f32_e64 s[30:31], s35, v220
	v_cmp_gt_f32_e64 s[98:99], s35, v221
	v_add_f32_e32 v222, 1.0, v214
	v_add_f32_e32 v223, 1.0, v215
	v_add_f32_e32 v224, 1.0, v216
	v_add_f32_e32 v225, 1.0, v217
	v_cndmask_b32_e64 v226, 0, 32, s[24:25]
	v_cndmask_b32_e64 v227, 0, 32, s[28:29]
	v_cndmask_b32_e64 v228, 0, 32, s[30:31]
	v_cndmask_b32_e64 v229, 0, 32, s[98:99]
	v_cndmask_b32_e64 v238, 0, v213, s[24:25]
	v_cndmask_b32_e64 v239, 0, v213, s[28:29]
	v_cndmask_b32_e64 v240, 0, v213, s[30:31]
	v_cndmask_b32_e64 v241, 0, v213, s[98:99]
	v_ldexp_f32 v218, v218, v226
	v_ldexp_f32 v219, v219, v227
	v_ldexp_f32 v220, v220, v228
	v_ldexp_f32 v221, v221, v229
	v_log_f32_e32 v218, v218
	v_log_f32_e32 v219, v219
	v_log_f32_e32 v220, v220
	v_log_f32_e32 v221, v221
	v_log_f32_e32 v222, v222
	v_log_f32_e32 v223, v223
	v_log_f32_e32 v224, v224
	v_log_f32_e32 v225, v225
	v_mul_f32_e32 v226, 0x3f317217, v218
	v_mul_f32_e32 v227, 0x3f317217, v219
	v_mul_f32_e32 v228, 0x3f317217, v220
	v_mul_f32_e32 v229, 0x3f317217, v221
	v_fma_f32 v226, v218, s70, -v226
	v_fma_f32 v227, v219, s70, -v227
	v_fma_f32 v228, v220, s70, -v228
	v_fma_f32 v229, v221, s70, -v229
	v_fmac_f32_e32 v226, 0x3377d1cf, v218
	v_fmac_f32_e32 v227, 0x3377d1cf, v219
	v_fmac_f32_e32 v228, 0x3377d1cf, v220
	v_fmac_f32_e32 v229, 0x3377d1cf, v221
	v_fmac_f32_e32 v226, 0x3f317217, v218
	v_fmac_f32_e32 v227, 0x3f317217, v219
	v_fmac_f32_e32 v228, 0x3f317217, v220
	v_fmac_f32_e32 v229, 0x3f317217, v221
	v_cmp_lt_f32_e64 s[24:25], |v218|, s71
	v_cmp_lt_f32_e64 s[28:29], |v219|, s71
	v_cmp_lt_f32_e64 s[30:31], |v220|, s71
	v_cmp_lt_f32_e64 s[98:99], |v221|, s71
	v_cndmask_b32_e64 v218, v218, v226, s[24:25]
	v_cndmask_b32_e64 v219, v219, v227, s[28:29]
	v_cndmask_b32_e64 v220, v220, v228, s[30:31]
	v_cndmask_b32_e64 v221, v221, v229, s[98:99]
	v_sub_f32_e32 v218, v218, v238
	v_sub_f32_e32 v219, v219, v239
	v_sub_f32_e32 v220, v220, v240
	v_sub_f32_e32 v221, v221, v241
	v_mul_f32_e32 v226, 0x3f317217, v222
	v_mul_f32_e32 v227, 0x3f317217, v223
	v_mul_f32_e32 v228, 0x3f317217, v224
	v_mul_f32_e32 v229, 0x3f317217, v225
	v_fma_f32 v226, v222, s70, -v226
	v_fma_f32 v227, v223, s70, -v227
	v_fma_f32 v228, v224, s70, -v228
	v_fma_f32 v229, v225, s70, -v229
	v_fmac_f32_e32 v226, 0x3377d1cf, v222
	v_fmac_f32_e32 v227, 0x3377d1cf, v223
	v_fmac_f32_e32 v228, 0x3377d1cf, v224
	v_fmac_f32_e32 v229, 0x3377d1cf, v225
	v_fmac_f32_e32 v226, 0x3f317217, v222
	v_fmac_f32_e32 v227, 0x3f317217, v223
	v_fmac_f32_e32 v228, 0x3f317217, v224
	v_fmac_f32_e32 v229, 0x3f317217, v225
	v_bfi_b32 v218, v230, v218, v44
	v_bfi_b32 v219, v231, v219, v45
	v_bfi_b32 v220, v232, v220, v46
	v_bfi_b32 v221, v233, v221, v47
	v_sub_f32_e32 v44, v218, v226
	v_sub_f32_e32 v45, v219, v227
	v_sub_f32_e32 v46, v220, v228
	v_sub_f32_e32 v47, v221, v229
	v_cvt_pk_f16_f32 v234, v40, v41
	v_cvt_pk_f16_f32 v235, v42, v43
	v_cvt_pk_f16_f32 v236, v44, v45
	v_cvt_pk_f16_f32 v237, v46, v47
	global_store_dwordx4 v169, v[234:237], s[26:27] offset:256
	s_add_u32 s26, s26, 0x4000
	s_addc_u32 s27, s27, 0
	v_mul_f32_e64 v226, |v96|, s83
	v_mul_f32_e64 v227, |v97|, s83
	v_mul_f32_e64 v228, |v98|, s83
	v_mul_f32_e64 v229, |v99|, s83
	v_exp_f32_e32 v214, v226
	v_exp_f32_e32 v215, v227
	v_exp_f32_e32 v216, v228
	v_exp_f32_e32 v217, v229
	v_cmp_le_f32_e64 s[24:25], 0, v96
	v_cmp_le_f32_e64 s[28:29], 0, v97
	v_cmp_le_f32_e64 s[30:31], 0, v98
	v_cmp_le_f32_e64 s[98:99], 0, v99
	v_fma_f32 v218, v214, v128, 1.0
	v_fma_f32 v219, v215, v129, 1.0
	v_fma_f32 v220, v216, v130, 1.0
	v_fma_f32 v221, v217, v131, 1.0
	v_add_f32_e32 v222, v214, v128
	v_add_f32_e32 v223, v215, v129
	v_add_f32_e32 v224, v216, v130
	v_add_f32_e32 v225, v217, v131
	v_cndmask_b32_e64 v218, v222, v218, s[24:25]
	v_cndmask_b32_e64 v219, v223, v219, s[28:29]
	v_cndmask_b32_e64 v220, v224, v220, s[30:31]
	v_cndmask_b32_e64 v221, v225, v221, s[98:99]
	v_cndmask_b32_e64 v230, v180, -1, s[24:25]
	v_cndmask_b32_e64 v231, v181, -1, s[28:29]
	v_cndmask_b32_e64 v232, v182, -1, s[30:31]
	v_cndmask_b32_e64 v233, v183, -1, s[98:99]
; __device__ __forceinline__ unsigned cvt_pk_bf16(float lo, float hi) { const f32x2c v = {lo, hi}; const bf16x2c b = __builtin_convertvector(v, bf16x2c); return __builtin_bit_cast(unsigned, b); }
; #define PG8_GAS __attribute__((address_space(1)))
; __device__ __forceinline__ float gate_logf(float fp, float lb) {
;     const float e = __expf(-fabsf(fp)), l1pe = __logf(1.f + e);
;     return (fp >= 0.f ? __logf(1.f + lb * e) : (lb > 0.f ? __logf(lb + e) : fp)) - l1pe;
;     __device__ __forceinline__ void operator()(const f32x4 (&acc)[2][2][4][2], const Unit& u, int wr, int wc, int fr, int fq) const {
;     ...
;                         if (seg == 4) {
;                             const f32x4 l0 = *(const PG8_GAS f32x4*)(lbl + wcol), l1 = *(const PG8_GAS f32x4*)(lbl + wcol + 4);
; #pragma unroll
;                             for (int j = 0; j < 4; ++j) { v0[j] = gate_logf(v0[j], l0[j]); v1[j] = gate_logf(v1[j], l1[j]); }
;                         }
;                         u32x4 w;
;                         if (seg == 4) { w.x = cvt_pk_f16(v0[0], v0[1]); w.y = cvt_pk_f16(v0[2], v0[3]); w.z = cvt_pk_f16(v1[0], v1[1]); w.w = cvt_pk_f16(v1[2], v1[3]); }
;                         else { w.x = cvt_pk_bf16(v0[0], v0[1]); w.y = cvt_pk_bf16(v0[2], v0[3]); w.z = cvt_pk_bf16(v1[0], v1[1]); w.w = cvt_pk_bf16(v1[2], v1[3]); }
;                         *(PG8_GAS u32x4*)(segp + (size_t)r * 512 + wcol) = w;
	v_cmp_gt_f32_e64 s[24:25], s35, v218
	v_cmp_gt_f32_e64 s[28:29], s35, v219
	v_cmp_gt_f32_e64 s[30:31], s35, v220
	v_cmp_gt_f32_e64 s[98:99], s35, v221
	v_add_f32_e32 v222, 1.0, v214
	v_add_f32_e32 v223, 1.0, v215
	v_add_f32_e32 v224, 1.0, v216
	v_add_f32_e32 v225, 1.0, v217
	v_cndmask_b32_e64 v226, 0, 32, s[24:25]
	v_cndmask_b32_e64 v227, 0, 32, s[28:29]
	v_cndmask_b32_e64 v228, 0, 32, s[30:31]
	v_cndmask_b32_e64 v229, 0, 32, s[98:99]
	v_cndmask_b32_e64 v238, 0, v213, s[24:25]
	v_cndmask_b32_e64 v239, 0, v213, s[28:29]
	v_cndmask_b32_e64 v240, 0, v213, s[30:31]
	v_cndmask_b32_e64 v241, 0, v213, s[98:99]
	v_ldexp_f32 v218, v218, v226
	v_ldexp_f32 v219, v219, v227
	v_ldexp_f32 v220, v220, v228
	v_ldexp_f32 v221, v221, v229
	v_log_f32_e32 v218, v218
	v_log_f32_e32 v219, v219
	v_log_f32_e32 v220, v220
	v_log_f32_e32 v221, v221
	v_log_f32_e32 v222, v222
	v_log_f32_e32 v223, v223
	v_log_f32_e32 v224, v224
	v_log_f32_e32 v225, v225
	v_mul_f32_e32 v226, 0x3f317217, v218
	v_mul_f32_e32 v227, 0x3f317217, v219
	v_mul_f32_e32 v228, 0x3f317217, v220
	v_mul_f32_e32 v229, 0x3f317217, v221
	v_fma_f32 v226, v218, s70, -v226
	v_fma_f32 v227, v219, s70, -v227
	v_fma_f32 v228, v220, s70, -v228
	v_fma_f32 v229, v221, s70, -v229
	v_fmac_f32_e32 v226, 0x3377d1cf, v218
	v_fmac_f32_e32 v227, 0x3377d1cf, v219
	v_fmac_f32_e32 v228, 0x3377d1cf, v220
	v_fmac_f32_e32 v229, 0x3377d1cf, v221
	v_fmac_f32_e32 v226, 0x3f317217, v218
	v_fmac_f32_e32 v227, 0x3f317217, v219
	v_fmac_f32_e32 v228, 0x3f317217, v220
	v_fmac_f32_e32 v229, 0x3f317217, v221
	v_cmp_lt_f32_e64 s[24:25], |v218|, s71
	v_cmp_lt_f32_e64 s[28:29], |v219|, s71
	v_cmp_lt_f32_e64 s[30:31], |v220|, s71
	v_cmp_lt_f32_e64 s[98:99], |v221|, s71
	v_cndmask_b32_e64 v218, v218, v226, s[24:25]
	v_cndmask_b32_e64 v219, v219, v227, s[28:29]
	v_cndmask_b32_e64 v220, v220, v228, s[30:31]
	v_cndmask_b32_e64 v221, v221, v229, s[98:99]
	v_sub_f32_e32 v218, v218, v238
	v_sub_f32_e32 v219, v219, v239
	v_sub_f32_e32 v220, v220, v240
	v_sub_f32_e32 v221, v221, v241
	v_mul_f32_e32 v226, 0x3f317217, v222
	v_mul_f32_e32 v227, 0x3f317217, v223
	v_mul_f32_e32 v228, 0x3f317217, v224
	v_mul_f32_e32 v229, 0x3f317217, v225
	v_fma_f32 v226, v222, s70, -v226
	v_fma_f32 v227, v223, s70, -v227
	v_fma_f32 v228, v224, s70, -v228
	v_fma_f32 v229, v225, s70, -v229
	v_fmac_f32_e32 v226, 0x3377d1cf, v222
	v_fmac_f32_e32 v227, 0x3377d1cf, v223
	v_fmac_f32_e32 v228, 0x3377d1cf, v224
	v_fmac_f32_e32 v229, 0x3377d1cf, v225
	v_fmac_f32_e32 v226, 0x3f317217, v222
	v_fmac_f32_e32 v227, 0x3f317217, v223
	v_fmac_f32_e32 v228, 0x3f317217, v224
	v_fmac_f32_e32 v229, 0x3f317217, v225
	v_bfi_b32 v218, v230, v218, v96
	v_bfi_b32 v219, v231, v219, v97
	v_bfi_b32 v220, v232, v220, v98
	v_bfi_b32 v221, v233, v221, v99
	v_sub_f32_e32 v96, v218, v226
	v_sub_f32_e32 v97, v219, v227
	v_sub_f32_e32 v98, v220, v228
	v_sub_f32_e32 v99, v221, v229
	v_mul_f32_e64 v226, |v100|, s83
	v_mul_f32_e64 v227, |v101|, s83
	v_mul_f32_e64 v228, |v102|, s83
	v_mul_f32_e64 v229, |v103|, s83
	v_exp_f32_e32 v214, v226
	v_exp_f32_e32 v215, v227
	v_exp_f32_e32 v216, v228
	v_exp_f32_e32 v217, v229
	v_cmp_le_f32_e64 s[24:25], 0, v100
	v_cmp_le_f32_e64 s[28:29], 0, v101
	v_cmp_le_f32_e64 s[30:31], 0, v102
	v_cmp_le_f32_e64 s[98:99], 0, v103
	v_fma_f32 v218, v214, v132, 1.0
	v_fma_f32 v219, v215, v133, 1.0
	v_fma_f32 v220, v216, v134, 1.0
	v_fma_f32 v221, v217, v135, 1.0
	v_add_f32_e32 v222, v214, v132
	v_add_f32_e32 v223, v215, v133
	v_add_f32_e32 v224, v216, v134
	v_add_f32_e32 v225, v217, v135
	v_cndmask_b32_e64 v218, v222, v218, s[24:25]
	v_cndmask_b32_e64 v219, v223, v219, s[28:29]
	v_cndmask_b32_e64 v220, v224, v220, s[30:31]
	v_cndmask_b32_e64 v221, v225, v221, s[98:99]
	v_cndmask_b32_e64 v230, v184, -1, s[24:25]
	v_cndmask_b32_e64 v231, v185, -1, s[28:29]
	v_cndmask_b32_e64 v232, v186, -1, s[30:31]
	v_cndmask_b32_e64 v233, v187, -1, s[98:99]
	v_cmp_gt_f32_e64 s[24:25], s35, v218
	v_cmp_gt_f32_e64 s[28:29], s35, v219
	v_cmp_gt_f32_e64 s[30:31], s35, v220
	v_cmp_gt_f32_e64 s[98:99], s35, v221
	v_add_f32_e32 v222, 1.0, v214
	v_add_f32_e32 v223, 1.0, v215
	v_add_f32_e32 v224, 1.0, v216
	v_add_f32_e32 v225, 1.0, v217
	v_cndmask_b32_e64 v226, 0, 32, s[24:25]
	v_cndmask_b32_e64 v227, 0, 32, s[28:29]
	v_cndmask_b32_e64 v228, 0, 32, s[30:31]
	v_cndmask_b32_e64 v229, 0, 32, s[98:99]
	v_cndmask_b32_e64 v238, 0, v213, s[24:25]
	v_cndmask_b32_e64 v239, 0, v213, s[28:29]
	v_cndmask_b32_e64 v240, 0, v213, s[30:31]
	v_cndmask_b32_e64 v241, 0, v213, s[98:99]
	v_ldexp_f32 v218, v218, v226
	v_ldexp_f32 v219, v219, v227
	v_ldexp_f32 v220, v220, v228
	v_ldexp_f32 v221, v221, v229
	v_log_f32_e32 v218, v218
	v_log_f32_e32 v219, v219
	v_log_f32_e32 v220, v220
	v_log_f32_e32 v221, v221
	v_log_f32_e32 v222, v222
	v_log_f32_e32 v223, v223
	v_log_f32_e32 v224, v224
	v_log_f32_e32 v225, v225
	v_mul_f32_e32 v226, 0x3f317217, v218
	v_mul_f32_e32 v227, 0x3f317217, v219
	v_mul_f32_e32 v228, 0x3f317217, v220
	v_mul_f32_e32 v229, 0x3f317217, v221
	v_fma_f32 v226, v218, s70, -v226
	v_fma_f32 v227, v219, s70, -v227
	v_fma_f32 v228, v220, s70, -v228
	v_fma_f32 v229, v221, s70, -v229
	v_fmac_f32_e32 v226, 0x3377d1cf, v218
	v_fmac_f32_e32 v227, 0x3377d1cf, v219
	v_fmac_f32_e32 v228, 0x3377d1cf, v220
	v_fmac_f32_e32 v229, 0x3377d1cf, v221
	v_fmac_f32_e32 v226, 0x3f317217, v218
	v_fmac_f32_e32 v227, 0x3f317217, v219
	v_fmac_f32_e32 v228, 0x3f317217, v220
	v_fmac_f32_e32 v229, 0x3f317217, v221
	v_cmp_lt_f32_e64 s[24:25], |v218|, s71
	v_cmp_lt_f32_e64 s[28:29], |v219|, s71
	v_cmp_lt_f32_e64 s[30:31], |v220|, s71
	v_cmp_lt_f32_e64 s[98:99], |v221|, s71
	v_cndmask_b32_e64 v218, v218, v226, s[24:25]
	v_cndmask_b32_e64 v219, v219, v227, s[28:29]
; __device__ __forceinline__ unsigned cvt_pk_bf16(float lo, float hi) { const f32x2c v = {lo, hi}; const bf16x2c b = __builtin_convertvector(v, bf16x2c); return __builtin_bit_cast(unsigned, b); }
; #define PG8_GAS __attribute__((address_space(1)))
; __device__ __forceinline__ float gate_logf(float fp, float lb) {
;     const float e = __expf(-fabsf(fp)), l1pe = __logf(1.f + e);
;     return (fp >= 0.f ? __logf(1.f + lb * e) : (lb > 0.f ? __logf(lb + e) : fp)) - l1pe;
;     __device__ __forceinline__ void operator()(const f32x4 (&acc)[2][2][4][2], const Unit& u, int wr, int wc, int fr, int fq) const {
;     ...
;                         if (seg == 4) {
;                             const f32x4 l0 = *(const PG8_GAS f32x4*)(lbl + wcol), l1 = *(const PG8_GAS f32x4*)(lbl + wcol + 4);
; #pragma unroll
;                             for (int j = 0; j < 4; ++j) { v0[j] = gate_logf(v0[j], l0[j]); v1[j] = gate_logf(v1[j], l1[j]); }
;                         }
;                         u32x4 w;
;                         if (seg == 4) { w.x = cvt_pk_f16(v0[0], v0[1]); w.y = cvt_pk_f16(v0[2], v0[3]); w.z = cvt_pk_f16(v1[0], v1[1]); w.w = cvt_pk_f16(v1[2], v1[3]); }
;                         else { w.x = cvt_pk_bf16(v0[0], v0[1]); w.y = cvt_pk_bf16(v0[2], v0[3]); w.z = cvt_pk_bf16(v1[0], v1[1]); w.w = cvt_pk_bf16(v1[2], v1[3]); }
;                         *(PG8_GAS u32x4*)(segp + (size_t)r * 512 + wcol) = w;
	v_cndmask_b32_e64 v220, v220, v228, s[30:31]
	v_cndmask_b32_e64 v221, v221, v229, s[98:99]
	v_sub_f32_e32 v218, v218, v238
	v_sub_f32_e32 v219, v219, v239
	v_sub_f32_e32 v220, v220, v240
	v_sub_f32_e32 v221, v221, v241
	v_mul_f32_e32 v226, 0x3f317217, v222
	v_mul_f32_e32 v227, 0x3f317217, v223
	v_mul_f32_e32 v228, 0x3f317217, v224
	v_mul_f32_e32 v229, 0x3f317217, v225
	v_fma_f32 v226, v222, s70, -v226
	v_fma_f32 v227, v223, s70, -v227
	v_fma_f32 v228, v224, s70, -v228
	v_fma_f32 v229, v225, s70, -v229
	v_fmac_f32_e32 v226, 0x3377d1cf, v222
	v_fmac_f32_e32 v227, 0x3377d1cf, v223
	v_fmac_f32_e32 v228, 0x3377d1cf, v224
	v_fmac_f32_e32 v229, 0x3377d1cf, v225
	v_fmac_f32_e32 v226, 0x3f317217, v222
	v_fmac_f32_e32 v227, 0x3f317217, v223
	v_fmac_f32_e32 v228, 0x3f317217, v224
	v_fmac_f32_e32 v229, 0x3f317217, v225
	v_bfi_b32 v218, v230, v218, v100
	v_bfi_b32 v219, v231, v219, v101
	v_bfi_b32 v220, v232, v220, v102
	v_bfi_b32 v221, v233, v221, v103
	v_sub_f32_e32 v100, v218, v226
	v_sub_f32_e32 v101, v219, v227
	v_sub_f32_e32 v102, v220, v228
	v_sub_f32_e32 v103, v221, v229
	v_cvt_pk_f16_f32 v234, v96, v97
	v_cvt_pk_f16_f32 v235, v98, v99
	v_cvt_pk_f16_f32 v236, v100, v101
	v_cvt_pk_f16_f32 v237, v102, v103
	global_store_dwordx4 v169, v[234:237], s[26:27]
	v_mul_f32_e64 v226, |v32|, s83
	v_mul_f32_e64 v227, |v33|, s83
	v_mul_f32_e64 v228, |v34|, s83
	v_mul_f32_e64 v229, |v35|, s83
	v_exp_f32_e32 v214, v226
	v_exp_f32_e32 v215, v227
	v_exp_f32_e32 v216, v228
	v_exp_f32_e32 v217, v229
	v_cmp_le_f32_e64 s[24:25], 0, v32
	v_cmp_le_f32_e64 s[28:29], 0, v33
	v_cmp_le_f32_e64 s[30:31], 0, v34
	v_cmp_le_f32_e64 s[98:99], 0, v35
	v_fma_f32 v218, v214, v136, 1.0
	v_fma_f32 v219, v215, v137, 1.0
	v_fma_f32 v220, v216, v138, 1.0
	v_fma_f32 v221, v217, v139, 1.0
	v_add_f32_e32 v222, v214, v136
	v_add_f32_e32 v223, v215, v137
	v_add_f32_e32 v224, v216, v138
	v_add_f32_e32 v225, v217, v139
	v_cndmask_b32_e64 v218, v222, v218, s[24:25]
	v_cndmask_b32_e64 v219, v223, v219, s[28:29]
	v_cndmask_b32_e64 v220, v224, v220, s[30:31]
	v_cndmask_b32_e64 v221, v225, v221, s[98:99]
	v_cndmask_b32_e64 v230, v188, -1, s[24:25]
	v_cndmask_b32_e64 v231, v189, -1, s[28:29]
	v_cndmask_b32_e64 v232, v190, -1, s[30:31]
	v_cndmask_b32_e64 v233, v191, -1, s[98:99]
	v_cmp_gt_f32_e64 s[24:25], s35, v218
	v_cmp_gt_f32_e64 s[28:29], s35, v219
	v_cmp_gt_f32_e64 s[30:31], s35, v220
	v_cmp_gt_f32_e64 s[98:99], s35, v221
	v_add_f32_e32 v222, 1.0, v214
	v_add_f32_e32 v223, 1.0, v215
	v_add_f32_e32 v224, 1.0, v216
	v_add_f32_e32 v225, 1.0, v217
	v_cndmask_b32_e64 v226, 0, 32, s[24:25]
	v_cndmask_b32_e64 v227, 0, 32, s[28:29]
	v_cndmask_b32_e64 v228, 0, 32, s[30:31]
	v_cndmask_b32_e64 v229, 0, 32, s[98:99]
	v_cndmask_b32_e64 v238, 0, v213, s[24:25]
	v_cndmask_b32_e64 v239, 0, v213, s[28:29]
	v_cndmask_b32_e64 v240, 0, v213, s[30:31]
	v_cndmask_b32_e64 v241, 0, v213, s[98:99]
	v_ldexp_f32 v218, v218, v226
	v_ldexp_f32 v219, v219, v227
	v_ldexp_f32 v220, v220, v228
	v_ldexp_f32 v221, v221, v229
	v_log_f32_e32 v218, v218
	v_log_f32_e32 v219, v219
	v_log_f32_e32 v220, v220
	v_log_f32_e32 v221, v221
	v_log_f32_e32 v222, v222
	v_log_f32_e32 v223, v223
	v_log_f32_e32 v224, v224
	v_log_f32_e32 v225, v225
	v_mul_f32_e32 v226, 0x3f317217, v218
	v_mul_f32_e32 v227, 0x3f317217, v219
	v_mul_f32_e32 v228, 0x3f317217, v220
	v_mul_f32_e32 v229, 0x3f317217, v221
	v_fma_f32 v226, v218, s70, -v226
	v_fma_f32 v227, v219, s70, -v227
	v_fma_f32 v228, v220, s70, -v228
	v_fma_f32 v229, v221, s70, -v229
	v_fmac_f32_e32 v226, 0x3377d1cf, v218
	v_fmac_f32_e32 v227, 0x3377d1cf, v219
	v_fmac_f32_e32 v228, 0x3377d1cf, v220
	v_fmac_f32_e32 v229, 0x3377d1cf, v221
	v_fmac_f32_e32 v226, 0x3f317217, v218
	v_fmac_f32_e32 v227, 0x3f317217, v219
	v_fmac_f32_e32 v228, 0x3f317217, v220
	v_fmac_f32_e32 v229, 0x3f317217, v221
	v_cmp_lt_f32_e64 s[24:25], |v218|, s71
	v_cmp_lt_f32_e64 s[28:29], |v219|, s71
	v_cmp_lt_f32_e64 s[30:31], |v220|, s71
	v_cmp_lt_f32_e64 s[98:99], |v221|, s71
	v_cndmask_b32_e64 v218, v218, v226, s[24:25]
	v_cndmask_b32_e64 v219, v219, v227, s[28:29]
	v_cndmask_b32_e64 v220, v220, v228, s[30:31]
	v_cndmask_b32_e64 v221, v221, v229, s[98:99]
	v_sub_f32_e32 v218, v218, v238
	v_sub_f32_e32 v219, v219, v239
	v_sub_f32_e32 v220, v220, v240
	v_sub_f32_e32 v221, v221, v241
	v_mul_f32_e32 v226, 0x3f317217, v222
	v_mul_f32_e32 v227, 0x3f317217, v223
	v_mul_f32_e32 v228, 0x3f317217, v224
	v_mul_f32_e32 v229, 0x3f317217, v225
	v_fma_f32 v226, v222, s70, -v226
	v_fma_f32 v227, v223, s70, -v227
	v_fma_f32 v228, v224, s70, -v228
	v_fma_f32 v229, v225, s70, -v229
	v_fmac_f32_e32 v226, 0x3377d1cf, v222
	v_fmac_f32_e32 v227, 0x3377d1cf, v223
	v_fmac_f32_e32 v228, 0x3377d1cf, v224
	v_fmac_f32_e32 v229, 0x3377d1cf, v225
	v_fmac_f32_e32 v226, 0x3f317217, v222
	v_fmac_f32_e32 v227, 0x3f317217, v223
	v_fmac_f32_e32 v228, 0x3f317217, v224
	v_fmac_f32_e32 v229, 0x3f317217, v225
	v_bfi_b32 v218, v230, v218, v32
	v_bfi_b32 v219, v231, v219, v33
	v_bfi_b32 v220, v232, v220, v34
	v_bfi_b32 v221, v233, v221, v35
	v_sub_f32_e32 v32, v218, v226
	v_sub_f32_e32 v33, v219, v227
	v_sub_f32_e32 v34, v220, v228
	v_sub_f32_e32 v35, v221, v229
	v_mul_f32_e64 v226, |v36|, s83
	v_mul_f32_e64 v227, |v37|, s83
	v_mul_f32_e64 v228, |v38|, s83
	v_mul_f32_e64 v229, |v39|, s83
	v_exp_f32_e32 v214, v226
	v_exp_f32_e32 v215, v227
	v_exp_f32_e32 v216, v228
	v_exp_f32_e32 v217, v229
	v_cmp_le_f32_e64 s[24:25], 0, v36
	v_cmp_le_f32_e64 s[28:29], 0, v37
	v_cmp_le_f32_e64 s[30:31], 0, v38
	v_cmp_le_f32_e64 s[98:99], 0, v39
	v_fma_f32 v218, v214, v140, 1.0
	v_fma_f32 v219, v215, v141, 1.0
	v_fma_f32 v220, v216, v142, 1.0
	v_fma_f32 v221, v217, v143, 1.0
; __device__ __forceinline__ unsigned cvt_pk_bf16(float lo, float hi) { const f32x2c v = {lo, hi}; const bf16x2c b = __builtin_convertvector(v, bf16x2c); return __builtin_bit_cast(unsigned, b); }
; #define PG8_GAS __attribute__((address_space(1)))
; __device__ __forceinline__ float gate_logf(float fp, float lb) {
;     const float e = __expf(-fabsf(fp)), l1pe = __logf(1.f + e);
;     return (fp >= 0.f ? __logf(1.f + lb * e) : (lb > 0.f ? __logf(lb + e) : fp)) - l1pe;
;     __device__ __forceinline__ void operator()(const f32x4 (&acc)[2][2][4][2], const Unit& u, int wr, int wc, int fr, int fq) const {
;     ...
;                         if (seg == 4) {
;                             const f32x4 l0 = *(const PG8_GAS f32x4*)(lbl + wcol), l1 = *(const PG8_GAS f32x4*)(lbl + wcol + 4);
; #pragma unroll
;                             for (int j = 0; j < 4; ++j) { v0[j] = gate_logf(v0[j], l0[j]); v1[j] = gate_logf(v1[j], l1[j]); }
;                         }
;                         u32x4 w;
;                         if (seg == 4) { w.x = cvt_pk_f16(v0[0], v0[1]); w.y = cvt_pk_f16(v0[2], v0[3]); w.z = cvt_pk_f16(v1[0], v1[1]); w.w = cvt_pk_f16(v1[2], v1[3]); }
;                         else { w.x = cvt_pk_bf16(v0[0], v0[1]); w.y = cvt_pk_bf16(v0[2], v0[3]); w.z = cvt_pk_bf16(v1[0], v1[1]); w.w = cvt_pk_bf16(v1[2], v1[3]); }
;                         *(PG8_GAS u32x4*)(segp + (size_t)r * 512 + wcol) = w;
	v_add_f32_e32 v222, v214, v140
	v_add_f32_e32 v223, v215, v141
	v_add_f32_e32 v224, v216, v142
	v_add_f32_e32 v225, v217, v143
	v_cndmask_b32_e64 v218, v222, v218, s[24:25]
	v_cndmask_b32_e64 v219, v223, v219, s[28:29]
	v_cndmask_b32_e64 v220, v224, v220, s[30:31]
	v_cndmask_b32_e64 v221, v225, v221, s[98:99]
	v_cndmask_b32_e64 v230, v192, -1, s[24:25]
	v_cndmask_b32_e64 v231, v193, -1, s[28:29]
	v_cndmask_b32_e64 v232, v194, -1, s[30:31]
	v_cndmask_b32_e64 v233, v195, -1, s[98:99]
	v_cmp_gt_f32_e64 s[24:25], s35, v218
	v_cmp_gt_f32_e64 s[28:29], s35, v219
	v_cmp_gt_f32_e64 s[30:31], s35, v220
	v_cmp_gt_f32_e64 s[98:99], s35, v221
	v_add_f32_e32 v222, 1.0, v214
	v_add_f32_e32 v223, 1.0, v215
	v_add_f32_e32 v224, 1.0, v216
	v_add_f32_e32 v225, 1.0, v217
	v_cndmask_b32_e64 v226, 0, 32, s[24:25]
	v_cndmask_b32_e64 v227, 0, 32, s[28:29]
	v_cndmask_b32_e64 v228, 0, 32, s[30:31]
	v_cndmask_b32_e64 v229, 0, 32, s[98:99]
	v_cndmask_b32_e64 v238, 0, v213, s[24:25]
	v_cndmask_b32_e64 v239, 0, v213, s[28:29]
	v_cndmask_b32_e64 v240, 0, v213, s[30:31]
	v_cndmask_b32_e64 v241, 0, v213, s[98:99]
	v_ldexp_f32 v218, v218, v226
	v_ldexp_f32 v219, v219, v227
	v_ldexp_f32 v220, v220, v228
	v_ldexp_f32 v221, v221, v229
	v_log_f32_e32 v218, v218
	v_log_f32_e32 v219, v219
	v_log_f32_e32 v220, v220
	v_log_f32_e32 v221, v221
	v_log_f32_e32 v222, v222
	v_log_f32_e32 v223, v223
	v_log_f32_e32 v224, v224
	v_log_f32_e32 v225, v225
	v_mul_f32_e32 v226, 0x3f317217, v218
	v_mul_f32_e32 v227, 0x3f317217, v219
	v_mul_f32_e32 v228, 0x3f317217, v220
	v_mul_f32_e32 v229, 0x3f317217, v221
	v_fma_f32 v226, v218, s70, -v226
	v_fma_f32 v227, v219, s70, -v227
	v_fma_f32 v228, v220, s70, -v228
	v_fma_f32 v229, v221, s70, -v229
	v_fmac_f32_e32 v226, 0x3377d1cf, v218
	v_fmac_f32_e32 v227, 0x3377d1cf, v219
	v_fmac_f32_e32 v228, 0x3377d1cf, v220
	v_fmac_f32_e32 v229, 0x3377d1cf, v221
	v_fmac_f32_e32 v226, 0x3f317217, v218
	v_fmac_f32_e32 v227, 0x3f317217, v219
	v_fmac_f32_e32 v228, 0x3f317217, v220
	v_fmac_f32_e32 v229, 0x3f317217, v221
	v_cmp_lt_f32_e64 s[24:25], |v218|, s71
	v_cmp_lt_f32_e64 s[28:29], |v219|, s71
	v_cmp_lt_f32_e64 s[30:31], |v220|, s71
	v_cmp_lt_f32_e64 s[98:99], |v221|, s71
	v_cndmask_b32_e64 v218, v218, v226, s[24:25]
	v_cndmask_b32_e64 v219, v219, v227, s[28:29]
	v_cndmask_b32_e64 v220, v220, v228, s[30:31]
	v_cndmask_b32_e64 v221, v221, v229, s[98:99]
	v_sub_f32_e32 v218, v218, v238
	v_sub_f32_e32 v219, v219, v239
	v_sub_f32_e32 v220, v220, v240
	v_sub_f32_e32 v221, v221, v241
	v_mul_f32_e32 v226, 0x3f317217, v222
	v_mul_f32_e32 v227, 0x3f317217, v223
	v_mul_f32_e32 v228, 0x3f317217, v224
	v_mul_f32_e32 v229, 0x3f317217, v225
	v_fma_f32 v226, v222, s70, -v226
	v_fma_f32 v227, v223, s70, -v227
	v_fma_f32 v228, v224, s70, -v228
	v_fma_f32 v229, v225, s70, -v229
	v_fmac_f32_e32 v226, 0x3377d1cf, v222
	v_fmac_f32_e32 v227, 0x3377d1cf, v223
	v_fmac_f32_e32 v228, 0x3377d1cf, v224
	v_fmac_f32_e32 v229, 0x3377d1cf, v225
	v_fmac_f32_e32 v226, 0x3f317217, v222
	v_fmac_f32_e32 v227, 0x3f317217, v223
	v_fmac_f32_e32 v228, 0x3f317217, v224
	v_fmac_f32_e32 v229, 0x3f317217, v225
	v_bfi_b32 v218, v230, v218, v36
	v_bfi_b32 v219, v231, v219, v37
	v_bfi_b32 v220, v232, v220, v38
	v_bfi_b32 v221, v233, v221, v39
	v_sub_f32_e32 v36, v218, v226
	v_sub_f32_e32 v37, v219, v227
	v_sub_f32_e32 v38, v220, v228
	v_sub_f32_e32 v39, v221, v229
	v_cvt_pk_f16_f32 v234, v32, v33
	v_cvt_pk_f16_f32 v235, v34, v35
	v_cvt_pk_f16_f32 v236, v36, v37
	v_cvt_pk_f16_f32 v237, v38, v39
	global_store_dwordx4 v169, v[234:237], s[26:27] offset:256
	s_add_u32 s26, s26, 0x14000
	s_addc_u32 s27, s27, 0
	v_mul_f32_e64 v226, |v88|, s83
	v_mul_f32_e64 v227, |v89|, s83
	v_mul_f32_e64 v228, |v90|, s83
	v_mul_f32_e64 v229, |v91|, s83
	v_exp_f32_e32 v214, v226
	v_exp_f32_e32 v215, v227
	v_exp_f32_e32 v216, v228
	v_exp_f32_e32 v217, v229
	v_cmp_le_f32_e64 s[24:25], 0, v88
	v_cmp_le_f32_e64 s[28:29], 0, v89
	v_cmp_le_f32_e64 s[30:31], 0, v90
	v_cmp_le_f32_e64 s[98:99], 0, v91
	v_fma_f32 v218, v214, v128, 1.0
	v_fma_f32 v219, v215, v129, 1.0
	v_fma_f32 v220, v216, v130, 1.0
	v_fma_f32 v221, v217, v131, 1.0
	v_add_f32_e32 v222, v214, v128
	v_add_f32_e32 v223, v215, v129
	v_add_f32_e32 v224, v216, v130
	v_add_f32_e32 v225, v217, v131
	v_cndmask_b32_e64 v218, v222, v218, s[24:25]
	v_cndmask_b32_e64 v219, v223, v219, s[28:29]
	v_cndmask_b32_e64 v220, v224, v220, s[30:31]
	v_cndmask_b32_e64 v221, v225, v221, s[98:99]
	v_cndmask_b32_e64 v230, v180, -1, s[24:25]
	v_cndmask_b32_e64 v231, v181, -1, s[28:29]
	v_cndmask_b32_e64 v232, v182, -1, s[30:31]
	v_cndmask_b32_e64 v233, v183, -1, s[98:99]
	v_cmp_gt_f32_e64 s[24:25], s35, v218
	v_cmp_gt_f32_e64 s[28:29], s35, v219
	v_cmp_gt_f32_e64 s[30:31], s35, v220
	v_cmp_gt_f32_e64 s[98:99], s35, v221
	v_add_f32_e32 v222, 1.0, v214
	v_add_f32_e32 v223, 1.0, v215
	v_add_f32_e32 v224, 1.0, v216
	v_add_f32_e32 v225, 1.0, v217
	v_cndmask_b32_e64 v226, 0, 32, s[24:25]
	v_cndmask_b32_e64 v227, 0, 32, s[28:29]
	v_cndmask_b32_e64 v228, 0, 32, s[30:31]
	v_cndmask_b32_e64 v229, 0, 32, s[98:99]
	v_cndmask_b32_e64 v238, 0, v213, s[24:25]
	v_cndmask_b32_e64 v239, 0, v213, s[28:29]
	v_cndmask_b32_e64 v240, 0, v213, s[30:31]
	v_cndmask_b32_e64 v241, 0, v213, s[98:99]
	v_ldexp_f32 v218, v218, v226
	v_ldexp_f32 v219, v219, v227
	v_ldexp_f32 v220, v220, v228
	v_ldexp_f32 v221, v221, v229
	v_log_f32_e32 v218, v218
	v_log_f32_e32 v219, v219
	v_log_f32_e32 v220, v220
	v_log_f32_e32 v221, v221
	v_log_f32_e32 v222, v222
	v_log_f32_e32 v223, v223
	v_log_f32_e32 v224, v224
	v_log_f32_e32 v225, v225
	v_mul_f32_e32 v226, 0x3f317217, v218
	v_mul_f32_e32 v227, 0x3f317217, v219
	v_mul_f32_e32 v228, 0x3f317217, v220
; __device__ __forceinline__ unsigned cvt_pk_bf16(float lo, float hi) { const f32x2c v = {lo, hi}; const bf16x2c b = __builtin_convertvector(v, bf16x2c); return __builtin_bit_cast(unsigned, b); }
; #define PG8_GAS __attribute__((address_space(1)))
; __device__ __forceinline__ float gate_logf(float fp, float lb) {
;     const float e = __expf(-fabsf(fp)), l1pe = __logf(1.f + e);
;     return (fp >= 0.f ? __logf(1.f + lb * e) : (lb > 0.f ? __logf(lb + e) : fp)) - l1pe;
;     __device__ __forceinline__ void operator()(const f32x4 (&acc)[2][2][4][2], const Unit& u, int wr, int wc, int fr, int fq) const {
;     ...
;                         if (seg == 4) {
;                             const f32x4 l0 = *(const PG8_GAS f32x4*)(lbl + wcol), l1 = *(const PG8_GAS f32x4*)(lbl + wcol + 4);
; #pragma unroll
;                             for (int j = 0; j < 4; ++j) { v0[j] = gate_logf(v0[j], l0[j]); v1[j] = gate_logf(v1[j], l1[j]); }
;                         }
;                         u32x4 w;
;                         if (seg == 4) { w.x = cvt_pk_f16(v0[0], v0[1]); w.y = cvt_pk_f16(v0[2], v0[3]); w.z = cvt_pk_f16(v1[0], v1[1]); w.w = cvt_pk_f16(v1[2], v1[3]); }
;                         else { w.x = cvt_pk_bf16(v0[0], v0[1]); w.y = cvt_pk_bf16(v0[2], v0[3]); w.z = cvt_pk_bf16(v1[0], v1[1]); w.w = cvt_pk_bf16(v1[2], v1[3]); }
;                         *(PG8_GAS u32x4*)(segp + (size_t)r * 512 + wcol) = w;
	v_mul_f32_e32 v229, 0x3f317217, v221
	v_fma_f32 v226, v218, s70, -v226
	v_fma_f32 v227, v219, s70, -v227
	v_fma_f32 v228, v220, s70, -v228
	v_fma_f32 v229, v221, s70, -v229
	v_fmac_f32_e32 v226, 0x3377d1cf, v218
	v_fmac_f32_e32 v227, 0x3377d1cf, v219
	v_fmac_f32_e32 v228, 0x3377d1cf, v220
	v_fmac_f32_e32 v229, 0x3377d1cf, v221
	v_fmac_f32_e32 v226, 0x3f317217, v218
	v_fmac_f32_e32 v227, 0x3f317217, v219
	v_fmac_f32_e32 v228, 0x3f317217, v220
	v_fmac_f32_e32 v229, 0x3f317217, v221
	v_cmp_lt_f32_e64 s[24:25], |v218|, s71
	v_cmp_lt_f32_e64 s[28:29], |v219|, s71
	v_cmp_lt_f32_e64 s[30:31], |v220|, s71
	v_cmp_lt_f32_e64 s[98:99], |v221|, s71
	v_cndmask_b32_e64 v218, v218, v226, s[24:25]
	v_cndmask_b32_e64 v219, v219, v227, s[28:29]
	v_cndmask_b32_e64 v220, v220, v228, s[30:31]
	v_cndmask_b32_e64 v221, v221, v229, s[98:99]
	v_sub_f32_e32 v218, v218, v238
	v_sub_f32_e32 v219, v219, v239
	v_sub_f32_e32 v220, v220, v240
	v_sub_f32_e32 v221, v221, v241
	v_mul_f32_e32 v226, 0x3f317217, v222
	v_mul_f32_e32 v227, 0x3f317217, v223
	v_mul_f32_e32 v228, 0x3f317217, v224
	v_mul_f32_e32 v229, 0x3f317217, v225
	v_fma_f32 v226, v222, s70, -v226
	v_fma_f32 v227, v223, s70, -v227
	v_fma_f32 v228, v224, s70, -v228
	v_fma_f32 v229, v225, s70, -v229
	v_fmac_f32_e32 v226, 0x3377d1cf, v222
	v_fmac_f32_e32 v227, 0x3377d1cf, v223
	v_fmac_f32_e32 v228, 0x3377d1cf, v224
	v_fmac_f32_e32 v229, 0x3377d1cf, v225
	v_fmac_f32_e32 v226, 0x3f317217, v222
	v_fmac_f32_e32 v227, 0x3f317217, v223
	v_fmac_f32_e32 v228, 0x3f317217, v224
	v_fmac_f32_e32 v229, 0x3f317217, v225
	v_bfi_b32 v218, v230, v218, v88
	v_bfi_b32 v219, v231, v219, v89
	v_bfi_b32 v220, v232, v220, v90
	v_bfi_b32 v221, v233, v221, v91
	v_sub_f32_e32 v88, v218, v226
	v_sub_f32_e32 v89, v219, v227
	v_sub_f32_e32 v90, v220, v228
	v_sub_f32_e32 v91, v221, v229
	v_mul_f32_e64 v226, |v92|, s83
	v_mul_f32_e64 v227, |v93|, s83
	v_mul_f32_e64 v228, |v94|, s83
	v_mul_f32_e64 v229, |v95|, s83
	v_exp_f32_e32 v214, v226
	v_exp_f32_e32 v215, v227
	v_exp_f32_e32 v216, v228
	v_exp_f32_e32 v217, v229
	v_cmp_le_f32_e64 s[24:25], 0, v92
	v_cmp_le_f32_e64 s[28:29], 0, v93
	v_cmp_le_f32_e64 s[30:31], 0, v94
	v_cmp_le_f32_e64 s[98:99], 0, v95
	v_fma_f32 v218, v214, v132, 1.0
	v_fma_f32 v219, v215, v133, 1.0
	v_fma_f32 v220, v216, v134, 1.0
	v_fma_f32 v221, v217, v135, 1.0
	v_add_f32_e32 v222, v214, v132
	v_add_f32_e32 v223, v215, v133
	v_add_f32_e32 v224, v216, v134
	v_add_f32_e32 v225, v217, v135
	v_cndmask_b32_e64 v218, v222, v218, s[24:25]
	v_cndmask_b32_e64 v219, v223, v219, s[28:29]
	v_cndmask_b32_e64 v220, v224, v220, s[30:31]
	v_cndmask_b32_e64 v221, v225, v221, s[98:99]
	v_cndmask_b32_e64 v230, v184, -1, s[24:25]
	v_cndmask_b32_e64 v231, v185, -1, s[28:29]
	v_cndmask_b32_e64 v232, v186, -1, s[30:31]
	v_cndmask_b32_e64 v233, v187, -1, s[98:99]
	v_cmp_gt_f32_e64 s[24:25], s35, v218
	v_cmp_gt_f32_e64 s[28:29], s35, v219
	v_cmp_gt_f32_e64 s[30:31], s35, v220
	v_cmp_gt_f32_e64 s[98:99], s35, v221
	v_add_f32_e32 v222, 1.0, v214
	v_add_f32_e32 v223, 1.0, v215
	v_add_f32_e32 v224, 1.0, v216
	v_add_f32_e32 v225, 1.0, v217
	v_cndmask_b32_e64 v226, 0, 32, s[24:25]
	v_cndmask_b32_e64 v227, 0, 32, s[28:29]
	v_cndmask_b32_e64 v228, 0, 32, s[30:31]
	v_cndmask_b32_e64 v229, 0, 32, s[98:99]
	v_cndmask_b32_e64 v238, 0, v213, s[24:25]
	v_cndmask_b32_e64 v239, 0, v213, s[28:29]
	v_cndmask_b32_e64 v240, 0, v213, s[30:31]
	v_cndmask_b32_e64 v241, 0, v213, s[98:99]
	v_ldexp_f32 v218, v218, v226
	v_ldexp_f32 v219, v219, v227
	v_ldexp_f32 v220, v220, v228
	v_ldexp_f32 v221, v221, v229
	v_log_f32_e32 v218, v218
	v_log_f32_e32 v219, v219
	v_log_f32_e32 v220, v220
	v_log_f32_e32 v221, v221
	v_log_f32_e32 v222, v222
	v_log_f32_e32 v223, v223
	v_log_f32_e32 v224, v224
	v_log_f32_e32 v225, v225
	v_mul_f32_e32 v226, 0x3f317217, v218
	v_mul_f32_e32 v227, 0x3f317217, v219
	v_mul_f32_e32 v228, 0x3f317217, v220
	v_mul_f32_e32 v229, 0x3f317217, v221
	v_fma_f32 v226, v218, s70, -v226
	v_fma_f32 v227, v219, s70, -v227
	v_fma_f32 v228, v220, s70, -v228
	v_fma_f32 v229, v221, s70, -v229
	v_fmac_f32_e32 v226, 0x3377d1cf, v218
	v_fmac_f32_e32 v227, 0x3377d1cf, v219
	v_fmac_f32_e32 v228, 0x3377d1cf, v220
	v_fmac_f32_e32 v229, 0x3377d1cf, v221
	v_fmac_f32_e32 v226, 0x3f317217, v218
	v_fmac_f32_e32 v227, 0x3f317217, v219
	v_fmac_f32_e32 v228, 0x3f317217, v220
	v_fmac_f32_e32 v229, 0x3f317217, v221
	v_cmp_lt_f32_e64 s[24:25], |v218|, s71
	v_cmp_lt_f32_e64 s[28:29], |v219|, s71
	v_cmp_lt_f32_e64 s[30:31], |v220|, s71
	v_cmp_lt_f32_e64 s[98:99], |v221|, s71
	v_cndmask_b32_e64 v218, v218, v226, s[24:25]
	v_cndmask_b32_e64 v219, v219, v227, s[28:29]
	v_cndmask_b32_e64 v220, v220, v228, s[30:31]
	v_cndmask_b32_e64 v221, v221, v229, s[98:99]
	v_sub_f32_e32 v218, v218, v238
	v_sub_f32_e32 v219, v219, v239
	v_sub_f32_e32 v220, v220, v240
	v_sub_f32_e32 v221, v221, v241
	v_mul_f32_e32 v226, 0x3f317217, v222
	v_mul_f32_e32 v227, 0x3f317217, v223
	v_mul_f32_e32 v228, 0x3f317217, v224
	v_mul_f32_e32 v229, 0x3f317217, v225
	v_fma_f32 v226, v222, s70, -v226
	v_fma_f32 v227, v223, s70, -v227
	v_fma_f32 v228, v224, s70, -v228
	v_fma_f32 v229, v225, s70, -v229
	v_fmac_f32_e32 v226, 0x3377d1cf, v222
	v_fmac_f32_e32 v227, 0x3377d1cf, v223
	v_fmac_f32_e32 v228, 0x3377d1cf, v224
	v_fmac_f32_e32 v229, 0x3377d1cf, v225
	v_fmac_f32_e32 v226, 0x3f317217, v222
	v_fmac_f32_e32 v227, 0x3f317217, v223
	v_fmac_f32_e32 v228, 0x3f317217, v224
	v_fmac_f32_e32 v229, 0x3f317217, v225
	v_bfi_b32 v218, v230, v218, v92
	v_bfi_b32 v219, v231, v219, v93
	v_bfi_b32 v220, v232, v220, v94
	v_bfi_b32 v221, v233, v221, v95
	v_sub_f32_e32 v92, v218, v226
	v_sub_f32_e32 v93, v219, v227
	v_sub_f32_e32 v94, v220, v228
; __device__ __forceinline__ unsigned cvt_pk_bf16(float lo, float hi) { const f32x2c v = {lo, hi}; const bf16x2c b = __builtin_convertvector(v, bf16x2c); return __builtin_bit_cast(unsigned, b); }
; #define PG8_GAS __attribute__((address_space(1)))
; __device__ __forceinline__ float gate_logf(float fp, float lb) {
;     const float e = __expf(-fabsf(fp)), l1pe = __logf(1.f + e);
;     return (fp >= 0.f ? __logf(1.f + lb * e) : (lb > 0.f ? __logf(lb + e) : fp)) - l1pe;
;     __device__ __forceinline__ void operator()(const f32x4 (&acc)[2][2][4][2], const Unit& u, int wr, int wc, int fr, int fq) const {
;     ...
;                         if (seg == 4) {
;                             const f32x4 l0 = *(const PG8_GAS f32x4*)(lbl + wcol), l1 = *(const PG8_GAS f32x4*)(lbl + wcol + 4);
; #pragma unroll
;                             for (int j = 0; j < 4; ++j) { v0[j] = gate_logf(v0[j], l0[j]); v1[j] = gate_logf(v1[j], l1[j]); }
;                         }
;                         u32x4 w;
;                         if (seg == 4) { w.x = cvt_pk_f16(v0[0], v0[1]); w.y = cvt_pk_f16(v0[2], v0[3]); w.z = cvt_pk_f16(v1[0], v1[1]); w.w = cvt_pk_f16(v1[2], v1[3]); }
;                         else { w.x = cvt_pk_bf16(v0[0], v0[1]); w.y = cvt_pk_bf16(v0[2], v0[3]); w.z = cvt_pk_bf16(v1[0], v1[1]); w.w = cvt_pk_bf16(v1[2], v1[3]); }
;                         *(PG8_GAS u32x4*)(segp + (size_t)r * 512 + wcol) = w;
	v_sub_f32_e32 v95, v221, v229
	v_cvt_pk_f16_f32 v234, v88, v89
	v_cvt_pk_f16_f32 v235, v90, v91
	v_cvt_pk_f16_f32 v236, v92, v93
	v_cvt_pk_f16_f32 v237, v94, v95
	global_store_dwordx4 v169, v[234:237], s[26:27]
	v_mul_f32_e64 v226, |v24|, s83
	v_mul_f32_e64 v227, |v25|, s83
	v_mul_f32_e64 v228, |v26|, s83
	v_mul_f32_e64 v229, |v27|, s83
	v_exp_f32_e32 v214, v226
	v_exp_f32_e32 v215, v227
	v_exp_f32_e32 v216, v228
	v_exp_f32_e32 v217, v229
	v_cmp_le_f32_e64 s[24:25], 0, v24
	v_cmp_le_f32_e64 s[28:29], 0, v25
	v_cmp_le_f32_e64 s[30:31], 0, v26
	v_cmp_le_f32_e64 s[98:99], 0, v27
	v_fma_f32 v218, v214, v136, 1.0
	v_fma_f32 v219, v215, v137, 1.0
	v_fma_f32 v220, v216, v138, 1.0
	v_fma_f32 v221, v217, v139, 1.0
	v_add_f32_e32 v222, v214, v136
	v_add_f32_e32 v223, v215, v137
	v_add_f32_e32 v224, v216, v138
	v_add_f32_e32 v225, v217, v139
	v_cndmask_b32_e64 v218, v222, v218, s[24:25]
	v_cndmask_b32_e64 v219, v223, v219, s[28:29]
	v_cndmask_b32_e64 v220, v224, v220, s[30:31]
	v_cndmask_b32_e64 v221, v225, v221, s[98:99]
	v_cndmask_b32_e64 v230, v188, -1, s[24:25]
	v_cndmask_b32_e64 v231, v189, -1, s[28:29]
	v_cndmask_b32_e64 v232, v190, -1, s[30:31]
	v_cndmask_b32_e64 v233, v191, -1, s[98:99]
	v_cmp_gt_f32_e64 s[24:25], s35, v218
	v_cmp_gt_f32_e64 s[28:29], s35, v219
	v_cmp_gt_f32_e64 s[30:31], s35, v220
	v_cmp_gt_f32_e64 s[98:99], s35, v221
	v_add_f32_e32 v222, 1.0, v214
	v_add_f32_e32 v223, 1.0, v215
	v_add_f32_e32 v224, 1.0, v216
	v_add_f32_e32 v225, 1.0, v217
	v_cndmask_b32_e64 v226, 0, 32, s[24:25]
	v_cndmask_b32_e64 v227, 0, 32, s[28:29]
	v_cndmask_b32_e64 v228, 0, 32, s[30:31]
	v_cndmask_b32_e64 v229, 0, 32, s[98:99]
	v_cndmask_b32_e64 v238, 0, v213, s[24:25]
	v_cndmask_b32_e64 v239, 0, v213, s[28:29]
	v_cndmask_b32_e64 v240, 0, v213, s[30:31]
	v_cndmask_b32_e64 v241, 0, v213, s[98:99]
	v_ldexp_f32 v218, v218, v226
	v_ldexp_f32 v219, v219, v227
	v_ldexp_f32 v220, v220, v228
	v_ldexp_f32 v221, v221, v229
	v_log_f32_e32 v218, v218
	v_log_f32_e32 v219, v219
	v_log_f32_e32 v220, v220
	v_log_f32_e32 v221, v221
	v_log_f32_e32 v222, v222
	v_log_f32_e32 v223, v223
	v_log_f32_e32 v224, v224
	v_log_f32_e32 v225, v225
	v_mul_f32_e32 v226, 0x3f317217, v218
	v_mul_f32_e32 v227, 0x3f317217, v219
	v_mul_f32_e32 v228, 0x3f317217, v220
	v_mul_f32_e32 v229, 0x3f317217, v221
	v_fma_f32 v226, v218, s70, -v226
	v_fma_f32 v227, v219, s70, -v227
	v_fma_f32 v228, v220, s70, -v228
	v_fma_f32 v229, v221, s70, -v229
	v_fmac_f32_e32 v226, 0x3377d1cf, v218
	v_fmac_f32_e32 v227, 0x3377d1cf, v219
	v_fmac_f32_e32 v228, 0x3377d1cf, v220
	v_fmac_f32_e32 v229, 0x3377d1cf, v221
	v_fmac_f32_e32 v226, 0x3f317217, v218
	v_fmac_f32_e32 v227, 0x3f317217, v219
	v_fmac_f32_e32 v228, 0x3f317217, v220
	v_fmac_f32_e32 v229, 0x3f317217, v221
	v_cmp_lt_f32_e64 s[24:25], |v218|, s71
	v_cmp_lt_f32_e64 s[28:29], |v219|, s71
	v_cmp_lt_f32_e64 s[30:31], |v220|, s71
	v_cmp_lt_f32_e64 s[98:99], |v221|, s71
	v_cndmask_b32_e64 v218, v218, v226, s[24:25]
	v_cndmask_b32_e64 v219, v219, v227, s[28:29]
	v_cndmask_b32_e64 v220, v220, v228, s[30:31]
	v_cndmask_b32_e64 v221, v221, v229, s[98:99]
	v_sub_f32_e32 v218, v218, v238
	v_sub_f32_e32 v219, v219, v239
	v_sub_f32_e32 v220, v220, v240
	v_sub_f32_e32 v221, v221, v241
	v_mul_f32_e32 v226, 0x3f317217, v222
	v_mul_f32_e32 v227, 0x3f317217, v223
	v_mul_f32_e32 v228, 0x3f317217, v224
	v_mul_f32_e32 v229, 0x3f317217, v225
	v_fma_f32 v226, v222, s70, -v226
	v_fma_f32 v227, v223, s70, -v227
	v_fma_f32 v228, v224, s70, -v228
	v_fma_f32 v229, v225, s70, -v229
	v_fmac_f32_e32 v226, 0x3377d1cf, v222
	v_fmac_f32_e32 v227, 0x3377d1cf, v223
	v_fmac_f32_e32 v228, 0x3377d1cf, v224
	v_fmac_f32_e32 v229, 0x3377d1cf, v225
	v_fmac_f32_e32 v226, 0x3f317217, v222
	v_fmac_f32_e32 v227, 0x3f317217, v223
	v_fmac_f32_e32 v228, 0x3f317217, v224
	v_fmac_f32_e32 v229, 0x3f317217, v225
	v_bfi_b32 v218, v230, v218, v24
	v_bfi_b32 v219, v231, v219, v25
	v_bfi_b32 v220, v232, v220, v26
	v_bfi_b32 v221, v233, v221, v27
	v_sub_f32_e32 v24, v218, v226
	v_sub_f32_e32 v25, v219, v227
	v_sub_f32_e32 v26, v220, v228
	v_sub_f32_e32 v27, v221, v229
	v_mul_f32_e64 v226, |v28|, s83
	v_mul_f32_e64 v227, |v29|, s83
	v_mul_f32_e64 v228, |v30|, s83
	v_mul_f32_e64 v229, |v31|, s83
	v_exp_f32_e32 v214, v226
	v_exp_f32_e32 v215, v227
	v_exp_f32_e32 v216, v228
	v_exp_f32_e32 v217, v229
	v_cmp_le_f32_e64 s[24:25], 0, v28
	v_cmp_le_f32_e64 s[28:29], 0, v29
	v_cmp_le_f32_e64 s[30:31], 0, v30
	v_cmp_le_f32_e64 s[98:99], 0, v31
	v_fma_f32 v218, v214, v140, 1.0
	v_fma_f32 v219, v215, v141, 1.0
	v_fma_f32 v220, v216, v142, 1.0
	v_fma_f32 v221, v217, v143, 1.0
	v_add_f32_e32 v222, v214, v140
	v_add_f32_e32 v223, v215, v141
	v_add_f32_e32 v224, v216, v142
	v_add_f32_e32 v225, v217, v143
	v_cndmask_b32_e64 v218, v222, v218, s[24:25]
	v_cndmask_b32_e64 v219, v223, v219, s[28:29]
	v_cndmask_b32_e64 v220, v224, v220, s[30:31]
	v_cndmask_b32_e64 v221, v225, v221, s[98:99]
	v_cndmask_b32_e64 v230, v192, -1, s[24:25]
	v_cndmask_b32_e64 v231, v193, -1, s[28:29]
	v_cndmask_b32_e64 v232, v194, -1, s[30:31]
	v_cndmask_b32_e64 v233, v195, -1, s[98:99]
	v_cmp_gt_f32_e64 s[24:25], s35, v218
	v_cmp_gt_f32_e64 s[28:29], s35, v219
	v_cmp_gt_f32_e64 s[30:31], s35, v220
	v_cmp_gt_f32_e64 s[98:99], s35, v221
	v_add_f32_e32 v222, 1.0, v214
	v_add_f32_e32 v223, 1.0, v215
	v_add_f32_e32 v224, 1.0, v216
	v_add_f32_e32 v225, 1.0, v217
	v_cndmask_b32_e64 v226, 0, 32, s[24:25]
	v_cndmask_b32_e64 v227, 0, 32, s[28:29]
	v_cndmask_b32_e64 v228, 0, 32, s[30:31]
	v_cndmask_b32_e64 v229, 0, 32, s[98:99]
	v_cndmask_b32_e64 v238, 0, v213, s[24:25]
	v_cndmask_b32_e64 v239, 0, v213, s[28:29]
	v_cndmask_b32_e64 v240, 0, v213, s[30:31]
; __device__ __forceinline__ unsigned cvt_pk_bf16(float lo, float hi) { const f32x2c v = {lo, hi}; const bf16x2c b = __builtin_convertvector(v, bf16x2c); return __builtin_bit_cast(unsigned, b); }
; #define PG8_GAS __attribute__((address_space(1)))
; __device__ __forceinline__ float gate_logf(float fp, float lb) {
;     const float e = __expf(-fabsf(fp)), l1pe = __logf(1.f + e);
;     return (fp >= 0.f ? __logf(1.f + lb * e) : (lb > 0.f ? __logf(lb + e) : fp)) - l1pe;
;     __device__ __forceinline__ void operator()(const f32x4 (&acc)[2][2][4][2], const Unit& u, int wr, int wc, int fr, int fq) const {
;     ...
;                         if (seg == 4) {
;                             const f32x4 l0 = *(const PG8_GAS f32x4*)(lbl + wcol), l1 = *(const PG8_GAS f32x4*)(lbl + wcol + 4);
; #pragma unroll
;                             for (int j = 0; j < 4; ++j) { v0[j] = gate_logf(v0[j], l0[j]); v1[j] = gate_logf(v1[j], l1[j]); }
;                         }
;                         u32x4 w;
;                         if (seg == 4) { w.x = cvt_pk_f16(v0[0], v0[1]); w.y = cvt_pk_f16(v0[2], v0[3]); w.z = cvt_pk_f16(v1[0], v1[1]); w.w = cvt_pk_f16(v1[2], v1[3]); }
;                         else { w.x = cvt_pk_bf16(v0[0], v0[1]); w.y = cvt_pk_bf16(v0[2], v0[3]); w.z = cvt_pk_bf16(v1[0], v1[1]); w.w = cvt_pk_bf16(v1[2], v1[3]); }
;                         *(PG8_GAS u32x4*)(segp + (size_t)r * 512 + wcol) = w;
	v_cndmask_b32_e64 v241, 0, v213, s[98:99]
	v_ldexp_f32 v218, v218, v226
	v_ldexp_f32 v219, v219, v227
	v_ldexp_f32 v220, v220, v228
	v_ldexp_f32 v221, v221, v229
	v_log_f32_e32 v218, v218
	v_log_f32_e32 v219, v219
	v_log_f32_e32 v220, v220
	v_log_f32_e32 v221, v221
	v_log_f32_e32 v222, v222
	v_log_f32_e32 v223, v223
	v_log_f32_e32 v224, v224
	v_log_f32_e32 v225, v225
	v_mul_f32_e32 v226, 0x3f317217, v218
	v_mul_f32_e32 v227, 0x3f317217, v219
	v_mul_f32_e32 v228, 0x3f317217, v220
	v_mul_f32_e32 v229, 0x3f317217, v221
	v_fma_f32 v226, v218, s70, -v226
	v_fma_f32 v227, v219, s70, -v227
	v_fma_f32 v228, v220, s70, -v228
	v_fma_f32 v229, v221, s70, -v229
	v_fmac_f32_e32 v226, 0x3377d1cf, v218
	v_fmac_f32_e32 v227, 0x3377d1cf, v219
	v_fmac_f32_e32 v228, 0x3377d1cf, v220
	v_fmac_f32_e32 v229, 0x3377d1cf, v221
	v_fmac_f32_e32 v226, 0x3f317217, v218
	v_fmac_f32_e32 v227, 0x3f317217, v219
	v_fmac_f32_e32 v228, 0x3f317217, v220
	v_fmac_f32_e32 v229, 0x3f317217, v221
	v_cmp_lt_f32_e64 s[24:25], |v218|, s71
	v_cmp_lt_f32_e64 s[28:29], |v219|, s71
	v_cmp_lt_f32_e64 s[30:31], |v220|, s71
	v_cmp_lt_f32_e64 s[98:99], |v221|, s71
	v_cndmask_b32_e64 v218, v218, v226, s[24:25]
	v_cndmask_b32_e64 v219, v219, v227, s[28:29]
	v_cndmask_b32_e64 v220, v220, v228, s[30:31]
	v_cndmask_b32_e64 v221, v221, v229, s[98:99]
	v_sub_f32_e32 v218, v218, v238
	v_sub_f32_e32 v219, v219, v239
	v_sub_f32_e32 v220, v220, v240
	v_sub_f32_e32 v221, v221, v241
	v_mul_f32_e32 v226, 0x3f317217, v222
	v_mul_f32_e32 v227, 0x3f317217, v223
	v_mul_f32_e32 v228, 0x3f317217, v224
	v_mul_f32_e32 v229, 0x3f317217, v225
	v_fma_f32 v226, v222, s70, -v226
	v_fma_f32 v227, v223, s70, -v227
	v_fma_f32 v228, v224, s70, -v228
	v_fma_f32 v229, v225, s70, -v229
	v_fmac_f32_e32 v226, 0x3377d1cf, v222
	v_fmac_f32_e32 v227, 0x3377d1cf, v223
	v_fmac_f32_e32 v228, 0x3377d1cf, v224
	v_fmac_f32_e32 v229, 0x3377d1cf, v225
	v_fmac_f32_e32 v226, 0x3f317217, v222
	v_fmac_f32_e32 v227, 0x3f317217, v223
	v_fmac_f32_e32 v228, 0x3f317217, v224
	v_fmac_f32_e32 v229, 0x3f317217, v225
	v_bfi_b32 v218, v230, v218, v28
	v_bfi_b32 v219, v231, v219, v29
	v_bfi_b32 v220, v232, v220, v30
	v_bfi_b32 v221, v233, v221, v31
	v_sub_f32_e32 v28, v218, v226
	v_sub_f32_e32 v29, v219, v227
	v_sub_f32_e32 v30, v220, v228
	v_sub_f32_e32 v31, v221, v229
	v_cvt_pk_f16_f32 v234, v24, v25
	v_cvt_pk_f16_f32 v235, v26, v27
	v_cvt_pk_f16_f32 v236, v28, v29
	v_cvt_pk_f16_f32 v237, v30, v31
	global_store_dwordx4 v169, v[234:237], s[26:27] offset:256
	s_add_u32 s26, s26, 0x4000
	s_addc_u32 s27, s27, 0
	v_mul_f32_e64 v226, |v80|, s83
	v_mul_f32_e64 v227, |v81|, s83
	v_mul_f32_e64 v228, |v82|, s83
	v_mul_f32_e64 v229, |v83|, s83
	v_exp_f32_e32 v214, v226
	v_exp_f32_e32 v215, v227
	v_exp_f32_e32 v216, v228
	v_exp_f32_e32 v217, v229
	v_cmp_le_f32_e64 s[24:25], 0, v80
	v_cmp_le_f32_e64 s[28:29], 0, v81
	v_cmp_le_f32_e64 s[30:31], 0, v82
	v_cmp_le_f32_e64 s[98:99], 0, v83
	v_fma_f32 v218, v214, v128, 1.0
	v_fma_f32 v219, v215, v129, 1.0
	v_fma_f32 v220, v216, v130, 1.0
	v_fma_f32 v221, v217, v131, 1.0
	v_add_f32_e32 v222, v214, v128
	v_add_f32_e32 v223, v215, v129
	v_add_f32_e32 v224, v216, v130
	v_add_f32_e32 v225, v217, v131
	v_cndmask_b32_e64 v218, v222, v218, s[24:25]
	v_cndmask_b32_e64 v219, v223, v219, s[28:29]
	v_cndmask_b32_e64 v220, v224, v220, s[30:31]
	v_cndmask_b32_e64 v221, v225, v221, s[98:99]
	v_cndmask_b32_e64 v230, v180, -1, s[24:25]
	v_cndmask_b32_e64 v231, v181, -1, s[28:29]
	v_cndmask_b32_e64 v232, v182, -1, s[30:31]
	v_cndmask_b32_e64 v233, v183, -1, s[98:99]
	v_cmp_gt_f32_e64 s[24:25], s35, v218
	v_cmp_gt_f32_e64 s[28:29], s35, v219
	v_cmp_gt_f32_e64 s[30:31], s35, v220
	v_cmp_gt_f32_e64 s[98:99], s35, v221
	v_add_f32_e32 v222, 1.0, v214
	v_add_f32_e32 v223, 1.0, v215
	v_add_f32_e32 v224, 1.0, v216
	v_add_f32_e32 v225, 1.0, v217
	v_cndmask_b32_e64 v226, 0, 32, s[24:25]
	v_cndmask_b32_e64 v227, 0, 32, s[28:29]
	v_cndmask_b32_e64 v228, 0, 32, s[30:31]
	v_cndmask_b32_e64 v229, 0, 32, s[98:99]
	v_cndmask_b32_e64 v238, 0, v213, s[24:25]
	v_cndmask_b32_e64 v239, 0, v213, s[28:29]
	v_cndmask_b32_e64 v240, 0, v213, s[30:31]
	v_cndmask_b32_e64 v241, 0, v213, s[98:99]
	v_ldexp_f32 v218, v218, v226
	v_ldexp_f32 v219, v219, v227
	v_ldexp_f32 v220, v220, v228
	v_ldexp_f32 v221, v221, v229
	v_log_f32_e32 v218, v218
	v_log_f32_e32 v219, v219
	v_log_f32_e32 v220, v220
	v_log_f32_e32 v221, v221
	v_log_f32_e32 v222, v222
	v_log_f32_e32 v223, v223
	v_log_f32_e32 v224, v224
	v_log_f32_e32 v225, v225
	v_mul_f32_e32 v226, 0x3f317217, v218
	v_mul_f32_e32 v227, 0x3f317217, v219
	v_mul_f32_e32 v228, 0x3f317217, v220
	v_mul_f32_e32 v229, 0x3f317217, v221
	v_fma_f32 v226, v218, s70, -v226
	v_fma_f32 v227, v219, s70, -v227
	v_fma_f32 v228, v220, s70, -v228
	v_fma_f32 v229, v221, s70, -v229
	v_fmac_f32_e32 v226, 0x3377d1cf, v218
	v_fmac_f32_e32 v227, 0x3377d1cf, v219
	v_fmac_f32_e32 v228, 0x3377d1cf, v220
	v_fmac_f32_e32 v229, 0x3377d1cf, v221
	v_fmac_f32_e32 v226, 0x3f317217, v218
	v_fmac_f32_e32 v227, 0x3f317217, v219
	v_fmac_f32_e32 v228, 0x3f317217, v220
	v_fmac_f32_e32 v229, 0x3f317217, v221
	v_cmp_lt_f32_e64 s[24:25], |v218|, s71
	v_cmp_lt_f32_e64 s[28:29], |v219|, s71
	v_cmp_lt_f32_e64 s[30:31], |v220|, s71
	v_cmp_lt_f32_e64 s[98:99], |v221|, s71
	v_cndmask_b32_e64 v218, v218, v226, s[24:25]
	v_cndmask_b32_e64 v219, v219, v227, s[28:29]
	v_cndmask_b32_e64 v220, v220, v228, s[30:31]
	v_cndmask_b32_e64 v221, v221, v229, s[98:99]
	v_sub_f32_e32 v218, v218, v238
	v_sub_f32_e32 v219, v219, v239
	v_sub_f32_e32 v220, v220, v240
	v_sub_f32_e32 v221, v221, v241
	v_mul_f32_e32 v226, 0x3f317217, v222
	v_mul_f32_e32 v227, 0x3f317217, v223
; __device__ __forceinline__ unsigned cvt_pk_bf16(float lo, float hi) { const f32x2c v = {lo, hi}; const bf16x2c b = __builtin_convertvector(v, bf16x2c); return __builtin_bit_cast(unsigned, b); }
; #define PG8_GAS __attribute__((address_space(1)))
; __device__ __forceinline__ float gate_logf(float fp, float lb) {
;     const float e = __expf(-fabsf(fp)), l1pe = __logf(1.f + e);
;     return (fp >= 0.f ? __logf(1.f + lb * e) : (lb > 0.f ? __logf(lb + e) : fp)) - l1pe;
;     __device__ __forceinline__ void operator()(const f32x4 (&acc)[2][2][4][2], const Unit& u, int wr, int wc, int fr, int fq) const {
;     ...
;                         if (seg == 4) {
;                             const f32x4 l0 = *(const PG8_GAS f32x4*)(lbl + wcol), l1 = *(const PG8_GAS f32x4*)(lbl + wcol + 4);
; #pragma unroll
;                             for (int j = 0; j < 4; ++j) { v0[j] = gate_logf(v0[j], l0[j]); v1[j] = gate_logf(v1[j], l1[j]); }
;                         }
;                         u32x4 w;
;                         if (seg == 4) { w.x = cvt_pk_f16(v0[0], v0[1]); w.y = cvt_pk_f16(v0[2], v0[3]); w.z = cvt_pk_f16(v1[0], v1[1]); w.w = cvt_pk_f16(v1[2], v1[3]); }
;                         else { w.x = cvt_pk_bf16(v0[0], v0[1]); w.y = cvt_pk_bf16(v0[2], v0[3]); w.z = cvt_pk_bf16(v1[0], v1[1]); w.w = cvt_pk_bf16(v1[2], v1[3]); }
;                         *(PG8_GAS u32x4*)(segp + (size_t)r * 512 + wcol) = w;
	v_mul_f32_e32 v228, 0x3f317217, v224
	v_mul_f32_e32 v229, 0x3f317217, v225
	v_fma_f32 v226, v222, s70, -v226
	v_fma_f32 v227, v223, s70, -v227
	v_fma_f32 v228, v224, s70, -v228
	v_fma_f32 v229, v225, s70, -v229
	v_fmac_f32_e32 v226, 0x3377d1cf, v222
	v_fmac_f32_e32 v227, 0x3377d1cf, v223
	v_fmac_f32_e32 v228, 0x3377d1cf, v224
	v_fmac_f32_e32 v229, 0x3377d1cf, v225
	v_fmac_f32_e32 v226, 0x3f317217, v222
	v_fmac_f32_e32 v227, 0x3f317217, v223
	v_fmac_f32_e32 v228, 0x3f317217, v224
	v_fmac_f32_e32 v229, 0x3f317217, v225
	v_bfi_b32 v218, v230, v218, v80
	v_bfi_b32 v219, v231, v219, v81
	v_bfi_b32 v220, v232, v220, v82
	v_bfi_b32 v221, v233, v221, v83
	v_sub_f32_e32 v80, v218, v226
	v_sub_f32_e32 v81, v219, v227
	v_sub_f32_e32 v82, v220, v228
	v_sub_f32_e32 v83, v221, v229
	v_mul_f32_e64 v226, |v84|, s83
	v_mul_f32_e64 v227, |v85|, s83
	v_mul_f32_e64 v228, |v86|, s83
	v_mul_f32_e64 v229, |v87|, s83
	v_exp_f32_e32 v214, v226
	v_exp_f32_e32 v215, v227
	v_exp_f32_e32 v216, v228
	v_exp_f32_e32 v217, v229
	v_cmp_le_f32_e64 s[24:25], 0, v84
	v_cmp_le_f32_e64 s[28:29], 0, v85
	v_cmp_le_f32_e64 s[30:31], 0, v86
	v_cmp_le_f32_e64 s[98:99], 0, v87
	v_fma_f32 v218, v214, v132, 1.0
	v_fma_f32 v219, v215, v133, 1.0
	v_fma_f32 v220, v216, v134, 1.0
	v_fma_f32 v221, v217, v135, 1.0
	v_add_f32_e32 v222, v214, v132
	v_add_f32_e32 v223, v215, v133
	v_add_f32_e32 v224, v216, v134
	v_add_f32_e32 v225, v217, v135
	v_cndmask_b32_e64 v218, v222, v218, s[24:25]
	v_cndmask_b32_e64 v219, v223, v219, s[28:29]
	v_cndmask_b32_e64 v220, v224, v220, s[30:31]
	v_cndmask_b32_e64 v221, v225, v221, s[98:99]
	v_cndmask_b32_e64 v230, v184, -1, s[24:25]
	v_cndmask_b32_e64 v231, v185, -1, s[28:29]
	v_cndmask_b32_e64 v232, v186, -1, s[30:31]
	v_cndmask_b32_e64 v233, v187, -1, s[98:99]
	v_cmp_gt_f32_e64 s[24:25], s35, v218
	v_cmp_gt_f32_e64 s[28:29], s35, v219
	v_cmp_gt_f32_e64 s[30:31], s35, v220
	v_cmp_gt_f32_e64 s[98:99], s35, v221
	v_add_f32_e32 v222, 1.0, v214
	v_add_f32_e32 v223, 1.0, v215
	v_add_f32_e32 v224, 1.0, v216
	v_add_f32_e32 v225, 1.0, v217
	v_cndmask_b32_e64 v226, 0, 32, s[24:25]
	v_cndmask_b32_e64 v227, 0, 32, s[28:29]
	v_cndmask_b32_e64 v228, 0, 32, s[30:31]
	v_cndmask_b32_e64 v229, 0, 32, s[98:99]
	v_cndmask_b32_e64 v238, 0, v213, s[24:25]
	v_cndmask_b32_e64 v239, 0, v213, s[28:29]
	v_cndmask_b32_e64 v240, 0, v213, s[30:31]
	v_cndmask_b32_e64 v241, 0, v213, s[98:99]
	v_ldexp_f32 v218, v218, v226
	v_ldexp_f32 v219, v219, v227
	v_ldexp_f32 v220, v220, v228
	v_ldexp_f32 v221, v221, v229
	v_log_f32_e32 v218, v218
	v_log_f32_e32 v219, v219
	v_log_f32_e32 v220, v220
	v_log_f32_e32 v221, v221
	v_log_f32_e32 v222, v222
	v_log_f32_e32 v223, v223
	v_log_f32_e32 v224, v224
	v_log_f32_e32 v225, v225
	v_mul_f32_e32 v226, 0x3f317217, v218
	v_mul_f32_e32 v227, 0x3f317217, v219
	v_mul_f32_e32 v228, 0x3f317217, v220
	v_mul_f32_e32 v229, 0x3f317217, v221
	v_fma_f32 v226, v218, s70, -v226
	v_fma_f32 v227, v219, s70, -v227
	v_fma_f32 v228, v220, s70, -v228
	v_fma_f32 v229, v221, s70, -v229
	v_fmac_f32_e32 v226, 0x3377d1cf, v218
	v_fmac_f32_e32 v227, 0x3377d1cf, v219
	v_fmac_f32_e32 v228, 0x3377d1cf, v220
	v_fmac_f32_e32 v229, 0x3377d1cf, v221
	v_fmac_f32_e32 v226, 0x3f317217, v218
	v_fmac_f32_e32 v227, 0x3f317217, v219
	v_fmac_f32_e32 v228, 0x3f317217, v220
	v_fmac_f32_e32 v229, 0x3f317217, v221
	v_cmp_lt_f32_e64 s[24:25], |v218|, s71
	v_cmp_lt_f32_e64 s[28:29], |v219|, s71
	v_cmp_lt_f32_e64 s[30:31], |v220|, s71
	v_cmp_lt_f32_e64 s[98:99], |v221|, s71
	v_cndmask_b32_e64 v218, v218, v226, s[24:25]
	v_cndmask_b32_e64 v219, v219, v227, s[28:29]
	v_cndmask_b32_e64 v220, v220, v228, s[30:31]
	v_cndmask_b32_e64 v221, v221, v229, s[98:99]
	v_sub_f32_e32 v218, v218, v238
	v_sub_f32_e32 v219, v219, v239
	v_sub_f32_e32 v220, v220, v240
	v_sub_f32_e32 v221, v221, v241
	v_mul_f32_e32 v226, 0x3f317217, v222
	v_mul_f32_e32 v227, 0x3f317217, v223
	v_mul_f32_e32 v228, 0x3f317217, v224
	v_mul_f32_e32 v229, 0x3f317217, v225
	v_fma_f32 v226, v222, s70, -v226
	v_fma_f32 v227, v223, s70, -v227
	v_fma_f32 v228, v224, s70, -v228
	v_fma_f32 v229, v225, s70, -v229
	v_fmac_f32_e32 v226, 0x3377d1cf, v222
	v_fmac_f32_e32 v227, 0x3377d1cf, v223
	v_fmac_f32_e32 v228, 0x3377d1cf, v224
	v_fmac_f32_e32 v229, 0x3377d1cf, v225
	v_fmac_f32_e32 v226, 0x3f317217, v222
	v_fmac_f32_e32 v227, 0x3f317217, v223
	v_fmac_f32_e32 v228, 0x3f317217, v224
	v_fmac_f32_e32 v229, 0x3f317217, v225
	v_bfi_b32 v218, v230, v218, v84
	v_bfi_b32 v219, v231, v219, v85
	v_bfi_b32 v220, v232, v220, v86
	v_bfi_b32 v221, v233, v221, v87
	v_sub_f32_e32 v84, v218, v226
	v_sub_f32_e32 v85, v219, v227
	v_sub_f32_e32 v86, v220, v228
	v_sub_f32_e32 v87, v221, v229
	v_cvt_pk_f16_f32 v234, v80, v81
	v_cvt_pk_f16_f32 v235, v82, v83
	v_cvt_pk_f16_f32 v236, v84, v85
	v_cvt_pk_f16_f32 v237, v86, v87
	global_store_dwordx4 v169, v[234:237], s[26:27]
	v_mul_f32_e64 v226, |v16|, s83
	v_mul_f32_e64 v227, |v17|, s83
	v_mul_f32_e64 v228, |v18|, s83
	v_mul_f32_e64 v229, |v19|, s83
	v_exp_f32_e32 v214, v226
	v_exp_f32_e32 v215, v227
	v_exp_f32_e32 v216, v228
	v_exp_f32_e32 v217, v229
	v_cmp_le_f32_e64 s[24:25], 0, v16
	v_cmp_le_f32_e64 s[28:29], 0, v17
	v_cmp_le_f32_e64 s[30:31], 0, v18
	v_cmp_le_f32_e64 s[98:99], 0, v19
	v_fma_f32 v218, v214, v136, 1.0
	v_fma_f32 v219, v215, v137, 1.0
	v_fma_f32 v220, v216, v138, 1.0
	v_fma_f32 v221, v217, v139, 1.0
	v_add_f32_e32 v222, v214, v136
	v_add_f32_e32 v223, v215, v137
	v_add_f32_e32 v224, v216, v138
	v_add_f32_e32 v225, v217, v139
	v_cndmask_b32_e64 v218, v222, v218, s[24:25]
	v_cndmask_b32_e64 v219, v223, v219, s[28:29]
	v_cndmask_b32_e64 v220, v224, v220, s[30:31]
	v_cndmask_b32_e64 v221, v225, v221, s[98:99]
; __device__ __forceinline__ unsigned cvt_pk_bf16(float lo, float hi) { const f32x2c v = {lo, hi}; const bf16x2c b = __builtin_convertvector(v, bf16x2c); return __builtin_bit_cast(unsigned, b); }
; #define PG8_GAS __attribute__((address_space(1)))
; __device__ __forceinline__ float gate_logf(float fp, float lb) {
;     const float e = __expf(-fabsf(fp)), l1pe = __logf(1.f + e);
;     return (fp >= 0.f ? __logf(1.f + lb * e) : (lb > 0.f ? __logf(lb + e) : fp)) - l1pe;
;     __device__ __forceinline__ void operator()(const f32x4 (&acc)[2][2][4][2], const Unit& u, int wr, int wc, int fr, int fq) const {
;     ...
;                         if (seg == 4) {
;                             const f32x4 l0 = *(const PG8_GAS f32x4*)(lbl + wcol), l1 = *(const PG8_GAS f32x4*)(lbl + wcol + 4);
; #pragma unroll
;                             for (int j = 0; j < 4; ++j) { v0[j] = gate_logf(v0[j], l0[j]); v1[j] = gate_logf(v1[j], l1[j]); }
;                         }
;                         u32x4 w;
;                         if (seg == 4) { w.x = cvt_pk_f16(v0[0], v0[1]); w.y = cvt_pk_f16(v0[2], v0[3]); w.z = cvt_pk_f16(v1[0], v1[1]); w.w = cvt_pk_f16(v1[2], v1[3]); }
;                         else { w.x = cvt_pk_bf16(v0[0], v0[1]); w.y = cvt_pk_bf16(v0[2], v0[3]); w.z = cvt_pk_bf16(v1[0], v1[1]); w.w = cvt_pk_bf16(v1[2], v1[3]); }
;                         *(PG8_GAS u32x4*)(segp + (size_t)r * 512 + wcol) = w;
	v_cndmask_b32_e64 v230, v188, -1, s[24:25]
	v_cndmask_b32_e64 v231, v189, -1, s[28:29]
	v_cndmask_b32_e64 v232, v190, -1, s[30:31]
	v_cndmask_b32_e64 v233, v191, -1, s[98:99]
	v_cmp_gt_f32_e64 s[24:25], s35, v218
	v_cmp_gt_f32_e64 s[28:29], s35, v219
	v_cmp_gt_f32_e64 s[30:31], s35, v220
	v_cmp_gt_f32_e64 s[98:99], s35, v221
	v_add_f32_e32 v222, 1.0, v214
	v_add_f32_e32 v223, 1.0, v215
	v_add_f32_e32 v224, 1.0, v216
	v_add_f32_e32 v225, 1.0, v217
	v_cndmask_b32_e64 v226, 0, 32, s[24:25]
	v_cndmask_b32_e64 v227, 0, 32, s[28:29]
	v_cndmask_b32_e64 v228, 0, 32, s[30:31]
	v_cndmask_b32_e64 v229, 0, 32, s[98:99]
	v_cndmask_b32_e64 v238, 0, v213, s[24:25]
	v_cndmask_b32_e64 v239, 0, v213, s[28:29]
	v_cndmask_b32_e64 v240, 0, v213, s[30:31]
	v_cndmask_b32_e64 v241, 0, v213, s[98:99]
	v_ldexp_f32 v218, v218, v226
	v_ldexp_f32 v219, v219, v227
	v_ldexp_f32 v220, v220, v228
	v_ldexp_f32 v221, v221, v229
	v_log_f32_e32 v218, v218
	v_log_f32_e32 v219, v219
	v_log_f32_e32 v220, v220
	v_log_f32_e32 v221, v221
	v_log_f32_e32 v222, v222
	v_log_f32_e32 v223, v223
	v_log_f32_e32 v224, v224
	v_log_f32_e32 v225, v225
	v_mul_f32_e32 v226, 0x3f317217, v218
	v_mul_f32_e32 v227, 0x3f317217, v219
	v_mul_f32_e32 v228, 0x3f317217, v220
	v_mul_f32_e32 v229, 0x3f317217, v221
	v_fma_f32 v226, v218, s70, -v226
	v_fma_f32 v227, v219, s70, -v227
	v_fma_f32 v228, v220, s70, -v228
	v_fma_f32 v229, v221, s70, -v229
	v_fmac_f32_e32 v226, 0x3377d1cf, v218
	v_fmac_f32_e32 v227, 0x3377d1cf, v219
	v_fmac_f32_e32 v228, 0x3377d1cf, v220
	v_fmac_f32_e32 v229, 0x3377d1cf, v221
	v_fmac_f32_e32 v226, 0x3f317217, v218
	v_fmac_f32_e32 v227, 0x3f317217, v219
	v_fmac_f32_e32 v228, 0x3f317217, v220
	v_fmac_f32_e32 v229, 0x3f317217, v221
	v_cmp_lt_f32_e64 s[24:25], |v218|, s71
	v_cmp_lt_f32_e64 s[28:29], |v219|, s71
	v_cmp_lt_f32_e64 s[30:31], |v220|, s71
	v_cmp_lt_f32_e64 s[98:99], |v221|, s71
	v_cndmask_b32_e64 v218, v218, v226, s[24:25]
	v_cndmask_b32_e64 v219, v219, v227, s[28:29]
	v_cndmask_b32_e64 v220, v220, v228, s[30:31]
	v_cndmask_b32_e64 v221, v221, v229, s[98:99]
	v_sub_f32_e32 v218, v218, v238
	v_sub_f32_e32 v219, v219, v239
	v_sub_f32_e32 v220, v220, v240
	v_sub_f32_e32 v221, v221, v241
	v_mul_f32_e32 v226, 0x3f317217, v222
	v_mul_f32_e32 v227, 0x3f317217, v223
	v_mul_f32_e32 v228, 0x3f317217, v224
	v_mul_f32_e32 v229, 0x3f317217, v225
	v_fma_f32 v226, v222, s70, -v226
	v_fma_f32 v227, v223, s70, -v227
	v_fma_f32 v228, v224, s70, -v228
	v_fma_f32 v229, v225, s70, -v229
	v_fmac_f32_e32 v226, 0x3377d1cf, v222
	v_fmac_f32_e32 v227, 0x3377d1cf, v223
	v_fmac_f32_e32 v228, 0x3377d1cf, v224
	v_fmac_f32_e32 v229, 0x3377d1cf, v225
	v_fmac_f32_e32 v226, 0x3f317217, v222
	v_fmac_f32_e32 v227, 0x3f317217, v223
	v_fmac_f32_e32 v228, 0x3f317217, v224
	v_fmac_f32_e32 v229, 0x3f317217, v225
	v_bfi_b32 v218, v230, v218, v16
	v_bfi_b32 v219, v231, v219, v17
	v_bfi_b32 v220, v232, v220, v18
	v_bfi_b32 v221, v233, v221, v19
	v_sub_f32_e32 v16, v218, v226
	v_sub_f32_e32 v17, v219, v227
	v_sub_f32_e32 v18, v220, v228
	v_sub_f32_e32 v19, v221, v229
	v_mul_f32_e64 v226, |v20|, s83
	v_mul_f32_e64 v227, |v21|, s83
	v_mul_f32_e64 v228, |v22|, s83
	v_mul_f32_e64 v229, |v23|, s83
	v_exp_f32_e32 v214, v226
	v_exp_f32_e32 v215, v227
	v_exp_f32_e32 v216, v228
	v_exp_f32_e32 v217, v229
	v_cmp_le_f32_e64 s[24:25], 0, v20
	v_cmp_le_f32_e64 s[28:29], 0, v21
	v_cmp_le_f32_e64 s[30:31], 0, v22
	v_cmp_le_f32_e64 s[98:99], 0, v23
	v_fma_f32 v218, v214, v140, 1.0
	v_fma_f32 v219, v215, v141, 1.0
	v_fma_f32 v220, v216, v142, 1.0
	v_fma_f32 v221, v217, v143, 1.0
	v_add_f32_e32 v222, v214, v140
	v_add_f32_e32 v223, v215, v141
	v_add_f32_e32 v224, v216, v142
	v_add_f32_e32 v225, v217, v143
	v_cndmask_b32_e64 v218, v222, v218, s[24:25]
	v_cndmask_b32_e64 v219, v223, v219, s[28:29]
	v_cndmask_b32_e64 v220, v224, v220, s[30:31]
	v_cndmask_b32_e64 v221, v225, v221, s[98:99]
	v_cndmask_b32_e64 v230, v192, -1, s[24:25]
	v_cndmask_b32_e64 v231, v193, -1, s[28:29]
	v_cndmask_b32_e64 v232, v194, -1, s[30:31]
	v_cndmask_b32_e64 v233, v195, -1, s[98:99]
	v_cmp_gt_f32_e64 s[24:25], s35, v218
	v_cmp_gt_f32_e64 s[28:29], s35, v219
	v_cmp_gt_f32_e64 s[30:31], s35, v220
	v_cmp_gt_f32_e64 s[98:99], s35, v221
	v_add_f32_e32 v222, 1.0, v214
	v_add_f32_e32 v223, 1.0, v215
	v_add_f32_e32 v224, 1.0, v216
	v_add_f32_e32 v225, 1.0, v217
	v_cndmask_b32_e64 v226, 0, 32, s[24:25]
	v_cndmask_b32_e64 v227, 0, 32, s[28:29]
	v_cndmask_b32_e64 v228, 0, 32, s[30:31]
	v_cndmask_b32_e64 v229, 0, 32, s[98:99]
	v_cndmask_b32_e64 v238, 0, v213, s[24:25]
	v_cndmask_b32_e64 v239, 0, v213, s[28:29]
	v_cndmask_b32_e64 v240, 0, v213, s[30:31]
	v_cndmask_b32_e64 v241, 0, v213, s[98:99]
	v_ldexp_f32 v218, v218, v226
	v_ldexp_f32 v219, v219, v227
	v_ldexp_f32 v220, v220, v228
	v_ldexp_f32 v221, v221, v229
	v_log_f32_e32 v218, v218
	v_log_f32_e32 v219, v219
	v_log_f32_e32 v220, v220
	v_log_f32_e32 v221, v221
	v_log_f32_e32 v222, v222
	v_log_f32_e32 v223, v223
	v_log_f32_e32 v224, v224
	v_log_f32_e32 v225, v225
	v_mul_f32_e32 v226, 0x3f317217, v218
	v_mul_f32_e32 v227, 0x3f317217, v219
	v_mul_f32_e32 v228, 0x3f317217, v220
	v_mul_f32_e32 v229, 0x3f317217, v221
	v_fma_f32 v226, v218, s70, -v226
	v_fma_f32 v227, v219, s70, -v227
	v_fma_f32 v228, v220, s70, -v228
	v_fma_f32 v229, v221, s70, -v229
	v_fmac_f32_e32 v226, 0x3377d1cf, v218
	v_fmac_f32_e32 v227, 0x3377d1cf, v219
	v_fmac_f32_e32 v228, 0x3377d1cf, v220
	v_fmac_f32_e32 v229, 0x3377d1cf, v221
	v_fmac_f32_e32 v226, 0x3f317217, v218
	v_fmac_f32_e32 v227, 0x3f317217, v219
	v_fmac_f32_e32 v228, 0x3f317217, v220
	v_fmac_f32_e32 v229, 0x3f317217, v221
	v_cmp_lt_f32_e64 s[24:25], |v218|, s71
	v_cmp_lt_f32_e64 s[28:29], |v219|, s71
; __device__ __forceinline__ unsigned cvt_pk_bf16(float lo, float hi) { const f32x2c v = {lo, hi}; const bf16x2c b = __builtin_convertvector(v, bf16x2c); return __builtin_bit_cast(unsigned, b); }
; #define PG8_GAS __attribute__((address_space(1)))
; __device__ __forceinline__ float gate_logf(float fp, float lb) {
;     const float e = __expf(-fabsf(fp)), l1pe = __logf(1.f + e);
;     return (fp >= 0.f ? __logf(1.f + lb * e) : (lb > 0.f ? __logf(lb + e) : fp)) - l1pe;
;     __device__ __forceinline__ void operator()(const f32x4 (&acc)[2][2][4][2], const Unit& u, int wr, int wc, int fr, int fq) const {
;     ...
;                         if (seg == 4) {
;                             const f32x4 l0 = *(const PG8_GAS f32x4*)(lbl + wcol), l1 = *(const PG8_GAS f32x4*)(lbl + wcol + 4);
; #pragma unroll
;                             for (int j = 0; j < 4; ++j) { v0[j] = gate_logf(v0[j], l0[j]); v1[j] = gate_logf(v1[j], l1[j]); }
;                         }
;                         u32x4 w;
;                         if (seg == 4) { w.x = cvt_pk_f16(v0[0], v0[1]); w.y = cvt_pk_f16(v0[2], v0[3]); w.z = cvt_pk_f16(v1[0], v1[1]); w.w = cvt_pk_f16(v1[2], v1[3]); }
;                         else { w.x = cvt_pk_bf16(v0[0], v0[1]); w.y = cvt_pk_bf16(v0[2], v0[3]); w.z = cvt_pk_bf16(v1[0], v1[1]); w.w = cvt_pk_bf16(v1[2], v1[3]); }
;                         *(PG8_GAS u32x4*)(segp + (size_t)r * 512 + wcol) = w;
	v_cmp_lt_f32_e64 s[30:31], |v220|, s71
	v_cmp_lt_f32_e64 s[98:99], |v221|, s71
	v_cndmask_b32_e64 v218, v218, v226, s[24:25]
	v_cndmask_b32_e64 v219, v219, v227, s[28:29]
	v_cndmask_b32_e64 v220, v220, v228, s[30:31]
	v_cndmask_b32_e64 v221, v221, v229, s[98:99]
	v_sub_f32_e32 v218, v218, v238
	v_sub_f32_e32 v219, v219, v239
	v_sub_f32_e32 v220, v220, v240
	v_sub_f32_e32 v221, v221, v241
	v_mul_f32_e32 v226, 0x3f317217, v222
	v_mul_f32_e32 v227, 0x3f317217, v223
	v_mul_f32_e32 v228, 0x3f317217, v224
	v_mul_f32_e32 v229, 0x3f317217, v225
	v_fma_f32 v226, v222, s70, -v226
	v_fma_f32 v227, v223, s70, -v227
	v_fma_f32 v228, v224, s70, -v228
	v_fma_f32 v229, v225, s70, -v229
	v_fmac_f32_e32 v226, 0x3377d1cf, v222
	v_fmac_f32_e32 v227, 0x3377d1cf, v223
	v_fmac_f32_e32 v228, 0x3377d1cf, v224
	v_fmac_f32_e32 v229, 0x3377d1cf, v225
	v_fmac_f32_e32 v226, 0x3f317217, v222
	v_fmac_f32_e32 v227, 0x3f317217, v223
	v_fmac_f32_e32 v228, 0x3f317217, v224
	v_fmac_f32_e32 v229, 0x3f317217, v225
	v_bfi_b32 v218, v230, v218, v20
	v_bfi_b32 v219, v231, v219, v21
	v_bfi_b32 v220, v232, v220, v22
	v_bfi_b32 v221, v233, v221, v23
	v_sub_f32_e32 v20, v218, v226
	v_sub_f32_e32 v21, v219, v227
	v_sub_f32_e32 v22, v220, v228
	v_sub_f32_e32 v23, v221, v229
	v_cvt_pk_f16_f32 v234, v16, v17
	v_cvt_pk_f16_f32 v235, v18, v19
	v_cvt_pk_f16_f32 v236, v20, v21
	v_cvt_pk_f16_f32 v237, v22, v23
	global_store_dwordx4 v169, v[234:237], s[26:27] offset:256
	s_add_u32 s26, s26, 0x4000
	s_addc_u32 s27, s27, 0
	v_mul_f32_e64 v226, |v72|, s83
	v_mul_f32_e64 v227, |v73|, s83
	v_mul_f32_e64 v228, |v74|, s83
	v_mul_f32_e64 v229, |v75|, s83
	v_exp_f32_e32 v214, v226
	v_exp_f32_e32 v215, v227
	v_exp_f32_e32 v216, v228
	v_exp_f32_e32 v217, v229
	v_cmp_le_f32_e64 s[24:25], 0, v72
	v_cmp_le_f32_e64 s[28:29], 0, v73
	v_cmp_le_f32_e64 s[30:31], 0, v74
	v_cmp_le_f32_e64 s[98:99], 0, v75
	v_fma_f32 v218, v214, v128, 1.0
	v_fma_f32 v219, v215, v129, 1.0
	v_fma_f32 v220, v216, v130, 1.0
	v_fma_f32 v221, v217, v131, 1.0
	v_add_f32_e32 v222, v214, v128
	v_add_f32_e32 v223, v215, v129
	v_add_f32_e32 v224, v216, v130
	v_add_f32_e32 v225, v217, v131
	v_cndmask_b32_e64 v218, v222, v218, s[24:25]
	v_cndmask_b32_e64 v219, v223, v219, s[28:29]
	v_cndmask_b32_e64 v220, v224, v220, s[30:31]
	v_cndmask_b32_e64 v221, v225, v221, s[98:99]
	v_cndmask_b32_e64 v230, v180, -1, s[24:25]
	v_cndmask_b32_e64 v231, v181, -1, s[28:29]
	v_cndmask_b32_e64 v232, v182, -1, s[30:31]
	v_cndmask_b32_e64 v233, v183, -1, s[98:99]
	v_cmp_gt_f32_e64 s[24:25], s35, v218
	v_cmp_gt_f32_e64 s[28:29], s35, v219
	v_cmp_gt_f32_e64 s[30:31], s35, v220
	v_cmp_gt_f32_e64 s[98:99], s35, v221
	v_add_f32_e32 v222, 1.0, v214
	v_add_f32_e32 v223, 1.0, v215
	v_add_f32_e32 v224, 1.0, v216
	v_add_f32_e32 v225, 1.0, v217
	v_cndmask_b32_e64 v226, 0, 32, s[24:25]
	v_cndmask_b32_e64 v227, 0, 32, s[28:29]
	v_cndmask_b32_e64 v228, 0, 32, s[30:31]
	v_cndmask_b32_e64 v229, 0, 32, s[98:99]
	v_cndmask_b32_e64 v238, 0, v213, s[24:25]
	v_cndmask_b32_e64 v239, 0, v213, s[28:29]
	v_cndmask_b32_e64 v240, 0, v213, s[30:31]
	v_cndmask_b32_e64 v241, 0, v213, s[98:99]
	v_ldexp_f32 v218, v218, v226
	v_ldexp_f32 v219, v219, v227
	v_ldexp_f32 v220, v220, v228
	v_ldexp_f32 v221, v221, v229
	v_log_f32_e32 v218, v218
	v_log_f32_e32 v219, v219
	v_log_f32_e32 v220, v220
	v_log_f32_e32 v221, v221
	v_log_f32_e32 v222, v222
	v_log_f32_e32 v223, v223
	v_log_f32_e32 v224, v224
	v_log_f32_e32 v225, v225
	v_mul_f32_e32 v226, 0x3f317217, v218
	v_mul_f32_e32 v227, 0x3f317217, v219
	v_mul_f32_e32 v228, 0x3f317217, v220
	v_mul_f32_e32 v229, 0x3f317217, v221
	v_fma_f32 v226, v218, s70, -v226
	v_fma_f32 v227, v219, s70, -v227
	v_fma_f32 v228, v220, s70, -v228
	v_fma_f32 v229, v221, s70, -v229
	v_fmac_f32_e32 v226, 0x3377d1cf, v218
	v_fmac_f32_e32 v227, 0x3377d1cf, v219
	v_fmac_f32_e32 v228, 0x3377d1cf, v220
	v_fmac_f32_e32 v229, 0x3377d1cf, v221
	v_fmac_f32_e32 v226, 0x3f317217, v218
	v_fmac_f32_e32 v227, 0x3f317217, v219
	v_fmac_f32_e32 v228, 0x3f317217, v220
	v_fmac_f32_e32 v229, 0x3f317217, v221
	v_cmp_lt_f32_e64 s[24:25], |v218|, s71
	v_cmp_lt_f32_e64 s[28:29], |v219|, s71
	v_cmp_lt_f32_e64 s[30:31], |v220|, s71
	v_cmp_lt_f32_e64 s[98:99], |v221|, s71
	v_cndmask_b32_e64 v218, v218, v226, s[24:25]
	v_cndmask_b32_e64 v219, v219, v227, s[28:29]
	v_cndmask_b32_e64 v220, v220, v228, s[30:31]
	v_cndmask_b32_e64 v221, v221, v229, s[98:99]
	v_sub_f32_e32 v218, v218, v238
	v_sub_f32_e32 v219, v219, v239
	v_sub_f32_e32 v220, v220, v240
	v_sub_f32_e32 v221, v221, v241
	v_mul_f32_e32 v226, 0x3f317217, v222
	v_mul_f32_e32 v227, 0x3f317217, v223
	v_mul_f32_e32 v228, 0x3f317217, v224
	v_mul_f32_e32 v229, 0x3f317217, v225
	v_fma_f32 v226, v222, s70, -v226
	v_fma_f32 v227, v223, s70, -v227
	v_fma_f32 v228, v224, s70, -v228
	v_fma_f32 v229, v225, s70, -v229
	v_fmac_f32_e32 v226, 0x3377d1cf, v222
	v_fmac_f32_e32 v227, 0x3377d1cf, v223
	v_fmac_f32_e32 v228, 0x3377d1cf, v224
	v_fmac_f32_e32 v229, 0x3377d1cf, v225
	v_fmac_f32_e32 v226, 0x3f317217, v222
	v_fmac_f32_e32 v227, 0x3f317217, v223
	v_fmac_f32_e32 v228, 0x3f317217, v224
	v_fmac_f32_e32 v229, 0x3f317217, v225
	v_bfi_b32 v218, v230, v218, v72
	v_bfi_b32 v219, v231, v219, v73
	v_bfi_b32 v220, v232, v220, v74
	v_bfi_b32 v221, v233, v221, v75
	v_sub_f32_e32 v72, v218, v226
	v_sub_f32_e32 v73, v219, v227
	v_sub_f32_e32 v74, v220, v228
	v_sub_f32_e32 v75, v221, v229
	v_mul_f32_e64 v226, |v76|, s83
	v_mul_f32_e64 v227, |v77|, s83
	v_mul_f32_e64 v228, |v78|, s83
	v_mul_f32_e64 v229, |v79|, s83
	v_exp_f32_e32 v214, v226
	v_exp_f32_e32 v215, v227
	v_exp_f32_e32 v216, v228
	v_exp_f32_e32 v217, v229
	v_cmp_le_f32_e64 s[24:25], 0, v76
	v_cmp_le_f32_e64 s[28:29], 0, v77
; __device__ __forceinline__ unsigned cvt_pk_bf16(float lo, float hi) { const f32x2c v = {lo, hi}; const bf16x2c b = __builtin_convertvector(v, bf16x2c); return __builtin_bit_cast(unsigned, b); }
; #define PG8_GAS __attribute__((address_space(1)))
; __device__ __forceinline__ float gate_logf(float fp, float lb) {
;     const float e = __expf(-fabsf(fp)), l1pe = __logf(1.f + e);
;     return (fp >= 0.f ? __logf(1.f + lb * e) : (lb > 0.f ? __logf(lb + e) : fp)) - l1pe;
;     __device__ __forceinline__ void operator()(const f32x4 (&acc)[2][2][4][2], const Unit& u, int wr, int wc, int fr, int fq) const {
;     ...
;                         if (seg == 4) {
;                             const f32x4 l0 = *(const PG8_GAS f32x4*)(lbl + wcol), l1 = *(const PG8_GAS f32x4*)(lbl + wcol + 4);
; #pragma unroll
;                             for (int j = 0; j < 4; ++j) { v0[j] = gate_logf(v0[j], l0[j]); v1[j] = gate_logf(v1[j], l1[j]); }
;                         }
;                         u32x4 w;
;                         if (seg == 4) { w.x = cvt_pk_f16(v0[0], v0[1]); w.y = cvt_pk_f16(v0[2], v0[3]); w.z = cvt_pk_f16(v1[0], v1[1]); w.w = cvt_pk_f16(v1[2], v1[3]); }
;                         else { w.x = cvt_pk_bf16(v0[0], v0[1]); w.y = cvt_pk_bf16(v0[2], v0[3]); w.z = cvt_pk_bf16(v1[0], v1[1]); w.w = cvt_pk_bf16(v1[2], v1[3]); }
;                         *(PG8_GAS u32x4*)(segp + (size_t)r * 512 + wcol) = w;
	v_cmp_le_f32_e64 s[30:31], 0, v78
	v_cmp_le_f32_e64 s[98:99], 0, v79
	v_fma_f32 v218, v214, v132, 1.0
	v_fma_f32 v219, v215, v133, 1.0
	v_fma_f32 v220, v216, v134, 1.0
	v_fma_f32 v221, v217, v135, 1.0
	v_add_f32_e32 v222, v214, v132
	v_add_f32_e32 v223, v215, v133
	v_add_f32_e32 v224, v216, v134
	v_add_f32_e32 v225, v217, v135
	v_cndmask_b32_e64 v218, v222, v218, s[24:25]
	v_cndmask_b32_e64 v219, v223, v219, s[28:29]
	v_cndmask_b32_e64 v220, v224, v220, s[30:31]
	v_cndmask_b32_e64 v221, v225, v221, s[98:99]
	v_cndmask_b32_e64 v230, v184, -1, s[24:25]
	v_cndmask_b32_e64 v231, v185, -1, s[28:29]
	v_cndmask_b32_e64 v232, v186, -1, s[30:31]
	v_cndmask_b32_e64 v233, v187, -1, s[98:99]
	v_cmp_gt_f32_e64 s[24:25], s35, v218
	v_cmp_gt_f32_e64 s[28:29], s35, v219
	v_cmp_gt_f32_e64 s[30:31], s35, v220
	v_cmp_gt_f32_e64 s[98:99], s35, v221
	v_add_f32_e32 v222, 1.0, v214
	v_add_f32_e32 v223, 1.0, v215
	v_add_f32_e32 v224, 1.0, v216
	v_add_f32_e32 v225, 1.0, v217
	v_cndmask_b32_e64 v226, 0, 32, s[24:25]
	v_cndmask_b32_e64 v227, 0, 32, s[28:29]
	v_cndmask_b32_e64 v228, 0, 32, s[30:31]
	v_cndmask_b32_e64 v229, 0, 32, s[98:99]
	v_cndmask_b32_e64 v238, 0, v213, s[24:25]
	v_cndmask_b32_e64 v239, 0, v213, s[28:29]
	v_cndmask_b32_e64 v240, 0, v213, s[30:31]
	v_cndmask_b32_e64 v241, 0, v213, s[98:99]
	v_ldexp_f32 v218, v218, v226
	v_ldexp_f32 v219, v219, v227
	v_ldexp_f32 v220, v220, v228
	v_ldexp_f32 v221, v221, v229
	v_log_f32_e32 v218, v218
	v_log_f32_e32 v219, v219
	v_log_f32_e32 v220, v220
	v_log_f32_e32 v221, v221
	v_log_f32_e32 v222, v222
	v_log_f32_e32 v223, v223
	v_log_f32_e32 v224, v224
	v_log_f32_e32 v225, v225
	v_mul_f32_e32 v226, 0x3f317217, v218
	v_mul_f32_e32 v227, 0x3f317217, v219
	v_mul_f32_e32 v228, 0x3f317217, v220
	v_mul_f32_e32 v229, 0x3f317217, v221
	v_fma_f32 v226, v218, s70, -v226
	v_fma_f32 v227, v219, s70, -v227
	v_fma_f32 v228, v220, s70, -v228
	v_fma_f32 v229, v221, s70, -v229
	v_fmac_f32_e32 v226, 0x3377d1cf, v218
	v_fmac_f32_e32 v227, 0x3377d1cf, v219
	v_fmac_f32_e32 v228, 0x3377d1cf, v220
	v_fmac_f32_e32 v229, 0x3377d1cf, v221
	v_fmac_f32_e32 v226, 0x3f317217, v218
	v_fmac_f32_e32 v227, 0x3f317217, v219
	v_fmac_f32_e32 v228, 0x3f317217, v220
	v_fmac_f32_e32 v229, 0x3f317217, v221
	v_cmp_lt_f32_e64 s[24:25], |v218|, s71
	v_cmp_lt_f32_e64 s[28:29], |v219|, s71
	v_cmp_lt_f32_e64 s[30:31], |v220|, s71
	v_cmp_lt_f32_e64 s[98:99], |v221|, s71
	v_cndmask_b32_e64 v218, v218, v226, s[24:25]
	v_cndmask_b32_e64 v219, v219, v227, s[28:29]
	v_cndmask_b32_e64 v220, v220, v228, s[30:31]
	v_cndmask_b32_e64 v221, v221, v229, s[98:99]
	v_sub_f32_e32 v218, v218, v238
	v_sub_f32_e32 v219, v219, v239
	v_sub_f32_e32 v220, v220, v240
	v_sub_f32_e32 v221, v221, v241
	v_mul_f32_e32 v226, 0x3f317217, v222
	v_mul_f32_e32 v227, 0x3f317217, v223
	v_mul_f32_e32 v228, 0x3f317217, v224
	v_mul_f32_e32 v229, 0x3f317217, v225
	v_fma_f32 v226, v222, s70, -v226
	v_fma_f32 v227, v223, s70, -v227
	v_fma_f32 v228, v224, s70, -v228
	v_fma_f32 v229, v225, s70, -v229
	v_fmac_f32_e32 v226, 0x3377d1cf, v222
	v_fmac_f32_e32 v227, 0x3377d1cf, v223
	v_fmac_f32_e32 v228, 0x3377d1cf, v224
	v_fmac_f32_e32 v229, 0x3377d1cf, v225
	v_fmac_f32_e32 v226, 0x3f317217, v222
	v_fmac_f32_e32 v227, 0x3f317217, v223
	v_fmac_f32_e32 v228, 0x3f317217, v224
	v_fmac_f32_e32 v229, 0x3f317217, v225
	v_bfi_b32 v218, v230, v218, v76
	v_bfi_b32 v219, v231, v219, v77
	v_bfi_b32 v220, v232, v220, v78
	v_bfi_b32 v221, v233, v221, v79
	v_sub_f32_e32 v76, v218, v226
	v_sub_f32_e32 v77, v219, v227
	v_sub_f32_e32 v78, v220, v228
	v_sub_f32_e32 v79, v221, v229
	v_cvt_pk_f16_f32 v234, v72, v73
	v_cvt_pk_f16_f32 v235, v74, v75
	v_cvt_pk_f16_f32 v236, v76, v77
	v_cvt_pk_f16_f32 v237, v78, v79
	global_store_dwordx4 v169, v[234:237], s[26:27]
	v_mul_f32_e64 v226, |v8|, s83
	v_mul_f32_e64 v227, |v9|, s83
	v_mul_f32_e64 v228, |v10|, s83
	v_mul_f32_e64 v229, |v11|, s83
	v_exp_f32_e32 v214, v226
	v_exp_f32_e32 v215, v227
	v_exp_f32_e32 v216, v228
	v_exp_f32_e32 v217, v229
	v_cmp_le_f32_e64 s[24:25], 0, v8
	v_cmp_le_f32_e64 s[28:29], 0, v9
	v_cmp_le_f32_e64 s[30:31], 0, v10
	v_cmp_le_f32_e64 s[98:99], 0, v11
	v_fma_f32 v218, v214, v136, 1.0
	v_fma_f32 v219, v215, v137, 1.0
	v_fma_f32 v220, v216, v138, 1.0
	v_fma_f32 v221, v217, v139, 1.0
	v_add_f32_e32 v222, v214, v136
	v_add_f32_e32 v223, v215, v137
	v_add_f32_e32 v224, v216, v138
	v_add_f32_e32 v225, v217, v139
	v_cndmask_b32_e64 v218, v222, v218, s[24:25]
	v_cndmask_b32_e64 v219, v223, v219, s[28:29]
	v_cndmask_b32_e64 v220, v224, v220, s[30:31]
	v_cndmask_b32_e64 v221, v225, v221, s[98:99]
	v_cndmask_b32_e64 v230, v188, -1, s[24:25]
	v_cndmask_b32_e64 v231, v189, -1, s[28:29]
	v_cndmask_b32_e64 v232, v190, -1, s[30:31]
	v_cndmask_b32_e64 v233, v191, -1, s[98:99]
	v_cmp_gt_f32_e64 s[24:25], s35, v218
	v_cmp_gt_f32_e64 s[28:29], s35, v219
	v_cmp_gt_f32_e64 s[30:31], s35, v220
	v_cmp_gt_f32_e64 s[98:99], s35, v221
	v_add_f32_e32 v222, 1.0, v214
	v_add_f32_e32 v223, 1.0, v215
	v_add_f32_e32 v224, 1.0, v216
	v_add_f32_e32 v225, 1.0, v217
	v_cndmask_b32_e64 v226, 0, 32, s[24:25]
	v_cndmask_b32_e64 v227, 0, 32, s[28:29]
	v_cndmask_b32_e64 v228, 0, 32, s[30:31]
	v_cndmask_b32_e64 v229, 0, 32, s[98:99]
	v_cndmask_b32_e64 v238, 0, v213, s[24:25]
	v_cndmask_b32_e64 v239, 0, v213, s[28:29]
	v_cndmask_b32_e64 v240, 0, v213, s[30:31]
	v_cndmask_b32_e64 v241, 0, v213, s[98:99]
	v_ldexp_f32 v218, v218, v226
	v_ldexp_f32 v219, v219, v227
	v_ldexp_f32 v220, v220, v228
	v_ldexp_f32 v221, v221, v229
	v_log_f32_e32 v218, v218
	v_log_f32_e32 v219, v219
	v_log_f32_e32 v220, v220
	v_log_f32_e32 v221, v221
	v_log_f32_e32 v222, v222
	v_log_f32_e32 v223, v223
	v_log_f32_e32 v224, v224
; __device__ __forceinline__ unsigned cvt_pk_bf16(float lo, float hi) { const f32x2c v = {lo, hi}; const bf16x2c b = __builtin_convertvector(v, bf16x2c); return __builtin_bit_cast(unsigned, b); }
; #define PG8_GAS __attribute__((address_space(1)))
; __device__ __forceinline__ float gate_logf(float fp, float lb) {
;     const float e = __expf(-fabsf(fp)), l1pe = __logf(1.f + e);
;     return (fp >= 0.f ? __logf(1.f + lb * e) : (lb > 0.f ? __logf(lb + e) : fp)) - l1pe;
;     __device__ __forceinline__ void operator()(const f32x4 (&acc)[2][2][4][2], const Unit& u, int wr, int wc, int fr, int fq) const {
;     ...
;                         if (seg == 4) {
;                             const f32x4 l0 = *(const PG8_GAS f32x4*)(lbl + wcol), l1 = *(const PG8_GAS f32x4*)(lbl + wcol + 4);
; #pragma unroll
;                             for (int j = 0; j < 4; ++j) { v0[j] = gate_logf(v0[j], l0[j]); v1[j] = gate_logf(v1[j], l1[j]); }
;                         }
;                         u32x4 w;
;                         if (seg == 4) { w.x = cvt_pk_f16(v0[0], v0[1]); w.y = cvt_pk_f16(v0[2], v0[3]); w.z = cvt_pk_f16(v1[0], v1[1]); w.w = cvt_pk_f16(v1[2], v1[3]); }
;                         else { w.x = cvt_pk_bf16(v0[0], v0[1]); w.y = cvt_pk_bf16(v0[2], v0[3]); w.z = cvt_pk_bf16(v1[0], v1[1]); w.w = cvt_pk_bf16(v1[2], v1[3]); }
;                         *(PG8_GAS u32x4*)(segp + (size_t)r * 512 + wcol) = w;
	v_log_f32_e32 v225, v225
	v_mul_f32_e32 v226, 0x3f317217, v218
	v_mul_f32_e32 v227, 0x3f317217, v219
	v_mul_f32_e32 v228, 0x3f317217, v220
	v_mul_f32_e32 v229, 0x3f317217, v221
	v_fma_f32 v226, v218, s70, -v226
	v_fma_f32 v227, v219, s70, -v227
	v_fma_f32 v228, v220, s70, -v228
	v_fma_f32 v229, v221, s70, -v229
	v_fmac_f32_e32 v226, 0x3377d1cf, v218
	v_fmac_f32_e32 v227, 0x3377d1cf, v219
	v_fmac_f32_e32 v228, 0x3377d1cf, v220
	v_fmac_f32_e32 v229, 0x3377d1cf, v221
	v_fmac_f32_e32 v226, 0x3f317217, v218
	v_fmac_f32_e32 v227, 0x3f317217, v219
	v_fmac_f32_e32 v228, 0x3f317217, v220
	v_fmac_f32_e32 v229, 0x3f317217, v221
	v_cmp_lt_f32_e64 s[24:25], |v218|, s71
	v_cmp_lt_f32_e64 s[28:29], |v219|, s71
	v_cmp_lt_f32_e64 s[30:31], |v220|, s71
	v_cmp_lt_f32_e64 s[98:99], |v221|, s71
	v_cndmask_b32_e64 v218, v218, v226, s[24:25]
	v_cndmask_b32_e64 v219, v219, v227, s[28:29]
	v_cndmask_b32_e64 v220, v220, v228, s[30:31]
	v_cndmask_b32_e64 v221, v221, v229, s[98:99]
	v_sub_f32_e32 v218, v218, v238
	v_sub_f32_e32 v219, v219, v239
	v_sub_f32_e32 v220, v220, v240
	v_sub_f32_e32 v221, v221, v241
	v_mul_f32_e32 v226, 0x3f317217, v222
	v_mul_f32_e32 v227, 0x3f317217, v223
	v_mul_f32_e32 v228, 0x3f317217, v224
	v_mul_f32_e32 v229, 0x3f317217, v225
	v_fma_f32 v226, v222, s70, -v226
	v_fma_f32 v227, v223, s70, -v227
	v_fma_f32 v228, v224, s70, -v228
	v_fma_f32 v229, v225, s70, -v229
	v_fmac_f32_e32 v226, 0x3377d1cf, v222
	v_fmac_f32_e32 v227, 0x3377d1cf, v223
	v_fmac_f32_e32 v228, 0x3377d1cf, v224
	v_fmac_f32_e32 v229, 0x3377d1cf, v225
	v_fmac_f32_e32 v226, 0x3f317217, v222
	v_fmac_f32_e32 v227, 0x3f317217, v223
	v_fmac_f32_e32 v228, 0x3f317217, v224
	v_fmac_f32_e32 v229, 0x3f317217, v225
	v_bfi_b32 v218, v230, v218, v8
	v_bfi_b32 v219, v231, v219, v9
	v_bfi_b32 v220, v232, v220, v10
	v_bfi_b32 v221, v233, v221, v11
	v_sub_f32_e32 v8, v218, v226
	v_sub_f32_e32 v9, v219, v227
	v_sub_f32_e32 v10, v220, v228
	v_sub_f32_e32 v11, v221, v229
	v_mul_f32_e64 v226, |v12|, s83
	v_mul_f32_e64 v227, |v13|, s83
	v_mul_f32_e64 v228, |v14|, s83
	v_mul_f32_e64 v229, |v15|, s83
	v_exp_f32_e32 v214, v226
	v_exp_f32_e32 v215, v227
	v_exp_f32_e32 v216, v228
	v_exp_f32_e32 v217, v229
	v_cmp_le_f32_e64 s[24:25], 0, v12
	v_cmp_le_f32_e64 s[28:29], 0, v13
	v_cmp_le_f32_e64 s[30:31], 0, v14
	v_cmp_le_f32_e64 s[98:99], 0, v15
	v_fma_f32 v218, v214, v140, 1.0
	v_fma_f32 v219, v215, v141, 1.0
	v_fma_f32 v220, v216, v142, 1.0
	v_fma_f32 v221, v217, v143, 1.0
	v_add_f32_e32 v222, v214, v140
	v_add_f32_e32 v223, v215, v141
	v_add_f32_e32 v224, v216, v142
	v_add_f32_e32 v225, v217, v143
	v_cndmask_b32_e64 v218, v222, v218, s[24:25]
	v_cndmask_b32_e64 v219, v223, v219, s[28:29]
	v_cndmask_b32_e64 v220, v224, v220, s[30:31]
	v_cndmask_b32_e64 v221, v225, v221, s[98:99]
	v_cndmask_b32_e64 v230, v192, -1, s[24:25]
	v_cndmask_b32_e64 v231, v193, -1, s[28:29]
	v_cndmask_b32_e64 v232, v194, -1, s[30:31]
	v_cndmask_b32_e64 v233, v195, -1, s[98:99]
	v_cmp_gt_f32_e64 s[24:25], s35, v218
	v_cmp_gt_f32_e64 s[28:29], s35, v219
	v_cmp_gt_f32_e64 s[30:31], s35, v220
	v_cmp_gt_f32_e64 s[98:99], s35, v221
	v_add_f32_e32 v222, 1.0, v214
	v_add_f32_e32 v223, 1.0, v215
	v_add_f32_e32 v224, 1.0, v216
	v_add_f32_e32 v225, 1.0, v217
	v_cndmask_b32_e64 v226, 0, 32, s[24:25]
	v_cndmask_b32_e64 v227, 0, 32, s[28:29]
	v_cndmask_b32_e64 v228, 0, 32, s[30:31]
	v_cndmask_b32_e64 v229, 0, 32, s[98:99]
	v_cndmask_b32_e64 v238, 0, v213, s[24:25]
	v_cndmask_b32_e64 v239, 0, v213, s[28:29]
	v_cndmask_b32_e64 v240, 0, v213, s[30:31]
	v_cndmask_b32_e64 v241, 0, v213, s[98:99]
	v_ldexp_f32 v218, v218, v226
	v_ldexp_f32 v219, v219, v227
	v_ldexp_f32 v220, v220, v228
	v_ldexp_f32 v221, v221, v229
	v_log_f32_e32 v218, v218
	v_log_f32_e32 v219, v219
	v_log_f32_e32 v220, v220
	v_log_f32_e32 v221, v221
	v_log_f32_e32 v222, v222
	v_log_f32_e32 v223, v223
	v_log_f32_e32 v224, v224
	v_log_f32_e32 v225, v225
	v_mul_f32_e32 v226, 0x3f317217, v218
	v_mul_f32_e32 v227, 0x3f317217, v219
	v_mul_f32_e32 v228, 0x3f317217, v220
	v_mul_f32_e32 v229, 0x3f317217, v221
	v_fma_f32 v226, v218, s70, -v226
	v_fma_f32 v227, v219, s70, -v227
	v_fma_f32 v228, v220, s70, -v228
	v_fma_f32 v229, v221, s70, -v229
	v_fmac_f32_e32 v226, 0x3377d1cf, v218
	v_fmac_f32_e32 v227, 0x3377d1cf, v219
	v_fmac_f32_e32 v228, 0x3377d1cf, v220
	v_fmac_f32_e32 v229, 0x3377d1cf, v221
	v_fmac_f32_e32 v226, 0x3f317217, v218
	v_fmac_f32_e32 v227, 0x3f317217, v219
	v_fmac_f32_e32 v228, 0x3f317217, v220
	v_fmac_f32_e32 v229, 0x3f317217, v221
	v_cmp_lt_f32_e64 s[24:25], |v218|, s71
	v_cmp_lt_f32_e64 s[28:29], |v219|, s71
	v_cmp_lt_f32_e64 s[30:31], |v220|, s71
	v_cmp_lt_f32_e64 s[98:99], |v221|, s71
	v_cndmask_b32_e64 v218, v218, v226, s[24:25]
	v_cndmask_b32_e64 v219, v219, v227, s[28:29]
	v_cndmask_b32_e64 v220, v220, v228, s[30:31]
	v_cndmask_b32_e64 v221, v221, v229, s[98:99]
	v_sub_f32_e32 v218, v218, v238
	v_sub_f32_e32 v219, v219, v239
	v_sub_f32_e32 v220, v220, v240
	v_sub_f32_e32 v221, v221, v241
	v_mul_f32_e32 v226, 0x3f317217, v222
	v_mul_f32_e32 v227, 0x3f317217, v223
	v_mul_f32_e32 v228, 0x3f317217, v224
	v_mul_f32_e32 v229, 0x3f317217, v225
	v_fma_f32 v226, v222, s70, -v226
	v_fma_f32 v227, v223, s70, -v227
	v_fma_f32 v228, v224, s70, -v228
	v_fma_f32 v229, v225, s70, -v229
	v_fmac_f32_e32 v226, 0x3377d1cf, v222
	v_fmac_f32_e32 v227, 0x3377d1cf, v223
	v_fmac_f32_e32 v228, 0x3377d1cf, v224
	v_fmac_f32_e32 v229, 0x3377d1cf, v225
	v_fmac_f32_e32 v226, 0x3f317217, v222
	v_fmac_f32_e32 v227, 0x3f317217, v223
	v_fmac_f32_e32 v228, 0x3f317217, v224
	v_fmac_f32_e32 v229, 0x3f317217, v225
	v_bfi_b32 v218, v230, v218, v12
	v_bfi_b32 v219, v231, v219, v13
	v_bfi_b32 v220, v232, v220, v14
; __device__ __forceinline__ unsigned cvt_pk_bf16(float lo, float hi) { const f32x2c v = {lo, hi}; const bf16x2c b = __builtin_convertvector(v, bf16x2c); return __builtin_bit_cast(unsigned, b); }
; #define PG8_GAS __attribute__((address_space(1)))
; __device__ __forceinline__ float gate_logf(float fp, float lb) {
;     const float e = __expf(-fabsf(fp)), l1pe = __logf(1.f + e);
;     return (fp >= 0.f ? __logf(1.f + lb * e) : (lb > 0.f ? __logf(lb + e) : fp)) - l1pe;
;     __device__ __forceinline__ void operator()(const f32x4 (&acc)[2][2][4][2], const Unit& u, int wr, int wc, int fr, int fq) const {
;     ...
;                         if (seg == 4) {
;                             const f32x4 l0 = *(const PG8_GAS f32x4*)(lbl + wcol), l1 = *(const PG8_GAS f32x4*)(lbl + wcol + 4);
; #pragma unroll
;                             for (int j = 0; j < 4; ++j) { v0[j] = gate_logf(v0[j], l0[j]); v1[j] = gate_logf(v1[j], l1[j]); }
;                         }
;                         u32x4 w;
;                         if (seg == 4) { w.x = cvt_pk_f16(v0[0], v0[1]); w.y = cvt_pk_f16(v0[2], v0[3]); w.z = cvt_pk_f16(v1[0], v1[1]); w.w = cvt_pk_f16(v1[2], v1[3]); }
;                         else { w.x = cvt_pk_bf16(v0[0], v0[1]); w.y = cvt_pk_bf16(v0[2], v0[3]); w.z = cvt_pk_bf16(v1[0], v1[1]); w.w = cvt_pk_bf16(v1[2], v1[3]); }
;                         *(PG8_GAS u32x4*)(segp + (size_t)r * 512 + wcol) = w;
	v_bfi_b32 v221, v233, v221, v15
	v_sub_f32_e32 v12, v218, v226
	v_sub_f32_e32 v13, v219, v227
	v_sub_f32_e32 v14, v220, v228
	v_sub_f32_e32 v15, v221, v229
	v_cvt_pk_f16_f32 v234, v8, v9
	v_cvt_pk_f16_f32 v235, v10, v11
	v_cvt_pk_f16_f32 v236, v12, v13
	v_cvt_pk_f16_f32 v237, v14, v15
	global_store_dwordx4 v169, v[234:237], s[26:27] offset:256
	s_add_u32 s26, s26, 0x4000
	s_addc_u32 s27, s27, 0
	v_mul_f32_e64 v226, |v64|, s83
	v_mul_f32_e64 v227, |v65|, s83
	v_mul_f32_e64 v228, |v66|, s83
	v_mul_f32_e64 v229, |v67|, s83
	v_exp_f32_e32 v214, v226
	v_exp_f32_e32 v215, v227
	v_exp_f32_e32 v216, v228
	v_exp_f32_e32 v217, v229
	v_cmp_le_f32_e64 s[24:25], 0, v64
	v_cmp_le_f32_e64 s[28:29], 0, v65
	v_cmp_le_f32_e64 s[30:31], 0, v66
	v_cmp_le_f32_e64 s[98:99], 0, v67
	v_fma_f32 v218, v214, v128, 1.0
	v_fma_f32 v219, v215, v129, 1.0
	v_fma_f32 v220, v216, v130, 1.0
	v_fma_f32 v221, v217, v131, 1.0
	v_add_f32_e32 v222, v214, v128
	v_add_f32_e32 v223, v215, v129
	v_add_f32_e32 v224, v216, v130
	v_add_f32_e32 v225, v217, v131
	v_cndmask_b32_e64 v218, v222, v218, s[24:25]
	v_cndmask_b32_e64 v219, v223, v219, s[28:29]
	v_cndmask_b32_e64 v220, v224, v220, s[30:31]
	v_cndmask_b32_e64 v221, v225, v221, s[98:99]
	v_cndmask_b32_e64 v230, v180, -1, s[24:25]
	v_cndmask_b32_e64 v231, v181, -1, s[28:29]
	v_cndmask_b32_e64 v232, v182, -1, s[30:31]
	v_cndmask_b32_e64 v233, v183, -1, s[98:99]
	v_cmp_gt_f32_e64 s[24:25], s35, v218
	v_cmp_gt_f32_e64 s[28:29], s35, v219
	v_cmp_gt_f32_e64 s[30:31], s35, v220
	v_cmp_gt_f32_e64 s[98:99], s35, v221
	v_add_f32_e32 v222, 1.0, v214
	v_add_f32_e32 v223, 1.0, v215
	v_add_f32_e32 v224, 1.0, v216
	v_add_f32_e32 v225, 1.0, v217
	v_cndmask_b32_e64 v226, 0, 32, s[24:25]
	v_cndmask_b32_e64 v227, 0, 32, s[28:29]
	v_cndmask_b32_e64 v228, 0, 32, s[30:31]
	v_cndmask_b32_e64 v229, 0, 32, s[98:99]
	v_cndmask_b32_e64 v238, 0, v213, s[24:25]
	v_cndmask_b32_e64 v239, 0, v213, s[28:29]
	v_cndmask_b32_e64 v240, 0, v213, s[30:31]
	v_cndmask_b32_e64 v241, 0, v213, s[98:99]
	v_ldexp_f32 v218, v218, v226
	v_ldexp_f32 v219, v219, v227
	v_ldexp_f32 v220, v220, v228
	v_ldexp_f32 v221, v221, v229
	v_log_f32_e32 v218, v218
	v_log_f32_e32 v219, v219
	v_log_f32_e32 v220, v220
	v_log_f32_e32 v221, v221
	v_log_f32_e32 v222, v222
	v_log_f32_e32 v223, v223
	v_log_f32_e32 v224, v224
	v_log_f32_e32 v225, v225
	v_mul_f32_e32 v226, 0x3f317217, v218
	v_mul_f32_e32 v227, 0x3f317217, v219
	v_mul_f32_e32 v228, 0x3f317217, v220
	v_mul_f32_e32 v229, 0x3f317217, v221
	v_fma_f32 v226, v218, s70, -v226
	v_fma_f32 v227, v219, s70, -v227
	v_fma_f32 v228, v220, s70, -v228
	v_fma_f32 v229, v221, s70, -v229
	v_fmac_f32_e32 v226, 0x3377d1cf, v218
	v_fmac_f32_e32 v227, 0x3377d1cf, v219
	v_fmac_f32_e32 v228, 0x3377d1cf, v220
	v_fmac_f32_e32 v229, 0x3377d1cf, v221
	v_fmac_f32_e32 v226, 0x3f317217, v218
	v_fmac_f32_e32 v227, 0x3f317217, v219
	v_fmac_f32_e32 v228, 0x3f317217, v220
	v_fmac_f32_e32 v229, 0x3f317217, v221
	v_cmp_lt_f32_e64 s[24:25], |v218|, s71
	v_cmp_lt_f32_e64 s[28:29], |v219|, s71
	v_cmp_lt_f32_e64 s[30:31], |v220|, s71
	v_cmp_lt_f32_e64 s[98:99], |v221|, s71
	v_cndmask_b32_e64 v218, v218, v226, s[24:25]
	v_cndmask_b32_e64 v219, v219, v227, s[28:29]
	v_cndmask_b32_e64 v220, v220, v228, s[30:31]
	v_cndmask_b32_e64 v221, v221, v229, s[98:99]
	v_sub_f32_e32 v218, v218, v238
	v_sub_f32_e32 v219, v219, v239
	v_sub_f32_e32 v220, v220, v240
	v_sub_f32_e32 v221, v221, v241
	v_mul_f32_e32 v226, 0x3f317217, v222
	v_mul_f32_e32 v227, 0x3f317217, v223
	v_mul_f32_e32 v228, 0x3f317217, v224
	v_mul_f32_e32 v229, 0x3f317217, v225
	v_fma_f32 v226, v222, s70, -v226
	v_fma_f32 v227, v223, s70, -v227
	v_fma_f32 v228, v224, s70, -v228
	v_fma_f32 v229, v225, s70, -v229
	v_fmac_f32_e32 v226, 0x3377d1cf, v222
	v_fmac_f32_e32 v227, 0x3377d1cf, v223
	v_fmac_f32_e32 v228, 0x3377d1cf, v224
	v_fmac_f32_e32 v229, 0x3377d1cf, v225
	v_fmac_f32_e32 v226, 0x3f317217, v222
	v_fmac_f32_e32 v227, 0x3f317217, v223
	v_fmac_f32_e32 v228, 0x3f317217, v224
	v_fmac_f32_e32 v229, 0x3f317217, v225
	v_bfi_b32 v218, v230, v218, v64
	v_bfi_b32 v219, v231, v219, v65
	v_bfi_b32 v220, v232, v220, v66
	v_bfi_b32 v221, v233, v221, v67
	v_sub_f32_e32 v64, v218, v226
	v_sub_f32_e32 v65, v219, v227
	v_sub_f32_e32 v66, v220, v228
	v_sub_f32_e32 v67, v221, v229
	v_mul_f32_e64 v226, |v68|, s83
	v_mul_f32_e64 v227, |v69|, s83
	v_mul_f32_e64 v228, |v70|, s83
	v_mul_f32_e64 v229, |v71|, s83
	v_exp_f32_e32 v214, v226
	v_exp_f32_e32 v215, v227
	v_exp_f32_e32 v216, v228
	v_exp_f32_e32 v217, v229
	v_cmp_le_f32_e64 s[24:25], 0, v68
	v_cmp_le_f32_e64 s[28:29], 0, v69
	v_cmp_le_f32_e64 s[30:31], 0, v70
	v_cmp_le_f32_e64 s[98:99], 0, v71
	v_fma_f32 v218, v214, v132, 1.0
	v_fma_f32 v219, v215, v133, 1.0
	v_fma_f32 v220, v216, v134, 1.0
	v_fma_f32 v221, v217, v135, 1.0
	v_add_f32_e32 v222, v214, v132
	v_add_f32_e32 v223, v215, v133
	v_add_f32_e32 v224, v216, v134
	v_add_f32_e32 v225, v217, v135
	v_cndmask_b32_e64 v218, v222, v218, s[24:25]
	v_cndmask_b32_e64 v219, v223, v219, s[28:29]
	v_cndmask_b32_e64 v220, v224, v220, s[30:31]
	v_cndmask_b32_e64 v221, v225, v221, s[98:99]
	v_cndmask_b32_e64 v230, v184, -1, s[24:25]
	v_cndmask_b32_e64 v231, v185, -1, s[28:29]
	v_cndmask_b32_e64 v232, v186, -1, s[30:31]
	v_cndmask_b32_e64 v233, v187, -1, s[98:99]
	v_cmp_gt_f32_e64 s[24:25], s35, v218
	v_cmp_gt_f32_e64 s[28:29], s35, v219
	v_cmp_gt_f32_e64 s[30:31], s35, v220
	v_cmp_gt_f32_e64 s[98:99], s35, v221
	v_add_f32_e32 v222, 1.0, v214
	v_add_f32_e32 v223, 1.0, v215
	v_add_f32_e32 v224, 1.0, v216
	v_add_f32_e32 v225, 1.0, v217
	v_cndmask_b32_e64 v226, 0, 32, s[24:25]
	v_cndmask_b32_e64 v227, 0, 32, s[28:29]
	v_cndmask_b32_e64 v228, 0, 32, s[30:31]
; __device__ __forceinline__ unsigned cvt_pk_bf16(float lo, float hi) { const f32x2c v = {lo, hi}; const bf16x2c b = __builtin_convertvector(v, bf16x2c); return __builtin_bit_cast(unsigned, b); }
; #define PG8_GAS __attribute__((address_space(1)))
; __device__ __forceinline__ float gate_logf(float fp, float lb) {
;     const float e = __expf(-fabsf(fp)), l1pe = __logf(1.f + e);
;     return (fp >= 0.f ? __logf(1.f + lb * e) : (lb > 0.f ? __logf(lb + e) : fp)) - l1pe;
;     __device__ __forceinline__ void operator()(const f32x4 (&acc)[2][2][4][2], const Unit& u, int wr, int wc, int fr, int fq) const {
;     ...
;                         if (seg == 4) {
;                             const f32x4 l0 = *(const PG8_GAS f32x4*)(lbl + wcol), l1 = *(const PG8_GAS f32x4*)(lbl + wcol + 4);
; #pragma unroll
;                             for (int j = 0; j < 4; ++j) { v0[j] = gate_logf(v0[j], l0[j]); v1[j] = gate_logf(v1[j], l1[j]); }
;                         }
;                         u32x4 w;
;                         if (seg == 4) { w.x = cvt_pk_f16(v0[0], v0[1]); w.y = cvt_pk_f16(v0[2], v0[3]); w.z = cvt_pk_f16(v1[0], v1[1]); w.w = cvt_pk_f16(v1[2], v1[3]); }
;                         else { w.x = cvt_pk_bf16(v0[0], v0[1]); w.y = cvt_pk_bf16(v0[2], v0[3]); w.z = cvt_pk_bf16(v1[0], v1[1]); w.w = cvt_pk_bf16(v1[2], v1[3]); }
;                         *(PG8_GAS u32x4*)(segp + (size_t)r * 512 + wcol) = w;
	v_cndmask_b32_e64 v229, 0, 32, s[98:99]
	v_cndmask_b32_e64 v238, 0, v213, s[24:25]
	v_cndmask_b32_e64 v239, 0, v213, s[28:29]
	v_cndmask_b32_e64 v240, 0, v213, s[30:31]
	v_cndmask_b32_e64 v241, 0, v213, s[98:99]
	v_ldexp_f32 v218, v218, v226
	v_ldexp_f32 v219, v219, v227
	v_ldexp_f32 v220, v220, v228
	v_ldexp_f32 v221, v221, v229
	v_log_f32_e32 v218, v218
	v_log_f32_e32 v219, v219
	v_log_f32_e32 v220, v220
	v_log_f32_e32 v221, v221
	v_log_f32_e32 v222, v222
	v_log_f32_e32 v223, v223
	v_log_f32_e32 v224, v224
	v_log_f32_e32 v225, v225
	v_mul_f32_e32 v226, 0x3f317217, v218
	v_mul_f32_e32 v227, 0x3f317217, v219
	v_mul_f32_e32 v228, 0x3f317217, v220
	v_mul_f32_e32 v229, 0x3f317217, v221
	v_fma_f32 v226, v218, s70, -v226
	v_fma_f32 v227, v219, s70, -v227
	v_fma_f32 v228, v220, s70, -v228
	v_fma_f32 v229, v221, s70, -v229
	v_fmac_f32_e32 v226, 0x3377d1cf, v218
	v_fmac_f32_e32 v227, 0x3377d1cf, v219
	v_fmac_f32_e32 v228, 0x3377d1cf, v220
	v_fmac_f32_e32 v229, 0x3377d1cf, v221
	v_fmac_f32_e32 v226, 0x3f317217, v218
	v_fmac_f32_e32 v227, 0x3f317217, v219
	v_fmac_f32_e32 v228, 0x3f317217, v220
	v_fmac_f32_e32 v229, 0x3f317217, v221
	v_cmp_lt_f32_e64 s[24:25], |v218|, s71
	v_cmp_lt_f32_e64 s[28:29], |v219|, s71
	v_cmp_lt_f32_e64 s[30:31], |v220|, s71
	v_cmp_lt_f32_e64 s[98:99], |v221|, s71
	v_cndmask_b32_e64 v218, v218, v226, s[24:25]
	v_cndmask_b32_e64 v219, v219, v227, s[28:29]
	v_cndmask_b32_e64 v220, v220, v228, s[30:31]
	v_cndmask_b32_e64 v221, v221, v229, s[98:99]
	v_sub_f32_e32 v218, v218, v238
	v_sub_f32_e32 v219, v219, v239
	v_sub_f32_e32 v220, v220, v240
	v_sub_f32_e32 v221, v221, v241
	v_mul_f32_e32 v226, 0x3f317217, v222
	v_mul_f32_e32 v227, 0x3f317217, v223
	v_mul_f32_e32 v228, 0x3f317217, v224
	v_mul_f32_e32 v229, 0x3f317217, v225
	v_fma_f32 v226, v222, s70, -v226
	v_fma_f32 v227, v223, s70, -v227
	v_fma_f32 v228, v224, s70, -v228
	v_fma_f32 v229, v225, s70, -v229
	v_fmac_f32_e32 v226, 0x3377d1cf, v222
	v_fmac_f32_e32 v227, 0x3377d1cf, v223
	v_fmac_f32_e32 v228, 0x3377d1cf, v224
	v_fmac_f32_e32 v229, 0x3377d1cf, v225
	v_fmac_f32_e32 v226, 0x3f317217, v222
	v_fmac_f32_e32 v227, 0x3f317217, v223
	v_fmac_f32_e32 v228, 0x3f317217, v224
	v_fmac_f32_e32 v229, 0x3f317217, v225
	v_bfi_b32 v218, v230, v218, v68
	v_bfi_b32 v219, v231, v219, v69
	v_bfi_b32 v220, v232, v220, v70
	v_bfi_b32 v221, v233, v221, v71
	v_sub_f32_e32 v68, v218, v226
	v_sub_f32_e32 v69, v219, v227
	v_sub_f32_e32 v70, v220, v228
	v_sub_f32_e32 v71, v221, v229
	v_cvt_pk_f16_f32 v234, v64, v65
	v_cvt_pk_f16_f32 v235, v66, v67
	v_cvt_pk_f16_f32 v236, v68, v69
	v_cvt_pk_f16_f32 v237, v70, v71
	global_store_dwordx4 v169, v[234:237], s[26:27]
	v_mul_f32_e64 v226, |v4|, s83
	v_mul_f32_e64 v227, |v5|, s83
	v_mul_f32_e64 v228, |v6|, s83
	v_mul_f32_e64 v229, |v7|, s83
	v_exp_f32_e32 v214, v226
	v_exp_f32_e32 v215, v227
	v_exp_f32_e32 v216, v228
	v_exp_f32_e32 v217, v229
	v_cmp_le_f32_e64 s[24:25], 0, v4
	v_cmp_le_f32_e64 s[28:29], 0, v5
	v_cmp_le_f32_e64 s[30:31], 0, v6
	v_cmp_le_f32_e64 s[98:99], 0, v7
	v_fma_f32 v218, v214, v136, 1.0
	v_fma_f32 v219, v215, v137, 1.0
	v_fma_f32 v220, v216, v138, 1.0
	v_fma_f32 v221, v217, v139, 1.0
	v_add_f32_e32 v222, v214, v136
	v_add_f32_e32 v223, v215, v137
	v_add_f32_e32 v224, v216, v138
	v_add_f32_e32 v225, v217, v139
	v_cndmask_b32_e64 v218, v222, v218, s[24:25]
	v_cndmask_b32_e64 v219, v223, v219, s[28:29]
	v_cndmask_b32_e64 v220, v224, v220, s[30:31]
	v_cndmask_b32_e64 v221, v225, v221, s[98:99]
	v_cndmask_b32_e64 v230, v188, -1, s[24:25]
	v_cndmask_b32_e64 v231, v189, -1, s[28:29]
	v_cndmask_b32_e64 v232, v190, -1, s[30:31]
	v_cndmask_b32_e64 v233, v191, -1, s[98:99]
	v_cmp_gt_f32_e64 s[24:25], s35, v218
	v_cmp_gt_f32_e64 s[28:29], s35, v219
	v_cmp_gt_f32_e64 s[30:31], s35, v220
	v_cmp_gt_f32_e64 s[98:99], s35, v221
	v_add_f32_e32 v222, 1.0, v214
	v_add_f32_e32 v223, 1.0, v215
	v_add_f32_e32 v224, 1.0, v216
	v_add_f32_e32 v225, 1.0, v217
	v_cndmask_b32_e64 v226, 0, 32, s[24:25]
	v_cndmask_b32_e64 v227, 0, 32, s[28:29]
	v_cndmask_b32_e64 v228, 0, 32, s[30:31]
	v_cndmask_b32_e64 v229, 0, 32, s[98:99]
	v_cndmask_b32_e64 v238, 0, v213, s[24:25]
	v_cndmask_b32_e64 v239, 0, v213, s[28:29]
	v_cndmask_b32_e64 v240, 0, v213, s[30:31]
	v_cndmask_b32_e64 v241, 0, v213, s[98:99]
	v_ldexp_f32 v218, v218, v226
	v_ldexp_f32 v219, v219, v227
	v_ldexp_f32 v220, v220, v228
	v_ldexp_f32 v221, v221, v229
	v_log_f32_e32 v218, v218
	v_log_f32_e32 v219, v219
	v_log_f32_e32 v220, v220
	v_log_f32_e32 v221, v221
	v_log_f32_e32 v222, v222
	v_log_f32_e32 v223, v223
	v_log_f32_e32 v224, v224
	v_log_f32_e32 v225, v225
	v_mul_f32_e32 v226, 0x3f317217, v218
	v_mul_f32_e32 v227, 0x3f317217, v219
	v_mul_f32_e32 v228, 0x3f317217, v220
	v_mul_f32_e32 v229, 0x3f317217, v221
	v_fma_f32 v226, v218, s70, -v226
	v_fma_f32 v227, v219, s70, -v227
	v_fma_f32 v228, v220, s70, -v228
	v_fma_f32 v229, v221, s70, -v229
	v_fmac_f32_e32 v226, 0x3377d1cf, v218
	v_fmac_f32_e32 v227, 0x3377d1cf, v219
	v_fmac_f32_e32 v228, 0x3377d1cf, v220
	v_fmac_f32_e32 v229, 0x3377d1cf, v221
	v_fmac_f32_e32 v226, 0x3f317217, v218
	v_fmac_f32_e32 v227, 0x3f317217, v219
	v_fmac_f32_e32 v228, 0x3f317217, v220
	v_fmac_f32_e32 v229, 0x3f317217, v221
	v_cmp_lt_f32_e64 s[24:25], |v218|, s71
	v_cmp_lt_f32_e64 s[28:29], |v219|, s71
; __device__ __forceinline__ unsigned cvt_pk_bf16(float lo, float hi) { const f32x2c v = {lo, hi}; const bf16x2c b = __builtin_convertvector(v, bf16x2c); return __builtin_bit_cast(unsigned, b); }
; #define PG8_GAS __attribute__((address_space(1)))
; __device__ __forceinline__ float gate_logf(float fp, float lb) {
;     const float e = __expf(-fabsf(fp)), l1pe = __logf(1.f + e);
;     return (fp >= 0.f ? __logf(1.f + lb * e) : (lb > 0.f ? __logf(lb + e) : fp)) - l1pe;
;     __device__ __forceinline__ void operator()(const f32x4 (&acc)[2][2][4][2], const Unit& u, int wr, int wc, int fr, int fq) const {
;     ...
;                         if (seg == 4) {
;                             const f32x4 l0 = *(const PG8_GAS f32x4*)(lbl + wcol), l1 = *(const PG8_GAS f32x4*)(lbl + wcol + 4);
; #pragma unroll
;                             for (int j = 0; j < 4; ++j) { v0[j] = gate_logf(v0[j], l0[j]); v1[j] = gate_logf(v1[j], l1[j]); }
;                         }
;                         u32x4 w;
;                         if (seg == 4) { w.x = cvt_pk_f16(v0[0], v0[1]); w.y = cvt_pk_f16(v0[2], v0[3]); w.z = cvt_pk_f16(v1[0], v1[1]); w.w = cvt_pk_f16(v1[2], v1[3]); }
;                         else { w.x = cvt_pk_bf16(v0[0], v0[1]); w.y = cvt_pk_bf16(v0[2], v0[3]); w.z = cvt_pk_bf16(v1[0], v1[1]); w.w = cvt_pk_bf16(v1[2], v1[3]); }
;                         *(PG8_GAS u32x4*)(segp + (size_t)r * 512 + wcol) = w;
	v_cmp_lt_f32_e64 s[30:31], |v220|, s71
	v_cmp_lt_f32_e64 s[98:99], |v221|, s71
	v_cndmask_b32_e64 v218, v218, v226, s[24:25]
	v_cndmask_b32_e64 v219, v219, v227, s[28:29]
	v_cndmask_b32_e64 v220, v220, v228, s[30:31]
	v_cndmask_b32_e64 v221, v221, v229, s[98:99]
	v_sub_f32_e32 v218, v218, v238
	v_sub_f32_e32 v219, v219, v239
	v_sub_f32_e32 v220, v220, v240
	v_sub_f32_e32 v221, v221, v241
	v_mul_f32_e32 v226, 0x3f317217, v222
	v_mul_f32_e32 v227, 0x3f317217, v223
	v_mul_f32_e32 v228, 0x3f317217, v224
	v_mul_f32_e32 v229, 0x3f317217, v225
	v_fma_f32 v226, v222, s70, -v226
	v_fma_f32 v227, v223, s70, -v227
	v_fma_f32 v228, v224, s70, -v228
	v_fma_f32 v229, v225, s70, -v229
	v_fmac_f32_e32 v226, 0x3377d1cf, v222
	v_fmac_f32_e32 v227, 0x3377d1cf, v223
	v_fmac_f32_e32 v228, 0x3377d1cf, v224
	v_fmac_f32_e32 v229, 0x3377d1cf, v225
	v_fmac_f32_e32 v226, 0x3f317217, v222
	v_fmac_f32_e32 v227, 0x3f317217, v223
	v_fmac_f32_e32 v228, 0x3f317217, v224
	v_fmac_f32_e32 v229, 0x3f317217, v225
	v_bfi_b32 v218, v230, v218, v4
	v_bfi_b32 v219, v231, v219, v5
	v_bfi_b32 v220, v232, v220, v6
	v_bfi_b32 v221, v233, v221, v7
	v_sub_f32_e32 v4, v218, v226
	v_sub_f32_e32 v5, v219, v227
	v_sub_f32_e32 v6, v220, v228
	v_sub_f32_e32 v7, v221, v229
	v_mul_f32_e64 v226, |v0|, s83
	v_mul_f32_e64 v227, |v1|, s83
	v_mul_f32_e64 v228, |v2|, s83
	v_mul_f32_e64 v229, |v3|, s83
	v_exp_f32_e32 v214, v226
	v_exp_f32_e32 v215, v227
	v_exp_f32_e32 v216, v228
	v_exp_f32_e32 v217, v229
	v_cmp_le_f32_e64 s[24:25], 0, v0
	v_cmp_le_f32_e64 s[28:29], 0, v1
	v_cmp_le_f32_e64 s[30:31], 0, v2
	v_cmp_le_f32_e64 s[98:99], 0, v3
	v_fma_f32 v218, v214, v140, 1.0
	v_fma_f32 v219, v215, v141, 1.0
	v_fma_f32 v220, v216, v142, 1.0
	v_fma_f32 v221, v217, v143, 1.0
	v_add_f32_e32 v222, v214, v140
	v_add_f32_e32 v223, v215, v141
	v_add_f32_e32 v224, v216, v142
	v_add_f32_e32 v225, v217, v143
	v_cndmask_b32_e64 v218, v222, v218, s[24:25]
	v_cndmask_b32_e64 v219, v223, v219, s[28:29]
	v_cndmask_b32_e64 v220, v224, v220, s[30:31]
	v_cndmask_b32_e64 v221, v225, v221, s[98:99]
	v_cndmask_b32_e64 v230, v192, -1, s[24:25]
	v_cndmask_b32_e64 v231, v193, -1, s[28:29]
	v_cndmask_b32_e64 v232, v194, -1, s[30:31]
	v_cndmask_b32_e64 v233, v195, -1, s[98:99]
	v_cmp_gt_f32_e64 s[24:25], s35, v218
	v_cmp_gt_f32_e64 s[28:29], s35, v219
	v_cmp_gt_f32_e64 s[30:31], s35, v220
	v_cmp_gt_f32_e64 s[98:99], s35, v221
	v_add_f32_e32 v222, 1.0, v214
	v_add_f32_e32 v223, 1.0, v215
	v_add_f32_e32 v224, 1.0, v216
	v_add_f32_e32 v225, 1.0, v217
	v_cndmask_b32_e64 v226, 0, 32, s[24:25]
	v_cndmask_b32_e64 v227, 0, 32, s[28:29]
	v_cndmask_b32_e64 v228, 0, 32, s[30:31]
	v_cndmask_b32_e64 v229, 0, 32, s[98:99]
	v_cndmask_b32_e64 v238, 0, v213, s[24:25]
	v_cndmask_b32_e64 v239, 0, v213, s[28:29]
	v_cndmask_b32_e64 v240, 0, v213, s[30:31]
	v_cndmask_b32_e64 v241, 0, v213, s[98:99]
	v_ldexp_f32 v218, v218, v226
	v_ldexp_f32 v219, v219, v227
	v_ldexp_f32 v220, v220, v228
	v_ldexp_f32 v221, v221, v229
	v_log_f32_e32 v218, v218
	v_log_f32_e32 v219, v219
	v_log_f32_e32 v220, v220
	v_log_f32_e32 v221, v221
	v_log_f32_e32 v222, v222
	v_log_f32_e32 v223, v223
	v_log_f32_e32 v224, v224
	v_log_f32_e32 v225, v225
	v_mul_f32_e32 v226, 0x3f317217, v218
	v_mul_f32_e32 v227, 0x3f317217, v219
	v_mul_f32_e32 v228, 0x3f317217, v220
	v_mul_f32_e32 v229, 0x3f317217, v221
	v_fma_f32 v226, v218, s70, -v226
	v_fma_f32 v227, v219, s70, -v227
	v_fma_f32 v228, v220, s70, -v228
	v_fma_f32 v229, v221, s70, -v229
	v_fmac_f32_e32 v226, 0x3377d1cf, v218
	v_fmac_f32_e32 v227, 0x3377d1cf, v219
	v_fmac_f32_e32 v228, 0x3377d1cf, v220
	v_fmac_f32_e32 v229, 0x3377d1cf, v221
	v_fmac_f32_e32 v226, 0x3f317217, v218
	v_fmac_f32_e32 v227, 0x3f317217, v219
	v_fmac_f32_e32 v228, 0x3f317217, v220
	v_fmac_f32_e32 v229, 0x3f317217, v221
	v_cmp_lt_f32_e64 s[24:25], |v218|, s71
	v_cmp_lt_f32_e64 s[28:29], |v219|, s71
	v_cmp_lt_f32_e64 s[30:31], |v220|, s71
	v_cmp_lt_f32_e64 s[98:99], |v221|, s71
	v_cndmask_b32_e64 v218, v218, v226, s[24:25]
	v_cndmask_b32_e64 v219, v219, v227, s[28:29]
	v_cndmask_b32_e64 v220, v220, v228, s[30:31]
	v_cndmask_b32_e64 v221, v221, v229, s[98:99]
	v_sub_f32_e32 v218, v218, v238
	v_sub_f32_e32 v219, v219, v239
	v_sub_f32_e32 v220, v220, v240
	v_sub_f32_e32 v221, v221, v241
	v_mul_f32_e32 v226, 0x3f317217, v222
	v_mul_f32_e32 v227, 0x3f317217, v223
	v_mul_f32_e32 v228, 0x3f317217, v224
	v_mul_f32_e32 v229, 0x3f317217, v225
	v_fma_f32 v226, v222, s70, -v226
	v_fma_f32 v227, v223, s70, -v227
	v_fma_f32 v228, v224, s70, -v228
	v_fma_f32 v229, v225, s70, -v229
	v_fmac_f32_e32 v226, 0x3377d1cf, v222
	v_fmac_f32_e32 v227, 0x3377d1cf, v223
	v_fmac_f32_e32 v228, 0x3377d1cf, v224
	v_fmac_f32_e32 v229, 0x3377d1cf, v225
	v_fmac_f32_e32 v226, 0x3f317217, v222
	v_fmac_f32_e32 v227, 0x3f317217, v223
	v_fmac_f32_e32 v228, 0x3f317217, v224
	v_fmac_f32_e32 v229, 0x3f317217, v225
	v_bfi_b32 v218, v230, v218, v0
	v_bfi_b32 v219, v231, v219, v1
	v_bfi_b32 v220, v232, v220, v2
	v_bfi_b32 v221, v233, v221, v3
	v_sub_f32_e32 v0, v218, v226
	v_sub_f32_e32 v1, v219, v227
	v_sub_f32_e32 v2, v220, v228
	v_sub_f32_e32 v3, v221, v229
	v_cvt_pk_f16_f32 v234, v4, v5
	v_cvt_pk_f16_f32 v235, v6, v7
	v_cvt_pk_f16_f32 v236, v0, v1
	v_cvt_pk_f16_f32 v237, v2, v3
	global_store_dwordx4 v169, v[234:237], s[26:27] offset:256
	s_branch .Lrope_done
